# mix phases (3,18) remapped to M-tile teams + team sync replaces mix->out-proj grid barriers (PM stores write-through)
# speedup vs baseline: 1.0445x; 1.0118x over previous
.LBB0_301:
	s_cmp_gt_i32 s22, 3
	s_cselect_b64 s[4:5], -1, 0
	s_cmp_lt_i32 s23, 4
	s_cselect_b64 s[6:7], -1, 0
	s_or_b64 s[4:5], s[4:5], s[6:7]
	v_bfe_u32 v1, v0, 6, 4
	s_and_b64 vcc, exec, s[4:5]
	v_lshl_or_b32 v150, s2, 2, v1
	s_cbranch_vccnz .LBB0_486
	s_load_dword s66, s[0:1], 0x468
	s_mov_b32 s75, s2
	s_movk_i32 s76, 0xc00
	s_waitcnt lgkmcnt(0)
	s_mov_b32 s77, s66
	s_cmpk_lg_u32 s66, 0x200
	s_cbranch_scc1 FUSE3_PAR
	s_and_b32 s67, s2, 63
	s_lshr_b32 s68, s2, 6
	s_mul_i32 s75, s67, 12
	s_add_i32 s75, s75, s68
	s_mul_i32 s76, s67, 48
	s_add_i32 s76, s76, 48
	s_mov_b32 s77, 8
FUSE3_PAR:
	v_lshl_or_b32 v149, s75, 2, v1
	s_mov_b32 s3, s76
	v_and_b32_e32 v147, 0x3ff, v0
	v_cmp_gt_i32_e32 vcc, s3, v149
	s_and_saveexec_b64 s[4:5], vcc
	s_cbranch_execz .LBB0_433
	s_load_dwordx2 s[8:9], s[0:1], 0x60
	s_load_dwordx2 s[10:11], s[0:1], 0x98
	s_load_dwordx2 s[12:13], s[0:1], 0x108
	s_load_dwordx2 s[6:7], s[0:1], 0x118
	v_lshlrev_b32_e32 v2, 3, v147
	v_and_b32_e32 v98, 0xf8, v2
	v_lshrrev_b32_e32 v2, 2, v147
	v_mov_b32_e32 v101, 0
	v_and_b32_e32 v151, 8, v2
	v_lshlrev_b32_e32 v2, 2, v98
	v_mov_b32_e32 v3, v101
	s_waitcnt lgkmcnt(0)
	v_lshl_add_u64 v[102:103], s[8:9], 0, v[2:3]
	s_add_u32 s8, s0, 0x468
	v_lshlrev_b32_e32 v2, 1, v98
	v_or_b32_e32 v100, 0x300, v98
	v_mov_b32_e32 v99, v101
	v_or_b32_e32 v104, 0x200, v98
	v_mov_b32_e32 v105, v101
	v_or_b32_e32 v106, 0x100, v98
	v_mov_b32_e32 v107, v101
	s_addc_u32 s9, s1, 0
	v_lshl_add_u64 v[108:109], s[12:13], 0, v[2:3]
	v_lshl_add_u64 v[110:111], s[10:11], 0, v[2:3]
	v_lshl_add_u64 v[112:113], s[6:7], 0, v[2:3]
	s_mov_b64 s[10:11], 0
	s_movk_i32 s3, 0x1000
	v_mov_b32_e32 v189, 0x7f8
	v_mov_b32_e32 v216, 0xf8
	v_mov_b32_e32 v217, 0x800
	v_mov_b32_e32 v218, 0x100
	v_mov_b32_e32 v219, 0xfffff800
	v_mov_b32_e32 v220, 0xffffff00
	s_add_i32 s18, s76, -1
	s_branch .LBB0_307
.LBB0_304:
	s_or_b64 exec, exec, s[16:17]
	v_lshlrev_b64 v[92:93], 11, v[54:55]
	v_lshl_add_u64 v[54:55], v[110:111], 0, v[92:93]
	global_load_dwordx4 v[6:9], v[102:103], off offset:1040
	global_load_dwordx4 v[10:13], v[102:103], off offset:1024
	s_waitcnt vmcnt(0)
	v_lshlrev_b32_e32 v74, 16, v53
	global_load_dwordx4 v[54:57], v[54:55], off offset:512
	v_and_b32_e32 v75, 0xffff0000, v53
	v_lshlrev_b32_e32 v66, 16, v49
	v_and_b32_e32 v67, 0xffff0000, v49
	v_min_u32_e32 v49, v117, v221
	v_sub_u32_e64 v53, v222, 2 clamp
	v_lshlrev_b32_e32 v82, 16, v36
	v_and_b32_e32 v83, 0xffff0000, v36
	v_sub_u32_e32 v36, v49, v53
	v_lshlrev_b32_e32 v86, 16, v38
	v_and_b32_e32 v87, 0xffff0000, v38
	v_cvt_f32_i32_e32 v36, v36
	v_lshlrev_b32_e32 v78, 16, v34
	v_and_b32_e32 v79, 0xffff0000, v34
	v_lshlrev_b32_e32 v88, 16, v39
	v_and_b32_e32 v89, 0xffff0000, v39
	v_lshlrev_b32_e32 v38, 16, v48
	v_and_b32_e32 v39, 0xffff0000, v48
	v_pk_add_f32 v[48:49], v[86:87], 0 op_sel_hi:[1,0]
	v_lshlrev_b32_e32 v76, 16, v50
	v_and_b32_e32 v77, 0xffff0000, v50
	v_pk_add_f32 v[48:49], v[48:49], v[78:79]
	v_lshlrev_b32_e32 v70, 16, v46
	v_and_b32_e32 v71, 0xffff0000, v46
	v_pk_add_f32 v[48:49], v[48:49], v[76:77]
	v_lshlrev_b32_e32 v80, 16, v35
	v_pk_add_f32 v[124:125], v[48:49], v[70:71]
	v_div_scale_f32 v48, s[16:17], v36, v36, 1.0
	v_rcp_f32_e32 v49, v48
	v_and_b32_e32 v81, 0xffff0000, v35
	v_lshlrev_b32_e32 v34, 16, v47
	v_and_b32_e32 v35, 0xffff0000, v47
	v_lshlrev_b32_e32 v46, 16, v52
	v_and_b32_e32 v47, 0xffff0000, v52
	v_pk_add_f32 v[52:53], v[88:89], 0 op_sel_hi:[1,0]
	v_lshlrev_b32_e32 v50, 16, v51
	v_and_b32_e32 v51, 0xffff0000, v51
	v_pk_add_f32 v[52:53], v[52:53], v[80:81]
	v_lshlrev_b32_e32 v90, 16, v40
	v_pk_add_f32 v[52:53], v[52:53], v[50:51]
	v_and_b32_e32 v91, 0xffff0000, v40
	v_pk_add_f32 v[126:127], v[52:53], v[34:35]
	v_fma_f32 v53, -v48, v49, 1.0
	v_div_scale_f32 v52, vcc, 1.0, v36, 1.0
	v_fmac_f32_e32 v49, v53, v49
	v_mul_f32_e32 v53, v52, v49
	v_fma_f32 v94, -v48, v53, v52
	v_fmac_f32_e32 v53, v94, v49
	v_fma_f32 v48, -v48, v53, v52
	v_div_fmas_f32 v48, v48, v49, v53
	v_div_fixup_f32 v36, v48, v36, 1.0
	v_pk_add_f32 v[120:121], v[90:91], 0 op_sel_hi:[1,0]
	v_pk_fma_f32 v[48:49], v[36:37], v[124:125], v[76:77] op_sel_hi:[0,1,1] neg_lo:[0,0,1] neg_hi:[0,0,1]
	v_pk_add_f32 v[120:121], v[120:121], v[82:83]
	v_pk_fma_f32 v[52:53], v[36:37], v[126:127], v[50:51] op_sel_hi:[0,1,1] neg_lo:[0,0,1] neg_hi:[0,0,1]
	v_lshlrev_b32_e32 v40, 16, v41
	v_pk_add_f32 v[120:121], v[120:121], v[46:47]
	v_and_b32_e32 v41, 0xffff0000, v41
	v_pk_add_f32 v[128:129], v[120:121], v[38:39]
	v_lshlrev_b64 v[84:85], 11, v[84:85]
	v_pk_fma_f32 v[120:121], v[36:37], v[128:129], v[46:47] op_sel_hi:[0,1,1] neg_lo:[0,0,1] neg_hi:[0,0,1]
	v_lshl_add_u64 v[92:93], v[112:113], 0, v[92:93]
	v_lshl_add_u64 v[122:123], v[110:111], 0, v[84:85]
	v_lshlrev_b64 v[64:65], 11, v[64:65]
	v_lshlrev_b64 v[62:63], 11, v[62:63]
	v_pk_mul_f32 v[120:121], v[120:121], v[6:7]
	v_pk_mul_f32 v[48:49], v[48:49], v[10:11]
	v_pk_mul_f32 v[52:53], v[52:53], v[12:13]
	s_waitcnt vmcnt(0)
	v_lshlrev_b32_e32 v130, 16, v54
	v_and_b32_e32 v131, 0xffff0000, v54
	v_lshlrev_b32_e32 v54, 16, v55
	v_and_b32_e32 v55, 0xffff0000, v55
	v_pk_mul_f32 v[48:49], v[48:49], v[130:131]
	v_pk_mul_f32 v[54:55], v[52:53], v[54:55]
	v_cvt_pk_bf16_f32 v52, v48, v49
	v_pk_add_f32 v[48:49], v[40:41], 0 op_sel_hi:[1,0]
	v_lshlrev_b32_e32 v130, 16, v37
	v_and_b32_e32 v131, 0xffff0000, v37
	v_pk_add_f32 v[48:49], v[48:49], v[130:131]
	v_lshlrev_b32_e32 v132, 16, v56
	v_and_b32_e32 v133, 0xffff0000, v56
	v_pk_add_f32 v[48:49], v[48:49], v[74:75]
	v_pk_mul_f32 v[120:121], v[120:121], v[132:133]
	v_pk_add_f32 v[132:133], v[48:49], v[66:67]
	v_lshlrev_b32_e32 v56, 16, v57
	v_pk_fma_f32 v[36:37], v[36:37], v[132:133], v[74:75] op_sel_hi:[0,1,1] neg_lo:[0,0,1] neg_hi:[0,0,1]
	v_and_b32_e32 v57, 0xffff0000, v57
	v_pk_mul_f32 v[36:37], v[36:37], v[8:9]
	v_cvt_pk_bf16_f32 v53, v54, v55
	v_pk_mul_f32 v[36:37], v[36:37], v[56:57]
	v_cvt_pk_bf16_f32 v54, v120, v121
	v_cvt_pk_bf16_f32 v55, v36, v37
	global_store_dwordx4 v[92:93], v[52:55], off offset:512 sc1
	global_load_dwordx4 v[120:123], v[122:123], off offset:512
	v_min_u32_e32 v36, v116, v221
	v_sub_u32_e64 v37, v118, 2 clamp
	v_sub_u32_e32 v92, v36, v37
	v_cvt_f32_i32_e32 v94, v92
	v_lshlrev_b32_e32 v48, 16, v45
	v_and_b32_e32 v49, 0xffff0000, v45
	v_lshlrev_b32_e32 v54, 16, v43
	v_and_b32_e32 v55, 0xffff0000, v43
	v_pk_add_f32 v[40:41], v[48:49], v[40:41] neg_lo:[0,1] neg_hi:[0,1]
	v_lshl_add_u64 v[36:37], v[112:113], 0, v[84:85]
	v_pk_add_f32 v[84:85], v[54:55], v[88:89] neg_lo:[0,1] neg_hi:[0,1]
	v_pk_add_f32 v[88:89], v[132:133], v[40:41]
	v_div_scale_f32 v40, s[16:17], v94, v94, 1.0
	v_rcp_f32_e32 v41, v40
	v_lshlrev_b32_e32 v52, 16, v42
	v_and_b32_e32 v53, 0xffff0000, v42
	v_lshlrev_b64 v[56:57], 11, v[72:73]
	v_lshlrev_b32_e32 v72, 16, v44
	v_and_b32_e32 v73, 0xffff0000, v44
	v_pk_add_f32 v[42:43], v[52:53], v[86:87] neg_lo:[0,1] neg_hi:[0,1]
	v_pk_add_f32 v[86:87], v[72:73], v[90:91] neg_lo:[0,1] neg_hi:[0,1]
	v_pk_add_f32 v[90:91], v[124:125], v[42:43]
	v_fma_f32 v43, -v40, v41, 1.0
	v_div_scale_f32 v42, vcc, 1.0, v94, 1.0
	v_fmac_f32_e32 v41, v43, v41
	v_mul_f32_e32 v43, v42, v41
	v_pk_add_f32 v[92:93], v[126:127], v[84:85]
	v_fma_f32 v84, -v40, v43, v42
	v_fmac_f32_e32 v43, v84, v41
	v_fma_f32 v40, -v40, v43, v42
	v_div_fmas_f32 v40, v40, v41, v43
	v_pk_add_f32 v[118:119], v[128:129], v[86:87]
	v_div_fixup_f32 v40, v40, v94, 1.0
	v_pk_fma_f32 v[42:43], v[40:41], v[90:91], v[70:71] op_sel_hi:[0,1,1] neg_lo:[0,0,1] neg_hi:[0,0,1]
	v_pk_fma_f32 v[84:85], v[40:41], v[92:93], v[34:35] op_sel_hi:[0,1,1] neg_lo:[0,0,1] neg_hi:[0,0,1]
	v_pk_fma_f32 v[86:87], v[40:41], v[118:119], v[38:39] op_sel_hi:[0,1,1] neg_lo:[0,0,1] neg_hi:[0,0,1]
	v_pk_fma_f32 v[40:41], v[40:41], v[88:89], v[66:67] op_sel_hi:[0,1,1] neg_lo:[0,0,1] neg_hi:[0,0,1]
	v_pk_mul_f32 v[42:43], v[42:43], v[10:11]
	v_pk_mul_f32 v[84:85], v[84:85], v[12:13]
	v_pk_mul_f32 v[86:87], v[86:87], v[6:7]
	v_pk_mul_f32 v[40:41], v[40:41], v[8:9]
	v_lshl_add_u64 v[44:45], v[110:111], 0, v[56:57]
	s_waitcnt vmcnt(0)
	v_lshlrev_b32_e32 v124, 16, v120
	v_and_b32_e32 v125, 0xffff0000, v120
	v_lshlrev_b32_e32 v120, 16, v121
	v_and_b32_e32 v121, 0xffff0000, v121
	v_lshlrev_b32_e32 v126, 16, v122
	v_and_b32_e32 v127, 0xffff0000, v122
	v_lshlrev_b32_e32 v122, 16, v123
	v_and_b32_e32 v123, 0xffff0000, v123
	v_pk_mul_f32 v[42:43], v[42:43], v[124:125]
	v_pk_mul_f32 v[84:85], v[84:85], v[120:121]
	v_pk_mul_f32 v[86:87], v[86:87], v[126:127]
	v_pk_mul_f32 v[120:121], v[40:41], v[122:123]
	v_cvt_pk_bf16_f32 v40, v42, v43
	v_cvt_pk_bf16_f32 v41, v84, v85
	v_cvt_pk_bf16_f32 v42, v86, v87
	v_cvt_pk_bf16_f32 v43, v120, v121
	global_store_dwordx4 v[36:37], v[40:43], off offset:512 sc1
	global_load_dwordx4 v[84:87], v[44:45], off offset:512
	v_lshlrev_b64 v[120:121], 11, v[68:69]
	v_min_u32_e32 v42, v115, v221
	v_lshlrev_b32_e32 v40, 16, v30
	v_and_b32_e32 v41, 0xffff0000, v30
	v_lshlrev_b32_e32 v44, 16, v31
	v_and_b32_e32 v45, 0xffff0000, v31
	v_lshlrev_b32_e32 v68, 16, v32
	v_and_b32_e32 v69, 0xffff0000, v32
	v_sub_u32_e32 v94, v42, v117
	v_lshlrev_b32_e32 v36, 16, v33
	v_and_b32_e32 v37, 0xffff0000, v33
	v_pk_add_f32 v[32:33], v[40:41], v[78:79] neg_lo:[0,1] neg_hi:[0,1]
	v_pk_add_f32 v[78:79], v[44:45], v[80:81] neg_lo:[0,1] neg_hi:[0,1]
	v_pk_add_f32 v[80:81], v[68:69], v[82:83] neg_lo:[0,1] neg_hi:[0,1]
	v_add_u32_e32 v82, 2, v94
	v_cvt_f32_i32_e32 v94, v82
	v_pk_add_f32 v[30:31], v[36:37], v[130:131] neg_lo:[0,1] neg_hi:[0,1]
	v_lshl_add_u64 v[42:43], v[112:113], 0, v[56:57]
	v_pk_add_f32 v[82:83], v[88:89], v[30:31]
	v_div_scale_f32 v30, s[16:17], v94, v94, 1.0
	v_rcp_f32_e32 v31, v30
	v_pk_add_f32 v[88:89], v[90:91], v[32:33]
	v_div_scale_f32 v32, vcc, 1.0, v94, 1.0
	v_fma_f32 v33, -v30, v31, 1.0
	v_fmac_f32_e32 v31, v33, v31
	v_mul_f32_e32 v33, v32, v31
	v_pk_add_f32 v[90:91], v[92:93], v[78:79]
	v_fma_f32 v78, -v30, v33, v32
	v_fmac_f32_e32 v33, v78, v31
	v_fma_f32 v30, -v30, v33, v32
	v_div_fmas_f32 v30, v30, v31, v33
	v_pk_add_f32 v[92:93], v[118:119], v[80:81]
	v_div_fixup_f32 v30, v30, v94, 1.0
	v_pk_fma_f32 v[32:33], v[30:31], v[88:89], v[52:53] op_sel_hi:[0,1,1] neg_lo:[0,0,1] neg_hi:[0,0,1]
	v_pk_fma_f32 v[78:79], v[30:31], v[90:91], v[54:55] op_sel_hi:[0,1,1] neg_lo:[0,0,1] neg_hi:[0,0,1]
	v_pk_fma_f32 v[80:81], v[30:31], v[92:93], v[72:73] op_sel_hi:[0,1,1] neg_lo:[0,0,1] neg_hi:[0,0,1]
	v_pk_fma_f32 v[30:31], v[30:31], v[82:83], v[48:49] op_sel_hi:[0,1,1] neg_lo:[0,0,1] neg_hi:[0,0,1]
	v_pk_mul_f32 v[32:33], v[32:33], v[10:11]
	v_pk_mul_f32 v[78:79], v[78:79], v[12:13]
	v_pk_mul_f32 v[80:81], v[80:81], v[6:7]
	v_pk_mul_f32 v[30:31], v[30:31], v[8:9]
	v_lshl_add_u64 v[56:57], v[110:111], 0, v[120:121]
	s_waitcnt vmcnt(0)
	v_lshlrev_b32_e32 v118, 16, v84
	v_and_b32_e32 v119, 0xffff0000, v84
	v_lshlrev_b32_e32 v84, 16, v85
	v_and_b32_e32 v85, 0xffff0000, v85
	v_lshlrev_b32_e32 v122, 16, v86
	v_and_b32_e32 v123, 0xffff0000, v86
	v_lshlrev_b32_e32 v86, 16, v87
	v_and_b32_e32 v87, 0xffff0000, v87
	v_pk_mul_f32 v[32:33], v[32:33], v[118:119]
	v_pk_mul_f32 v[78:79], v[78:79], v[84:85]
	v_pk_mul_f32 v[80:81], v[80:81], v[122:123]
	v_pk_mul_f32 v[84:85], v[30:31], v[86:87]
	v_cvt_pk_bf16_f32 v30, v32, v33
	v_cvt_pk_bf16_f32 v31, v78, v79
	v_cvt_pk_bf16_f32 v32, v80, v81
	v_cvt_pk_bf16_f32 v33, v84, v85
	global_store_dwordx4 v[42:43], v[30:33], off offset:512 sc1
	global_load_dwordx4 v[78:81], v[56:57], off offset:512
	v_lshlrev_b32_e32 v42, 16, v27
	v_lshlrev_b32_e32 v30, 16, v29
	v_and_b32_e32 v31, 0xffff0000, v29
	v_min_u32_e32 v29, v97, v221
	v_sub_u32_e32 v94, v29, v116
	v_lshlrev_b32_e32 v32, 16, v26
	v_and_b32_e32 v33, 0xffff0000, v26
	v_and_b32_e32 v43, 0xffff0000, v27
	v_pk_add_f32 v[26:27], v[30:31], v[74:75] neg_lo:[0,1] neg_hi:[0,1]
	v_add_u32_e32 v74, 2, v94
	v_cvt_f32_i32_e32 v94, v74
	v_pk_add_f32 v[74:75], v[82:83], v[26:27]
	v_lshlrev_b32_e32 v56, 16, v28
	v_and_b32_e32 v57, 0xffff0000, v28
	v_div_scale_f32 v116, s[16:17], v94, v94, 1.0
	v_rcp_f32_e32 v26, v116
	v_div_scale_f32 v117, vcc, 1.0, v94, 1.0
	v_pk_add_f32 v[28:29], v[32:33], v[76:77] neg_lo:[0,1] neg_hi:[0,1]
	v_fma_f32 v27, -v116, v26, 1.0
	v_fmac_f32_e32 v26, v27, v26
	v_mul_f32_e32 v27, v117, v26
	v_pk_add_f32 v[76:77], v[88:89], v[28:29]
	v_fma_f32 v28, -v116, v27, v117
	v_fmac_f32_e32 v27, v28, v26
	v_fma_f32 v28, -v116, v27, v117
	v_pk_add_f32 v[50:51], v[42:43], v[50:51] neg_lo:[0,1] neg_hi:[0,1]
	v_pk_add_f32 v[46:47], v[56:57], v[46:47] neg_lo:[0,1] neg_hi:[0,1]
	v_div_fmas_f32 v26, v28, v26, v27
	v_pk_add_f32 v[50:51], v[90:91], v[50:51]
	v_pk_add_f32 v[46:47], v[92:93], v[46:47]
	v_div_fixup_f32 v26, v26, v94, 1.0
	v_pk_fma_f32 v[28:29], v[26:27], v[76:77], v[40:41] op_sel_hi:[0,1,1] neg_lo:[0,0,1] neg_hi:[0,0,1]
	v_pk_fma_f32 v[82:83], v[26:27], v[50:51], v[44:45] op_sel_hi:[0,1,1] neg_lo:[0,0,1] neg_hi:[0,0,1]
	v_pk_fma_f32 v[88:89], v[26:27], v[46:47], v[68:69] op_sel_hi:[0,1,1] neg_lo:[0,0,1] neg_hi:[0,0,1]
	v_pk_fma_f32 v[26:27], v[26:27], v[74:75], v[36:37] op_sel_hi:[0,1,1] neg_lo:[0,0,1] neg_hi:[0,0,1]
	v_pk_mul_f32 v[28:29], v[28:29], v[10:11]
	v_pk_mul_f32 v[82:83], v[82:83], v[12:13]
	v_pk_mul_f32 v[88:89], v[88:89], v[6:7]
	v_pk_mul_f32 v[26:27], v[26:27], v[8:9]
	v_lshl_add_u64 v[84:85], v[112:113], 0, v[120:121]
	v_lshl_add_u64 v[86:87], v[110:111], 0, v[64:65]
	v_lshl_add_u64 v[64:65], v[112:113], 0, v[64:65]
	s_waitcnt vmcnt(0)
	v_lshlrev_b32_e32 v90, 16, v78
	v_and_b32_e32 v91, 0xffff0000, v78
	v_lshlrev_b32_e32 v78, 16, v79
	v_and_b32_e32 v79, 0xffff0000, v79
	v_lshlrev_b32_e32 v92, 16, v80
	v_and_b32_e32 v93, 0xffff0000, v80
	v_lshlrev_b32_e32 v80, 16, v81
	v_and_b32_e32 v81, 0xffff0000, v81
	v_pk_mul_f32 v[28:29], v[28:29], v[90:91]
	v_pk_mul_f32 v[78:79], v[82:83], v[78:79]
	v_pk_mul_f32 v[82:83], v[88:89], v[92:93]
	v_pk_mul_f32 v[80:81], v[26:27], v[80:81]
	v_cvt_pk_bf16_f32 v26, v28, v29
	v_cvt_pk_bf16_f32 v27, v78, v79
	v_cvt_pk_bf16_f32 v28, v82, v83
	v_cvt_pk_bf16_f32 v29, v80, v81
	global_store_dwordx4 v[84:85], v[26:29], off offset:512 sc1
	global_load_dwordx4 v[26:29], v[86:87], off offset:512
	v_lshlrev_b32_e32 v78, 16, v25
	v_and_b32_e32 v79, 0xffff0000, v25
	v_min_u32_e32 v25, v96, v221
	v_sub_u32_e32 v88, v25, v115
	v_lshlrev_b32_e32 v80, 16, v22
	v_and_b32_e32 v81, 0xffff0000, v22
	v_lshlrev_b32_e32 v82, 16, v23
	v_and_b32_e32 v83, 0xffff0000, v23
	v_pk_add_f32 v[22:23], v[78:79], v[66:67] neg_lo:[0,1] neg_hi:[0,1]
	v_add_u32_e32 v66, 2, v88
	v_cvt_f32_i32_e32 v88, v66
	v_pk_add_f32 v[66:67], v[74:75], v[22:23]
	v_lshlrev_b32_e32 v84, 16, v24
	v_and_b32_e32 v85, 0xffff0000, v24
	v_div_scale_f32 v89, s[16:17], v88, v88, 1.0
	v_rcp_f32_e32 v91, v89
	v_div_scale_f32 v90, vcc, 1.0, v88, 1.0
	v_pk_add_f32 v[24:25], v[80:81], v[70:71] neg_lo:[0,1] neg_hi:[0,1]
	v_fma_f32 v22, -v89, v91, 1.0
	v_fmac_f32_e32 v91, v22, v91
	v_mul_f32_e32 v22, v90, v91
	v_fma_f32 v23, -v89, v22, v90
	v_fmac_f32_e32 v22, v23, v91
	v_fma_f32 v23, -v89, v22, v90
	v_pk_add_f32 v[34:35], v[82:83], v[34:35] neg_lo:[0,1] neg_hi:[0,1]
	v_pk_add_f32 v[38:39], v[84:85], v[38:39] neg_lo:[0,1] neg_hi:[0,1]
	v_div_fmas_f32 v22, v23, v91, v22
	v_pk_add_f32 v[70:71], v[76:77], v[24:25]
	v_pk_add_f32 v[34:35], v[50:51], v[34:35]
	v_pk_add_f32 v[38:39], v[46:47], v[38:39]
	v_div_fixup_f32 v22, v22, v88, 1.0
	v_pk_fma_f32 v[24:25], v[22:23], v[70:71], v[32:33] op_sel_hi:[0,1,1] neg_lo:[0,0,1] neg_hi:[0,0,1]
	v_pk_fma_f32 v[46:47], v[22:23], v[34:35], v[42:43] op_sel_hi:[0,1,1] neg_lo:[0,0,1] neg_hi:[0,0,1]
	v_pk_fma_f32 v[50:51], v[22:23], v[38:39], v[56:57] op_sel_hi:[0,1,1] neg_lo:[0,0,1] neg_hi:[0,0,1]
	v_pk_fma_f32 v[22:23], v[22:23], v[66:67], v[30:31] op_sel_hi:[0,1,1] neg_lo:[0,0,1] neg_hi:[0,0,1]
	v_pk_mul_f32 v[24:25], v[24:25], v[10:11]
	v_pk_mul_f32 v[46:47], v[46:47], v[12:13]
	v_pk_mul_f32 v[50:51], v[50:51], v[6:7]
	v_pk_mul_f32 v[22:23], v[22:23], v[8:9]
	v_lshl_add_u64 v[86:87], v[110:111], 0, v[62:63]
	v_lshl_add_u64 v[62:63], v[112:113], 0, v[62:63]
	s_waitcnt vmcnt(0)
	v_lshlrev_b32_e32 v74, 16, v26
	v_and_b32_e32 v75, 0xffff0000, v26
	v_lshlrev_b32_e32 v26, 16, v27
	v_and_b32_e32 v27, 0xffff0000, v27
	v_lshlrev_b32_e32 v76, 16, v28
	v_and_b32_e32 v77, 0xffff0000, v28
	v_lshlrev_b32_e32 v28, 16, v29
	v_and_b32_e32 v29, 0xffff0000, v29
	v_pk_mul_f32 v[24:25], v[24:25], v[74:75]
	v_pk_mul_f32 v[26:27], v[46:47], v[26:27]
	v_pk_mul_f32 v[46:47], v[50:51], v[76:77]
	v_pk_mul_f32 v[28:29], v[22:23], v[28:29]
	v_cvt_pk_bf16_f32 v22, v24, v25
	v_cvt_pk_bf16_f32 v23, v26, v27
	v_cvt_pk_bf16_f32 v24, v46, v47
	v_cvt_pk_bf16_f32 v25, v28, v29
	global_store_dwordx4 v[64:65], v[22:25], off offset:512 sc1
	global_load_dwordx4 v[22:25], v[86:87], off offset:512
	v_min_u32_e32 v64, v95, v221
	v_lshlrev_b32_e32 v28, 16, v21
	v_and_b32_e32 v29, 0xffff0000, v21
	v_sub_u32_e32 v74, v64, v97
	v_lshlrev_b32_e32 v46, 16, v18
	v_and_b32_e32 v47, 0xffff0000, v18
	v_lshlrev_b32_e32 v50, 16, v19
	v_and_b32_e32 v51, 0xffff0000, v19
	v_pk_add_f32 v[18:19], v[28:29], v[48:49] neg_lo:[0,1] neg_hi:[0,1]
	v_add_u32_e32 v48, 2, v74
	v_cvt_f32_i32_e32 v74, v48
	v_lshlrev_b64 v[26:27], 11, v[60:61]
	v_lshlrev_b32_e32 v60, 16, v20
	v_and_b32_e32 v61, 0xffff0000, v20
	v_pk_add_f32 v[20:21], v[46:47], v[52:53] neg_lo:[0,1] neg_hi:[0,1]
	v_pk_add_f32 v[52:53], v[60:61], v[72:73] neg_lo:[0,1] neg_hi:[0,1]
	v_div_scale_f32 v72, s[16:17], v74, v74, 1.0
	v_rcp_f32_e32 v75, v72
	v_pk_add_f32 v[48:49], v[50:51], v[54:55] neg_lo:[0,1] neg_hi:[0,1]
	v_pk_add_f32 v[54:55], v[66:67], v[18:19]
	v_div_scale_f32 v73, vcc, 1.0, v74, 1.0
	v_fma_f32 v18, -v72, v75, 1.0
	v_fmac_f32_e32 v75, v18, v75
	v_mul_f32_e32 v18, v73, v75
	v_fma_f32 v19, -v72, v18, v73
	v_fmac_f32_e32 v18, v19, v75
	v_fma_f32 v19, -v72, v18, v73
	v_div_fmas_f32 v18, v19, v75, v18
	v_pk_add_f32 v[66:67], v[70:71], v[20:21]
	v_pk_add_f32 v[34:35], v[34:35], v[48:49]
	v_pk_add_f32 v[38:39], v[38:39], v[52:53]
	v_div_fixup_f32 v18, v18, v74, 1.0
	v_pk_fma_f32 v[20:21], v[18:19], v[66:67], v[80:81] op_sel_hi:[0,1,1] neg_lo:[0,0,1] neg_hi:[0,0,1]
	v_pk_fma_f32 v[48:49], v[18:19], v[34:35], v[82:83] op_sel_hi:[0,1,1] neg_lo:[0,0,1] neg_hi:[0,0,1]
	v_pk_fma_f32 v[52:53], v[18:19], v[38:39], v[84:85] op_sel_hi:[0,1,1] neg_lo:[0,0,1] neg_hi:[0,0,1]
	v_pk_fma_f32 v[18:19], v[18:19], v[54:55], v[78:79] op_sel_hi:[0,1,1] neg_lo:[0,0,1] neg_hi:[0,0,1]
	v_pk_mul_f32 v[20:21], v[20:21], v[10:11]
	v_pk_mul_f32 v[48:49], v[48:49], v[12:13]
	v_pk_mul_f32 v[52:53], v[52:53], v[6:7]
	v_pk_mul_f32 v[18:19], v[18:19], v[8:9]
	v_lshl_add_u64 v[64:65], v[110:111], 0, v[26:27]
	v_lshl_add_u64 v[26:27], v[112:113], 0, v[26:27]
	s_waitcnt vmcnt(0)
	v_lshlrev_b32_e32 v70, 16, v22
	v_and_b32_e32 v71, 0xffff0000, v22
	v_lshlrev_b32_e32 v22, 16, v23
	v_and_b32_e32 v23, 0xffff0000, v23
	v_lshlrev_b32_e32 v72, 16, v24
	v_and_b32_e32 v73, 0xffff0000, v24
	v_lshlrev_b32_e32 v24, 16, v25
	v_and_b32_e32 v25, 0xffff0000, v25
	v_pk_mul_f32 v[20:21], v[20:21], v[70:71]
	v_pk_mul_f32 v[22:23], v[48:49], v[22:23]
	v_pk_mul_f32 v[48:49], v[52:53], v[72:73]
	v_pk_mul_f32 v[24:25], v[18:19], v[24:25]
	v_cvt_pk_bf16_f32 v18, v20, v21
	v_cvt_pk_bf16_f32 v19, v22, v23
	v_cvt_pk_bf16_f32 v20, v48, v49
	v_cvt_pk_bf16_f32 v21, v24, v25
	global_store_dwordx4 v[62:63], v[18:21], off offset:512 sc1
	global_load_dwordx4 v[18:21], v[64:65], off offset:512
	v_min_u32_e32 v64, v114, v221
	v_lshlrev_b32_e32 v24, 16, v17
	v_and_b32_e32 v25, 0xffff0000, v17
	v_sub_u32_e32 v64, v64, v96
	v_lshlrev_b32_e32 v48, 16, v14
	v_and_b32_e32 v49, 0xffff0000, v14
	v_lshlrev_b32_e32 v52, 16, v15
	v_and_b32_e32 v53, 0xffff0000, v15
	v_pk_add_f32 v[14:15], v[24:25], v[36:37] neg_lo:[0,1] neg_hi:[0,1]
	v_add_u32_e32 v36, 2, v64
	v_cvt_f32_i32_e32 v64, v36
	v_lshlrev_b32_e32 v62, 16, v16
	v_and_b32_e32 v63, 0xffff0000, v16
	v_pk_add_f32 v[16:17], v[48:49], v[40:41] neg_lo:[0,1] neg_hi:[0,1]
	v_div_scale_f32 v65, s[16:17], v64, v64, 1.0
	v_pk_add_f32 v[40:41], v[62:63], v[68:69] neg_lo:[0,1] neg_hi:[0,1]
	v_rcp_f32_e32 v69, v65
	v_pk_add_f32 v[36:37], v[52:53], v[44:45] neg_lo:[0,1] neg_hi:[0,1]
	v_pk_add_f32 v[44:45], v[54:55], v[14:15]
	v_div_scale_f32 v68, vcc, 1.0, v64, 1.0
	v_fma_f32 v14, -v65, v69, 1.0
	v_fmac_f32_e32 v69, v14, v69
	v_mul_f32_e32 v14, v68, v69
	v_fma_f32 v15, -v65, v14, v68
	v_fmac_f32_e32 v14, v15, v69
	v_fma_f32 v15, -v65, v14, v68
	v_div_fmas_f32 v14, v15, v69, v14
	v_pk_add_f32 v[54:55], v[66:67], v[16:17]
	v_pk_add_f32 v[34:35], v[34:35], v[36:37]
	v_pk_add_f32 v[36:37], v[38:39], v[40:41]
	v_div_fixup_f32 v14, v14, v64, 1.0
	v_pk_fma_f32 v[16:17], v[14:15], v[54:55], v[46:47] op_sel_hi:[0,1,1] neg_lo:[0,0,1] neg_hi:[0,0,1]
	v_pk_fma_f32 v[38:39], v[14:15], v[34:35], v[50:51] op_sel_hi:[0,1,1] neg_lo:[0,0,1] neg_hi:[0,0,1]
	v_pk_fma_f32 v[40:41], v[14:15], v[36:37], v[60:61] op_sel_hi:[0,1,1] neg_lo:[0,0,1] neg_hi:[0,0,1]
	v_pk_fma_f32 v[14:15], v[14:15], v[44:45], v[28:29] op_sel_hi:[0,1,1] neg_lo:[0,0,1] neg_hi:[0,0,1]
	v_pk_mul_f32 v[16:17], v[16:17], v[10:11]
	v_pk_mul_f32 v[28:29], v[38:39], v[12:13]
	v_pk_mul_f32 v[38:39], v[40:41], v[6:7]
	v_pk_mul_f32 v[14:15], v[14:15], v[8:9]
	v_lshlrev_b64 v[22:23], 11, v[58:59]
	v_lshl_add_u64 v[22:23], v[110:111], 0, v[22:23]
	s_waitcnt vmcnt(0)
	v_lshlrev_b32_e32 v40, 16, v18
	v_and_b32_e32 v41, 0xffff0000, v18
	v_lshlrev_b32_e32 v18, 16, v19
	v_and_b32_e32 v19, 0xffff0000, v19
	v_lshlrev_b32_e32 v46, 16, v20
	v_and_b32_e32 v47, 0xffff0000, v20
	v_lshlrev_b32_e32 v20, 16, v21
	v_and_b32_e32 v21, 0xffff0000, v21
	v_pk_mul_f32 v[16:17], v[16:17], v[40:41]
	v_pk_mul_f32 v[18:19], v[28:29], v[18:19]
	v_pk_mul_f32 v[28:29], v[38:39], v[46:47]
	v_pk_mul_f32 v[20:21], v[14:15], v[20:21]
	v_cvt_pk_bf16_f32 v14, v16, v17
	v_cvt_pk_bf16_f32 v15, v18, v19
	v_cvt_pk_bf16_f32 v16, v28, v29
	v_cvt_pk_bf16_f32 v17, v20, v21
	global_store_dwordx4 v[26:27], v[14:17], off offset:512 sc1
	global_load_dwordx4 v[14:17], v[22:23], off offset:512
	v_add_u32_e32 v28, 9, v222
	v_lshlrev_b32_e32 v18, 16, v5
	v_and_b32_e32 v19, 0xffff0000, v5
	v_lshlrev_b32_e32 v20, 16, v2
	v_and_b32_e32 v21, 0xffff0000, v2
	v_min_u32_e32 v28, v28, v221
	v_lshlrev_b32_e32 v22, 16, v4
	v_and_b32_e32 v23, 0xffff0000, v4
	v_pk_add_f32 v[4:5], v[18:19], v[30:31] neg_lo:[0,1] neg_hi:[0,1]
	v_pk_add_f32 v[18:19], v[20:21], v[32:33] neg_lo:[0,1] neg_hi:[0,1]
	v_sub_u32_e32 v20, v28, v95
	v_add_u32_e32 v20, 2, v20
	v_cvt_f32_i32_e32 v28, v20
	v_pk_add_f32 v[20:21], v[22:23], v[56:57] neg_lo:[0,1] neg_hi:[0,1]
	v_lshlrev_b32_e32 v2, 16, v3
	v_and_b32_e32 v3, 0xffff0000, v3
	v_div_scale_f32 v22, s[16:17], v28, v28, 1.0
	v_rcp_f32_e32 v29, v22
	v_div_scale_f32 v23, vcc, 1.0, v28, 1.0
	v_pk_add_f32 v[2:3], v[2:3], v[42:43] neg_lo:[0,1] neg_hi:[0,1]
	v_fma_f32 v30, -v22, v29, 1.0
	v_fmac_f32_e32 v29, v30, v29
	v_mul_f32_e32 v30, v23, v29
	v_fma_f32 v31, -v22, v30, v23
	v_fmac_f32_e32 v30, v31, v29
	v_fma_f32 v22, -v22, v30, v23
	v_div_fmas_f32 v22, v22, v29, v30
	v_pk_add_f32 v[18:19], v[54:55], v[18:19]
	v_pk_add_f32 v[2:3], v[34:35], v[2:3]
	v_pk_add_f32 v[20:21], v[36:37], v[20:21]
	v_div_fixup_f32 v22, v22, v28, 1.0
	v_pk_add_f32 v[4:5], v[44:45], v[4:5]
	v_pk_fma_f32 v[18:19], v[22:23], v[18:19], v[48:49] op_sel_hi:[0,1,1] neg_lo:[0,0,1] neg_hi:[0,0,1]
	v_pk_fma_f32 v[2:3], v[22:23], v[2:3], v[52:53] op_sel_hi:[0,1,1] neg_lo:[0,0,1] neg_hi:[0,0,1]
	v_pk_fma_f32 v[20:21], v[22:23], v[20:21], v[62:63] op_sel_hi:[0,1,1] neg_lo:[0,0,1] neg_hi:[0,0,1]
	v_pk_fma_f32 v[4:5], v[22:23], v[4:5], v[24:25] op_sel_hi:[0,1,1] neg_lo:[0,0,1] neg_hi:[0,0,1]
	v_pk_mul_f32 v[10:11], v[10:11], v[18:19]
	v_pk_mul_f32 v[2:3], v[12:13], v[2:3]
	v_pk_mul_f32 v[6:7], v[6:7], v[20:21]
	v_pk_mul_f32 v[4:5], v[8:9], v[4:5]
	v_lshlrev_b64 v[26:27], 10, v[58:59]
	s_waitcnt vmcnt(0)
	v_lshlrev_b32_e32 v12, 16, v14
	v_and_b32_e32 v13, 0xffff0000, v14
	v_lshlrev_b32_e32 v14, 16, v15
	v_and_b32_e32 v15, 0xffff0000, v15
	v_lshlrev_b32_e32 v18, 16, v16
	v_and_b32_e32 v19, 0xffff0000, v16
	v_lshlrev_b32_e32 v8, 16, v17
	v_and_b32_e32 v9, 0xffff0000, v17
	v_pk_mul_f32 v[10:11], v[10:11], v[12:13]
	v_pk_mul_f32 v[12:13], v[2:3], v[14:15]
	v_pk_mul_f32 v[14:15], v[6:7], v[18:19]
	v_pk_mul_f32 v[6:7], v[4:5], v[8:9]
	v_cvt_pk_bf16_f32 v2, v10, v11
	v_cvt_pk_bf16_f32 v3, v12, v13
	v_cvt_pk_bf16_f32 v4, v14, v15
	v_mov_b64_e32 v[8:9], v[106:107]

.LBB0_306:
	s_or_b64 exec, exec, s[12:13]
	v_cvt_pk_bf16_f32 v5, v6, v7
	v_lshl_add_u64 v[6:7], v[26:27], 1, s[6:7]
	v_lshl_add_u64 v[6:7], v[8:9], 1, v[6:7]
	global_store_dwordx4 v[6:7], v[2:5], off sc1
	s_mov_b32 s12, s77
	s_waitcnt lgkmcnt(0)
	v_lshl_add_u32 v149, s12, 2, v149
	v_cmp_lt_i32_e32 vcc, s18, v149
	s_or_b64 s[10:11], vcc, s[10:11]
	s_andn2_b64 exec, exec, s[10:11]
	s_cbranch_execz .LBB0_433

.LBB0_355:
	s_or_b64 exec, exec, s[16:17]
	v_add_u32_e32 v94, v222, v94
	v_ashrrev_i32_e32 v95, 31, v94
	v_lshlrev_b64 v[192:193], 11, v[94:95]
	v_lshl_add_u64 v[94:95], v[110:111], 0, v[192:193]
	global_load_dwordx4 v[94:97], v[94:95], off offset:1536
	s_waitcnt vmcnt(0)
	v_lshlrev_b32_e32 v172, 16, v14
	v_and_b32_e32 v173, 0xffff0000, v14
	v_lshlrev_b32_e32 v178, 16, v15
	v_and_b32_e32 v179, 0xffff0000, v15
	v_min_u32_e32 v14, v126, v221
	v_sub_u32_e64 v15, v222, 8 clamp
	v_sub_u32_e32 v14, v14, v15
	v_cvt_f32_i32_e32 v14, v14
	v_lshlrev_b32_e32 v180, 16, v16
	v_and_b32_e32 v181, 0xffff0000, v16
	v_lshlrev_b32_e32 v182, 16, v17
	v_div_scale_f32 v15, s[16:17], v14, v14, 1.0
	v_rcp_f32_e32 v16, v15
	v_and_b32_e32 v183, 0xffff0000, v17
	v_lshlrev_b32_e32 v156, 16, v18
	v_and_b32_e32 v157, 0xffff0000, v18
	v_fma_f32 v17, -v15, v16, 1.0
	v_fmac_f32_e32 v16, v17, v16
	v_div_scale_f32 v17, vcc, 1.0, v14, 1.0
	v_mul_f32_e32 v18, v17, v16
	v_lshlrev_b32_e32 v144, 16, v19
	v_and_b32_e32 v145, 0xffff0000, v19
	v_fma_f32 v19, -v15, v18, v17
	v_fmac_f32_e32 v18, v19, v16
	v_fma_f32 v15, -v15, v18, v17
	v_div_fmas_f32 v15, v15, v16, v18
	v_lshlrev_b32_e32 v142, 16, v20
	v_and_b32_e32 v143, 0xffff0000, v20
	v_lshlrev_b32_e32 v140, 16, v21
	v_and_b32_e32 v141, 0xffff0000, v21
	v_div_fixup_f32 v188, v15, v14, 1.0
	global_load_dwordx4 v[14:17], v[102:103], off offset:3088
	global_load_dwordx4 v[18:21], v[102:103], off offset:3072
	v_lshlrev_b32_e32 v190, 16, v58
	v_and_b32_e32 v191, 0xffff0000, v58
	v_lshlrev_b32_e32 v198, 16, v59
	v_and_b32_e32 v199, 0xffff0000, v59
	v_pk_add_f32 v[58:59], v[178:179], 0 op_sel_hi:[1,0]
	v_lshlrev_b32_e32 v184, 16, v3
	v_and_b32_e32 v185, 0xffff0000, v3
	v_lshlrev_b32_e32 v176, 16, v2
	v_and_b32_e32 v177, 0xffff0000, v2
	v_pk_add_f32 v[2:3], v[58:59], v[184:185]
	v_lshlrev_b32_e32 v174, 16, v67
	v_and_b32_e32 v175, 0xffff0000, v67
	v_lshlrev_b32_e32 v170, 16, v90
	v_and_b32_e32 v171, 0xffff0000, v90
	v_lshlrev_b32_e32 v168, 16, v91
	v_and_b32_e32 v169, 0xffff0000, v91
	v_pk_add_f32 v[90:91], v[172:173], 0 op_sel_hi:[1,0]
	v_pk_add_f32 v[2:3], v[2:3], v[174:175]
	v_lshlrev_b32_e32 v158, 16, v63
	v_and_b32_e32 v159, 0xffff0000, v63
	v_pk_add_f32 v[90:91], v[90:91], v[176:177]
	v_lshlrev_b32_e32 v162, 16, v66
	v_and_b32_e32 v163, 0xffff0000, v66
	v_pk_add_f32 v[2:3], v[2:3], v[158:159]
	v_lshlrev_b32_e32 v66, 16, v31
	v_and_b32_e32 v67, 0xffff0000, v31
	v_pk_add_f32 v[90:91], v[90:91], v[162:163]
	v_lshlrev_b32_e32 v138, 16, v62
	v_and_b32_e32 v139, 0xffff0000, v62
	v_pk_add_f32 v[2:3], v[2:3], v[66:67]
	v_lshlrev_b32_e32 v58, 16, v23
	v_and_b32_e32 v59, 0xffff0000, v23
	v_pk_add_f32 v[90:91], v[90:91], v[138:139]
	v_lshlrev_b32_e32 v130, 16, v30
	v_and_b32_e32 v131, 0xffff0000, v30
	v_lshlrev_b32_e32 v126, 16, v22
	v_and_b32_e32 v127, 0xffff0000, v22
	v_pk_add_f32 v[22:23], v[2:3], v[58:59]
	v_lshlrev_b32_e32 v2, 16, v47
	v_and_b32_e32 v3, 0xffff0000, v47
	v_pk_add_f32 v[90:91], v[90:91], v[130:131]
	v_pk_add_f32 v[22:23], v[22:23], v[2:3]
	v_lshlrev_b32_e32 v30, 16, v43
	v_and_b32_e32 v31, 0xffff0000, v43
	v_lshlrev_b32_e32 v166, 16, v92
	v_and_b32_e32 v167, 0xffff0000, v92
	v_lshlrev_b32_e32 v160, 16, v93
	v_and_b32_e32 v161, 0xffff0000, v93
	v_pk_add_f32 v[92:93], v[90:91], v[126:127]
	v_lshlrev_b32_e32 v90, 16, v46
	v_and_b32_e32 v91, 0xffff0000, v46
	v_pk_add_f32 v[22:23], v[22:23], v[30:31]
	v_pk_add_f32 v[30:31], v[180:181], 0 op_sel_hi:[1,0]
	v_lshlrev_b32_e32 v186, 16, v4
	v_and_b32_e32 v187, 0xffff0000, v4
	v_pk_add_f32 v[92:93], v[92:93], v[90:91]
	v_lshlrev_b32_e32 v128, 16, v42
	v_and_b32_e32 v129, 0xffff0000, v42
	v_lshlrev_b32_e32 v196, 16, v94
	v_and_b32_e32 v197, 0xffff0000, v94
	v_lshlrev_b32_e32 v202, 16, v95
	v_and_b32_e32 v203, 0xffff0000, v95
	v_pk_add_f32 v[30:31], v[30:31], v[186:187]
	v_lshlrev_b32_e32 v94, 16, v68
	v_and_b32_e32 v95, 0xffff0000, v68
	v_pk_add_f32 v[92:93], v[92:93], v[128:129]
	v_lshlrev_b32_e32 v128, 16, v82
	v_and_b32_e32 v129, 0xffff0000, v82
	v_lshlrev_b32_e32 v46, 16, v83
	v_and_b32_e32 v47, 0xffff0000, v83
	v_pk_add_f32 v[30:31], v[30:31], v[94:95]
	v_lshlrev_b32_e32 v82, 16, v64
	v_and_b32_e32 v83, 0xffff0000, v64
	v_lshlrev_b32_e32 v154, 16, v69
	v_and_b32_e32 v155, 0xffff0000, v69
	v_pk_add_f32 v[30:31], v[30:31], v[82:83]
	v_lshlrev_b32_e32 v68, 16, v32
	v_and_b32_e32 v69, 0xffff0000, v32
	v_pk_add_f32 v[30:31], v[30:31], v[68:69]
	v_lshlrev_b32_e32 v62, 16, v24
	v_and_b32_e32 v63, 0xffff0000, v24
	v_pk_add_f32 v[42:43], v[30:31], v[62:63]
	v_lshlrev_b32_e32 v30, 16, v48
	v_and_b32_e32 v31, 0xffff0000, v48
	v_lshlrev_b32_e32 v134, 16, v65
	v_and_b32_e32 v135, 0xffff0000, v65
	v_pk_add_f32 v[42:43], v[42:43], v[30:31]
	v_lshlrev_b32_e32 v64, 16, v44
	v_and_b32_e32 v65, 0xffff0000, v44
	v_pk_add_f32 v[42:43], v[42:43], v[64:65]
	v_lshlrev_b32_e32 v64, 16, v84
	v_and_b32_e32 v65, 0xffff0000, v84
	v_lshl_add_u64 v[206:207], v[112:113], 0, v[192:193]
	v_lshlrev_b32_e32 v192, 16, v33
	v_and_b32_e32 v193, 0xffff0000, v33
	v_lshlrev_b32_e32 v32, 16, v49
	v_and_b32_e32 v33, 0xffff0000, v49
	v_lshlrev_b32_e32 v48, 16, v85
	v_and_b32_e32 v49, 0xffff0000, v85
	v_pk_add_f32 v[84:85], v[182:183], 0 op_sel_hi:[1,0]
	v_lshlrev_b32_e32 v4, 16, v5
	v_and_b32_e32 v5, 0xffff0000, v5
	v_pk_add_f32 v[84:85], v[84:85], v[4:5]
	v_lshlrev_b64 v[208:209], 11, v[136:137]
	v_pk_add_f32 v[84:85], v[84:85], v[154:155]
	v_lshlrev_b32_e32 v136, 16, v25
	v_pk_add_f32 v[84:85], v[84:85], v[134:135]
	v_and_b32_e32 v137, 0xffff0000, v25
	v_pk_add_f32 v[84:85], v[84:85], v[192:193]
	v_lshlrev_b32_e32 v204, 16, v60
	v_pk_add_f32 v[84:85], v[84:85], v[136:137]
	v_and_b32_e32 v205, 0xffff0000, v60
	v_lshlrev_b32_e32 v44, 16, v45
	v_and_b32_e32 v45, 0xffff0000, v45
	v_pk_add_f32 v[84:85], v[84:85], v[32:33]
	v_pk_add_f32 v[212:213], v[42:43], v[204:205]
	v_lshlrev_b32_e32 v42, 16, v88
	v_and_b32_e32 v43, 0xffff0000, v88
	v_lshlrev_b32_e32 v24, 16, v89
	v_and_b32_e32 v25, 0xffff0000, v89
	v_lshlrev_b32_e32 v88, 16, v61
	v_and_b32_e32 v89, 0xffff0000, v61
	v_pk_add_f32 v[44:45], v[84:85], v[44:45]
	v_lshlrev_b32_e32 v84, 16, v37
	v_pk_add_f32 v[44:45], v[44:45], v[88:89]
	v_and_b32_e32 v85, 0xffff0000, v37
	v_pk_add_f32 v[44:45], v[44:45], v[84:85]
	v_pk_add_f32 v[194:195], v[92:93], v[190:191]
	v_pk_add_f32 v[44:45], v[44:45], v[160:161]
	v_lshlrev_b32_e32 v92, 16, v86
	v_and_b32_e32 v93, 0xffff0000, v86
	v_pk_add_f32 v[200:201], v[22:23], v[198:199]
	v_lshlrev_b32_e32 v22, 16, v87
	v_and_b32_e32 v23, 0xffff0000, v87
	v_lshlrev_b32_e32 v86, 16, v80
	v_and_b32_e32 v87, 0xffff0000, v80
	v_lshlrev_b32_e32 v80, 16, v81
	v_and_b32_e32 v81, 0xffff0000, v81
	v_pk_add_f32 v[44:45], v[44:45], v[140:141]
	v_lshlrev_b32_e32 v60, 16, v77
	v_and_b32_e32 v61, 0xffff0000, v77
	v_pk_add_f32 v[44:45], v[44:45], v[80:81]
	v_lshlrev_b32_e32 v152, 16, v78
	v_pk_add_f32 v[44:45], v[44:45], v[60:61]
	v_and_b32_e32 v153, 0xffff0000, v78
	v_pk_add_f32 v[44:45], v[44:45], v[48:49]
	v_lshlrev_b32_e32 v164, 16, v79
	v_pk_add_f32 v[44:45], v[44:45], v[24:25]
	v_and_b32_e32 v165, 0xffff0000, v79
	v_pk_fma_f32 v[88:89], v[188:189], v[44:45], v[88:89] op_sel_hi:[0,1,1] neg_lo:[0,0,1] neg_hi:[0,0,1]
	v_lshlrev_b32_e32 v78, 16, v76
	v_and_b32_e32 v79, 0xffff0000, v76
	v_lshlrev_b32_e32 v76, 16, v97
	v_and_b32_e32 v77, 0xffff0000, v97
	s_waitcnt vmcnt(1)
	v_pk_mul_f32 v[88:89], v[88:89], v[16:17]
	v_lshlrev_b32_e32 v214, 16, v96
	v_pk_mul_f32 v[76:77], v[88:89], v[76:77]
	v_and_b32_e32 v215, 0xffff0000, v96
	v_cvt_pk_bf16_f32 v37, v76, v77
	v_lshlrev_b32_e32 v76, 16, v36
	v_and_b32_e32 v77, 0xffff0000, v36
	v_pk_add_f32 v[88:89], v[212:213], v[76:77]
	v_lshlrev_b32_e32 v132, 16, v74
	v_pk_add_f32 v[88:89], v[88:89], v[166:167]
	v_and_b32_e32 v133, 0xffff0000, v74
	v_pk_add_f32 v[88:89], v[88:89], v[142:143]
	v_lshlrev_b32_e32 v74, 16, v75
	v_pk_add_f32 v[88:89], v[88:89], v[86:87]
	v_and_b32_e32 v75, 0xffff0000, v75
	v_pk_add_f32 v[88:89], v[88:89], v[78:79]
	v_lshl_add_u64 v[210:211], v[110:111], 0, v[208:209]
	v_pk_add_f32 v[88:89], v[88:89], v[64:65]
	v_lshlrev_b64 v[124:125], 11, v[124:125]
	v_pk_add_f32 v[88:89], v[88:89], v[42:43]
	v_lshlrev_b64 v[122:123], 11, v[122:123]
	v_pk_fma_f32 v[96:97], v[188:189], v[88:89], v[204:205] op_sel_hi:[0,1,1] neg_lo:[0,0,1] neg_hi:[0,0,1]
	v_pk_mul_f32 v[96:97], v[96:97], v[14:15]
	s_nop 0
	v_pk_mul_f32 v[96:97], v[96:97], v[214:215]
	s_nop 0
	v_cvt_pk_bf16_f32 v36, v96, v97
	v_lshlrev_b32_e32 v96, 16, v35
	v_and_b32_e32 v97, 0xffff0000, v35
	v_pk_add_f32 v[200:201], v[200:201], v[96:97]
	s_nop 0
	v_pk_add_f32 v[200:201], v[200:201], v[168:169]
	s_nop 0
	v_pk_add_f32 v[200:201], v[200:201], v[144:145]
	s_nop 0
	v_pk_add_f32 v[200:201], v[200:201], v[164:165]
	s_nop 0
	v_pk_add_f32 v[200:201], v[200:201], v[74:75]
	s_nop 0
	v_pk_add_f32 v[200:201], v[200:201], v[46:47]
	s_nop 0
	v_pk_add_f32 v[200:201], v[200:201], v[22:23]
	s_nop 0
	v_pk_fma_f32 v[198:199], v[188:189], v[200:201], v[198:199] op_sel_hi:[0,1,1] neg_lo:[0,0,1] neg_hi:[0,0,1]
	s_waitcnt vmcnt(0)
	v_pk_mul_f32 v[198:199], v[198:199], v[20:21]
	s_nop 0
	v_pk_mul_f32 v[198:199], v[198:199], v[202:203]
	v_and_b32_e32 v203, 0xffff0000, v73
	v_cvt_pk_bf16_f32 v35, v198, v199
	v_lshlrev_b32_e32 v198, 16, v34
	v_and_b32_e32 v199, 0xffff0000, v34
	v_pk_add_f32 v[194:195], v[194:195], v[198:199]
	s_nop 0
	v_pk_add_f32 v[194:195], v[194:195], v[170:171]
	s_nop 0
	v_pk_add_f32 v[194:195], v[194:195], v[156:157]
	s_nop 0
	v_pk_add_f32 v[194:195], v[194:195], v[152:153]
	s_nop 0
	v_pk_add_f32 v[194:195], v[194:195], v[132:133]
	s_nop 0
	v_pk_add_f32 v[194:195], v[194:195], v[128:129]
	s_nop 0
	v_pk_add_f32 v[194:195], v[194:195], v[92:93]
	s_nop 0
	v_pk_fma_f32 v[190:191], v[188:189], v[194:195], v[190:191] op_sel_hi:[0,1,1] neg_lo:[0,0,1] neg_hi:[0,0,1]
	v_pk_mul_f32 v[190:191], v[190:191], v[18:19]
	v_min_u32_e32 v188, v235, v221
	v_pk_mul_f32 v[190:191], v[190:191], v[196:197]
	s_nop 0
	v_cvt_pk_bf16_f32 v34, v190, v191
	global_store_dwordx4 v[206:207], v[34:37], off offset:1536 sc1
	global_load_dwordx4 v[34:37], v[210:211], off offset:1536
	v_sub_u32_e64 v190, v229, 8 clamp
	v_sub_u32_e32 v188, v188, v190
	v_cvt_f32_i32_e32 v188, v188
	v_div_scale_f32 v190, s[16:17], v188, v188, 1.0
	v_rcp_f32_e32 v191, v190
	s_nop 0
	v_fma_f32 v196, -v190, v191, 1.0
	v_fmac_f32_e32 v191, v196, v191
	v_div_scale_f32 v196, vcc, 1.0, v188, 1.0
	v_mul_f32_e32 v197, v196, v191
	v_fma_f32 v202, -v190, v197, v196
	v_fmac_f32_e32 v197, v202, v191
	v_lshlrev_b32_e32 v202, 16, v73
	v_pk_add_f32 v[182:183], v[202:203], v[182:183] neg_lo:[0,1] neg_hi:[0,1]
	v_fma_f32 v190, -v190, v197, v196
	v_pk_add_f32 v[44:45], v[44:45], v[182:183]
	v_lshlrev_b32_e32 v182, 16, v72
	v_and_b32_e32 v183, 0xffff0000, v72
	v_pk_add_f32 v[72:73], v[182:183], v[180:181] neg_lo:[0,1] neg_hi:[0,1]
	v_div_fmas_f32 v190, v190, v191, v197
	v_pk_add_f32 v[72:73], v[88:89], v[72:73]
	v_lshlrev_b32_e32 v88, 16, v71
	v_and_b32_e32 v89, 0xffff0000, v71
	v_pk_add_f32 v[88:89], v[88:89], v[178:179] neg_lo:[0,1] neg_hi:[0,1]
	v_lshlrev_b32_e32 v178, 16, v70
	v_and_b32_e32 v179, 0xffff0000, v70
	v_pk_add_f32 v[70:71], v[178:179], v[172:173] neg_lo:[0,1] neg_hi:[0,1]
	v_div_fixup_f32 v188, v190, v188, 1.0
	v_pk_add_f32 v[88:89], v[200:201], v[88:89]
	v_pk_add_f32 v[70:71], v[194:195], v[70:71]
	v_pk_fma_f32 v[96:97], v[188:189], v[88:89], v[96:97] op_sel_hi:[0,1,1] neg_lo:[0,0,1] neg_hi:[0,0,1]
	v_pk_fma_f32 v[172:173], v[188:189], v[70:71], v[198:199] op_sel_hi:[0,1,1] neg_lo:[0,0,1] neg_hi:[0,0,1]
	v_pk_fma_f32 v[76:77], v[188:189], v[72:73], v[76:77] op_sel_hi:[0,1,1] neg_lo:[0,0,1] neg_hi:[0,0,1]
	v_pk_mul_f32 v[96:97], v[96:97], v[20:21]
	v_pk_mul_f32 v[172:173], v[172:173], v[18:19]
	v_pk_mul_f32 v[76:77], v[76:77], v[14:15]
	v_lshl_add_u64 v[190:191], v[112:113], 0, v[208:209]
	v_lshl_add_u64 v[196:197], v[110:111], 0, v[124:125]
	s_waitcnt vmcnt(0)
	v_lshlrev_b32_e32 v178, 16, v34
	v_and_b32_e32 v179, 0xffff0000, v34
	v_lshlrev_b32_e32 v180, 16, v35
	v_and_b32_e32 v181, 0xffff0000, v35
	v_lshlrev_b32_e32 v182, 16, v36
	v_and_b32_e32 v183, 0xffff0000, v36
	v_lshlrev_b32_e32 v194, 16, v37
	v_and_b32_e32 v195, 0xffff0000, v37
	v_pk_mul_f32 v[34:35], v[172:173], v[178:179]
	v_pk_mul_f32 v[36:37], v[96:97], v[180:181]
	v_cvt_pk_bf16_f32 v34, v34, v35
	v_cvt_pk_bf16_f32 v35, v36, v37
	v_pk_mul_f32 v[36:37], v[76:77], v[182:183]
	v_pk_fma_f32 v[76:77], v[188:189], v[44:45], v[84:85] op_sel_hi:[0,1,1] neg_lo:[0,0,1] neg_hi:[0,0,1]
	v_pk_mul_f32 v[76:77], v[76:77], v[16:17]
	v_cvt_pk_bf16_f32 v36, v36, v37
	v_pk_mul_f32 v[76:77], v[76:77], v[194:195]
	s_nop 0
	v_cvt_pk_bf16_f32 v37, v76, v77
	global_store_dwordx4 v[190:191], v[34:37], off offset:1536 sc1
	global_load_dwordx4 v[34:37], v[196:197], off offset:1536
	v_min_u32_e32 v76, v234, v221
	v_sub_u32_e64 v77, v228, 8 clamp
	v_sub_u32_e32 v76, v76, v77
	v_cvt_f32_i32_e32 v84, v76
	v_lshlrev_b32_e32 v76, 16, v57
	v_and_b32_e32 v77, 0xffff0000, v57
	v_pk_add_f32 v[4:5], v[76:77], v[4:5] neg_lo:[0,1] neg_hi:[0,1]
	v_div_scale_f32 v85, s[16:17], v84, v84, 1.0
	v_rcp_f32_e32 v96, v85
	v_pk_add_f32 v[4:5], v[44:45], v[4:5]
	v_lshlrev_b32_e32 v44, 16, v54
	v_and_b32_e32 v45, 0xffff0000, v54
	v_fma_f32 v57, -v85, v96, 1.0
	v_fmac_f32_e32 v96, v57, v96
	v_div_scale_f32 v57, vcc, 1.0, v84, 1.0
	v_mul_f32_e32 v97, v57, v96
	v_fma_f32 v172, -v85, v97, v57
	v_fmac_f32_e32 v97, v172, v96
	v_fma_f32 v57, -v85, v97, v57
	v_div_fmas_f32 v57, v57, v96, v97
	v_pk_add_f32 v[44:45], v[44:45], v[176:177] neg_lo:[0,1] neg_hi:[0,1]
	v_div_fixup_f32 v84, v57, v84, 1.0
	v_pk_add_f32 v[44:45], v[70:71], v[44:45]
	v_lshlrev_b32_e32 v54, 16, v55
	v_pk_fma_f32 v[70:71], v[84:85], v[44:45], v[170:171] op_sel_hi:[0,1,1] neg_lo:[0,0,1] neg_hi:[0,0,1]
	v_and_b32_e32 v55, 0xffff0000, v55
	v_pk_mul_f32 v[70:71], v[70:71], v[18:19]
	v_pk_add_f32 v[54:55], v[54:55], v[184:185] neg_lo:[0,1] neg_hi:[0,1]
	v_lshl_add_u64 v[96:97], v[112:113], 0, v[124:125]
	v_pk_add_f32 v[54:55], v[88:89], v[54:55]
	v_lshl_add_u64 v[124:125], v[110:111], 0, v[122:123]
	s_waitcnt vmcnt(0)
	v_lshlrev_b32_e32 v76, 16, v34
	v_and_b32_e32 v77, 0xffff0000, v34
	v_pk_mul_f32 v[70:71], v[70:71], v[76:77]
	v_lshlrev_b32_e32 v76, 16, v35
	v_cvt_pk_bf16_f32 v34, v70, v71
	v_pk_fma_f32 v[70:71], v[84:85], v[54:55], v[168:169] op_sel_hi:[0,1,1] neg_lo:[0,0,1] neg_hi:[0,0,1]
	v_pk_mul_f32 v[70:71], v[70:71], v[20:21]
	v_and_b32_e32 v77, 0xffff0000, v35
	v_pk_mul_f32 v[70:71], v[70:71], v[76:77]
	s_nop 0
	v_cvt_pk_bf16_f32 v35, v70, v71
	v_lshlrev_b32_e32 v70, 16, v56
	v_and_b32_e32 v71, 0xffff0000, v56
	v_pk_add_f32 v[56:57], v[70:71], v[186:187] neg_lo:[0,1] neg_hi:[0,1]
	s_nop 0
	v_pk_add_f32 v[56:57], v[72:73], v[56:57]
	v_lshlrev_b32_e32 v72, 16, v36
	v_pk_fma_f32 v[70:71], v[84:85], v[56:57], v[166:167] op_sel_hi:[0,1,1] neg_lo:[0,0,1] neg_hi:[0,0,1]
	v_pk_mul_f32 v[70:71], v[70:71], v[14:15]
	v_and_b32_e32 v73, 0xffff0000, v36
	v_pk_mul_f32 v[70:71], v[70:71], v[72:73]
	v_pk_fma_f32 v[72:73], v[84:85], v[4:5], v[160:161] op_sel_hi:[0,1,1] neg_lo:[0,0,1] neg_hi:[0,0,1]
	v_cvt_pk_bf16_f32 v36, v70, v71
	v_lshlrev_b32_e32 v70, 16, v37
	v_and_b32_e32 v71, 0xffff0000, v37
	v_pk_mul_f32 v[72:73], v[72:73], v[16:17]
	s_nop 0
	v_pk_mul_f32 v[70:71], v[72:73], v[70:71]
	s_nop 0
	v_cvt_pk_bf16_f32 v37, v70, v71
	global_store_dwordx4 v[96:97], v[34:37], off offset:1536 sc1
	global_load_dwordx4 v[34:37], v[124:125], off offset:1536
	v_min_u32_e32 v70, v233, v221
	v_sub_u32_e64 v71, v227, 8 clamp
	v_sub_u32_e32 v70, v70, v71
	v_cvt_f32_i32_e32 v72, v70
	v_lshlrev_b32_e32 v70, 16, v53
	v_and_b32_e32 v71, 0xffff0000, v53
	v_pk_add_f32 v[70:71], v[70:71], v[154:155] neg_lo:[0,1] neg_hi:[0,1]
	v_div_scale_f32 v73, s[16:17], v72, v72, 1.0
	v_rcp_f32_e32 v76, v73
	v_pk_add_f32 v[4:5], v[4:5], v[70:71]
	v_lshlrev_b32_e32 v70, 16, v50
	v_and_b32_e32 v71, 0xffff0000, v50
	v_fma_f32 v53, -v73, v76, 1.0
	v_fmac_f32_e32 v76, v53, v76
	v_div_scale_f32 v53, vcc, 1.0, v72, 1.0
	v_mul_f32_e32 v77, v53, v76
	v_fma_f32 v84, -v73, v77, v53
	v_fmac_f32_e32 v77, v84, v76
	v_fma_f32 v53, -v73, v77, v53
	v_div_fmas_f32 v53, v53, v76, v77
	v_pk_add_f32 v[70:71], v[70:71], v[162:163] neg_lo:[0,1] neg_hi:[0,1]
	v_div_fixup_f32 v72, v53, v72, 1.0
	v_pk_add_f32 v[44:45], v[44:45], v[70:71]
	v_lshlrev_b32_e32 v50, 16, v51
	v_and_b32_e32 v51, 0xffff0000, v51
	v_pk_fma_f32 v[70:71], v[72:73], v[44:45], v[156:157] op_sel_hi:[0,1,1] neg_lo:[0,0,1] neg_hi:[0,0,1]
	v_pk_add_f32 v[50:51], v[50:51], v[174:175] neg_lo:[0,1] neg_hi:[0,1]
	v_pk_mul_f32 v[70:71], v[70:71], v[18:19]
	v_pk_add_f32 v[50:51], v[54:55], v[50:51]
	v_lshl_add_u64 v[76:77], v[112:113], 0, v[122:123]
	v_pk_fma_f32 v[54:55], v[72:73], v[50:51], v[144:145] op_sel_hi:[0,1,1] neg_lo:[0,0,1] neg_hi:[0,0,1]
	v_pk_mul_f32 v[54:55], v[54:55], v[20:21]
	v_lshlrev_b64 v[84:85], 11, v[120:121]
	v_lshl_add_u64 v[88:89], v[110:111], 0, v[84:85]
	s_waitcnt vmcnt(0)
	v_lshlrev_b32_e32 v96, 16, v34
	v_and_b32_e32 v97, 0xffff0000, v34
	v_pk_mul_f32 v[70:71], v[70:71], v[96:97]
	s_nop 0
	v_cvt_pk_bf16_f32 v34, v70, v71
	v_lshlrev_b32_e32 v70, 16, v35
	v_and_b32_e32 v71, 0xffff0000, v35
	v_pk_mul_f32 v[54:55], v[54:55], v[70:71]
	s_nop 0
	v_cvt_pk_bf16_f32 v35, v54, v55
	v_lshlrev_b32_e32 v54, 16, v52
	v_and_b32_e32 v55, 0xffff0000, v52
	v_pk_add_f32 v[52:53], v[54:55], v[94:95] neg_lo:[0,1] neg_hi:[0,1]
	s_nop 0
	v_pk_add_f32 v[52:53], v[56:57], v[52:53]
	v_lshlrev_b32_e32 v56, 16, v36
	v_pk_fma_f32 v[54:55], v[72:73], v[52:53], v[142:143] op_sel_hi:[0,1,1] neg_lo:[0,0,1] neg_hi:[0,0,1]
	v_pk_mul_f32 v[54:55], v[54:55], v[14:15]
	v_and_b32_e32 v57, 0xffff0000, v36
	v_pk_mul_f32 v[54:55], v[54:55], v[56:57]
	v_pk_fma_f32 v[56:57], v[72:73], v[4:5], v[140:141] op_sel_hi:[0,1,1] neg_lo:[0,0,1] neg_hi:[0,0,1]
	v_cvt_pk_bf16_f32 v36, v54, v55
	v_lshlrev_b32_e32 v54, 16, v37
	v_and_b32_e32 v55, 0xffff0000, v37
	v_pk_mul_f32 v[56:57], v[56:57], v[16:17]
	s_nop 0
	v_pk_mul_f32 v[54:55], v[56:57], v[54:55]
	s_nop 0
	v_cvt_pk_bf16_f32 v37, v54, v55
	global_store_dwordx4 v[76:77], v[34:37], off offset:1536 sc1
	global_load_dwordx4 v[34:37], v[88:89], off offset:1536
	v_min_u32_e32 v54, v232, v221
	v_sub_u32_e64 v55, v226, 8 clamp
	v_sub_u32_e32 v54, v54, v55
	v_cvt_f32_i32_e32 v56, v54
	v_lshlrev_b32_e32 v54, 16, v41
	v_and_b32_e32 v55, 0xffff0000, v41
	v_pk_add_f32 v[54:55], v[54:55], v[134:135] neg_lo:[0,1] neg_hi:[0,1]
	v_div_scale_f32 v57, s[16:17], v56, v56, 1.0
	v_rcp_f32_e32 v70, v57
	v_pk_add_f32 v[4:5], v[4:5], v[54:55]
	v_lshlrev_b32_e32 v54, 16, v38
	v_and_b32_e32 v55, 0xffff0000, v38
	v_fma_f32 v41, -v57, v70, 1.0
	v_fmac_f32_e32 v70, v41, v70
	v_div_scale_f32 v41, vcc, 1.0, v56, 1.0
	v_mul_f32_e32 v71, v41, v70
	v_fma_f32 v72, -v57, v71, v41
	v_fmac_f32_e32 v71, v72, v70
	v_fma_f32 v41, -v57, v71, v41
	v_div_fmas_f32 v41, v41, v70, v71
	v_pk_add_f32 v[54:55], v[54:55], v[138:139] neg_lo:[0,1] neg_hi:[0,1]
	v_div_fixup_f32 v56, v41, v56, 1.0
	v_pk_add_f32 v[44:45], v[44:45], v[54:55]
	v_lshlrev_b32_e32 v38, 16, v39
	v_and_b32_e32 v39, 0xffff0000, v39
	v_pk_fma_f32 v[54:55], v[56:57], v[44:45], v[152:153] op_sel_hi:[0,1,1] neg_lo:[0,0,1] neg_hi:[0,0,1]
	v_pk_add_f32 v[38:39], v[38:39], v[158:159] neg_lo:[0,1] neg_hi:[0,1]
	v_lshl_add_u64 v[70:71], v[112:113], 0, v[84:85]
	v_pk_mul_f32 v[54:55], v[54:55], v[18:19]
	v_pk_add_f32 v[38:39], v[50:51], v[38:39]
	v_lshlrev_b64 v[72:73], 11, v[118:119]
	v_pk_fma_f32 v[50:51], v[56:57], v[38:39], v[164:165] op_sel_hi:[0,1,1] neg_lo:[0,0,1] neg_hi:[0,0,1]
	v_pk_mul_f32 v[50:51], v[50:51], v[20:21]
	v_lshl_add_u64 v[76:77], v[110:111], 0, v[72:73]
	s_waitcnt vmcnt(0)
	v_lshlrev_b32_e32 v84, 16, v34
	v_and_b32_e32 v85, 0xffff0000, v34
	v_pk_mul_f32 v[54:55], v[54:55], v[84:85]
	s_nop 0
	v_cvt_pk_bf16_f32 v34, v54, v55
	v_lshlrev_b32_e32 v54, 16, v35
	v_and_b32_e32 v55, 0xffff0000, v35
	v_pk_mul_f32 v[50:51], v[50:51], v[54:55]
	s_nop 0
	v_cvt_pk_bf16_f32 v35, v50, v51
	v_lshlrev_b32_e32 v50, 16, v40
	v_and_b32_e32 v51, 0xffff0000, v40
	v_pk_add_f32 v[40:41], v[50:51], v[82:83] neg_lo:[0,1] neg_hi:[0,1]
	s_nop 0
	v_pk_add_f32 v[40:41], v[52:53], v[40:41]
	v_lshlrev_b32_e32 v52, 16, v36
	v_pk_fma_f32 v[50:51], v[56:57], v[40:41], v[86:87] op_sel_hi:[0,1,1] neg_lo:[0,0,1] neg_hi:[0,0,1]
	v_pk_mul_f32 v[50:51], v[50:51], v[14:15]
	v_and_b32_e32 v53, 0xffff0000, v36
	v_pk_mul_f32 v[50:51], v[50:51], v[52:53]
	v_pk_fma_f32 v[52:53], v[56:57], v[4:5], v[80:81] op_sel_hi:[0,1,1] neg_lo:[0,0,1] neg_hi:[0,0,1]
	v_cvt_pk_bf16_f32 v36, v50, v51
	v_lshlrev_b32_e32 v50, 16, v37
	v_and_b32_e32 v51, 0xffff0000, v37
	v_pk_mul_f32 v[52:53], v[52:53], v[16:17]
	s_nop 0
	v_pk_mul_f32 v[50:51], v[52:53], v[50:51]
	s_nop 0
	v_cvt_pk_bf16_f32 v37, v50, v51
	global_store_dwordx4 v[70:71], v[34:37], off offset:1536 sc1
	global_load_dwordx4 v[34:37], v[76:77], off offset:1536
	v_min_u32_e32 v50, v231, v221
	v_sub_u32_e64 v51, v225, 8 clamp
	v_sub_u32_e32 v50, v50, v51
	v_cvt_f32_i32_e32 v50, v50
	v_lshlrev_b32_e32 v70, 16, v29
	v_and_b32_e32 v71, 0xffff0000, v29
	v_pk_add_f32 v[70:71], v[70:71], v[192:193] neg_lo:[0,1] neg_hi:[0,1]
	v_div_scale_f32 v51, s[16:17], v50, v50, 1.0
	v_rcp_f32_e32 v52, v51
	v_pk_add_f32 v[4:5], v[4:5], v[70:71]
	v_lshlrev_b32_e32 v70, 16, v26
	v_and_b32_e32 v71, 0xffff0000, v26
	v_fma_f32 v53, -v51, v52, 1.0
	v_fmac_f32_e32 v52, v53, v52
	v_div_scale_f32 v53, vcc, 1.0, v50, 1.0
	v_mul_f32_e32 v54, v53, v52
	v_fma_f32 v55, -v51, v54, v53
	v_fmac_f32_e32 v54, v55, v52
	v_fma_f32 v51, -v51, v54, v53
	v_div_fmas_f32 v51, v51, v52, v54
	v_pk_add_f32 v[70:71], v[70:71], v[130:131] neg_lo:[0,1] neg_hi:[0,1]
	v_div_fixup_f32 v50, v51, v50, 1.0
	v_pk_add_f32 v[44:45], v[44:45], v[70:71]
	v_lshl_add_u64 v[52:53], v[112:113], 0, v[72:73]
	v_pk_fma_f32 v[70:71], v[50:51], v[44:45], v[132:133] op_sel_hi:[0,1,1] neg_lo:[0,0,1] neg_hi:[0,0,1]
	v_pk_mul_f32 v[70:71], v[70:71], v[18:19]
	v_lshlrev_b64 v[54:55], 11, v[116:117]
	v_lshl_add_u64 v[56:57], v[110:111], 0, v[54:55]
	s_waitcnt vmcnt(0)
	v_lshlrev_b32_e32 v72, 16, v34
	v_and_b32_e32 v73, 0xffff0000, v34
	v_pk_mul_f32 v[70:71], v[70:71], v[72:73]
	v_lshlrev_b32_e32 v34, 16, v35
	v_cvt_pk_bf16_f32 v26, v70, v71
	v_lshlrev_b32_e32 v70, 16, v27
	v_and_b32_e32 v71, 0xffff0000, v27
	v_pk_add_f32 v[66:67], v[70:71], v[66:67] neg_lo:[0,1] neg_hi:[0,1]
	v_and_b32_e32 v35, 0xffff0000, v35
	v_pk_add_f32 v[38:39], v[38:39], v[66:67]
	s_nop 0
	v_pk_fma_f32 v[66:67], v[50:51], v[38:39], v[74:75] op_sel_hi:[0,1,1] neg_lo:[0,0,1] neg_hi:[0,0,1]
	v_pk_mul_f32 v[66:67], v[66:67], v[20:21]
	s_nop 0
	v_pk_mul_f32 v[34:35], v[66:67], v[34:35]
	s_nop 0
	v_cvt_pk_bf16_f32 v27, v34, v35
	v_lshlrev_b32_e32 v34, 16, v28
	v_and_b32_e32 v35, 0xffff0000, v28
	v_pk_add_f32 v[28:29], v[34:35], v[68:69] neg_lo:[0,1] neg_hi:[0,1]
	s_nop 0
	v_pk_add_f32 v[34:35], v[40:41], v[28:29]
	v_lshlrev_b32_e32 v40, 16, v36
	v_pk_fma_f32 v[28:29], v[50:51], v[34:35], v[78:79] op_sel_hi:[0,1,1] neg_lo:[0,0,1] neg_hi:[0,0,1]
	v_pk_mul_f32 v[28:29], v[28:29], v[14:15]
	v_and_b32_e32 v41, 0xffff0000, v36
	v_pk_mul_f32 v[28:29], v[28:29], v[40:41]
	v_pk_fma_f32 v[40:41], v[50:51], v[4:5], v[60:61] op_sel_hi:[0,1,1] neg_lo:[0,0,1] neg_hi:[0,0,1]
	v_lshlrev_b32_e32 v36, 16, v37
	v_and_b32_e32 v37, 0xffff0000, v37
	v_pk_mul_f32 v[40:41], v[40:41], v[16:17]
	v_cvt_pk_bf16_f32 v28, v28, v29
	v_pk_mul_f32 v[36:37], v[40:41], v[36:37]
	s_nop 0
	v_cvt_pk_bf16_f32 v29, v36, v37
	global_store_dwordx4 v[52:53], v[26:29], off offset:1536 sc1
	global_load_dwordx4 v[26:29], v[56:57], off offset:1536
	v_min_u32_e32 v36, v230, v221
	v_sub_u32_e64 v37, v224, 8 clamp
	v_sub_u32_e32 v36, v36, v37
	v_cvt_f32_i32_e32 v36, v36
	v_lshlrev_b32_e32 v52, 16, v13
	v_and_b32_e32 v53, 0xffff0000, v13
	v_pk_add_f32 v[52:53], v[52:53], v[136:137] neg_lo:[0,1] neg_hi:[0,1]
	v_div_scale_f32 v37, s[16:17], v36, v36, 1.0
	v_rcp_f32_e32 v40, v37
	v_pk_add_f32 v[4:5], v[4:5], v[52:53]
	v_lshlrev_b32_e32 v52, 16, v10
	v_and_b32_e32 v53, 0xffff0000, v10
	v_fma_f32 v41, -v37, v40, 1.0
	v_fmac_f32_e32 v40, v41, v40
	v_div_scale_f32 v41, vcc, 1.0, v36, 1.0
	v_mul_f32_e32 v50, v41, v40
	v_fma_f32 v51, -v37, v50, v41
	v_fmac_f32_e32 v50, v51, v40
	v_fma_f32 v37, -v37, v50, v41
	v_div_fmas_f32 v37, v37, v40, v50
	v_pk_add_f32 v[52:53], v[52:53], v[126:127] neg_lo:[0,1] neg_hi:[0,1]
	v_div_fixup_f32 v36, v37, v36, 1.0
	v_pk_add_f32 v[44:45], v[44:45], v[52:53]
	v_lshl_add_u64 v[40:41], v[112:113], 0, v[54:55]
	v_pk_fma_f32 v[52:53], v[36:37], v[44:45], v[128:129] op_sel_hi:[0,1,1] neg_lo:[0,0,1] neg_hi:[0,0,1]
	v_pk_mul_f32 v[52:53], v[52:53], v[18:19]
	v_lshlrev_b64 v[50:51], 11, v[114:115]
	v_lshl_add_u64 v[50:51], v[110:111], 0, v[50:51]
	s_waitcnt vmcnt(0)
	v_lshlrev_b32_e32 v54, 16, v26
	v_and_b32_e32 v55, 0xffff0000, v26
	v_pk_mul_f32 v[52:53], v[52:53], v[54:55]
	v_lshlrev_b32_e32 v26, 16, v27
	v_cvt_pk_bf16_f32 v10, v52, v53
	v_lshlrev_b32_e32 v52, 16, v11
	v_and_b32_e32 v53, 0xffff0000, v11
	v_pk_add_f32 v[52:53], v[52:53], v[58:59] neg_lo:[0,1] neg_hi:[0,1]
	v_and_b32_e32 v27, 0xffff0000, v27
	v_pk_add_f32 v[38:39], v[38:39], v[52:53]
	s_nop 0
	v_pk_fma_f32 v[46:47], v[36:37], v[38:39], v[46:47] op_sel_hi:[0,1,1] neg_lo:[0,0,1] neg_hi:[0,0,1]
	v_pk_mul_f32 v[46:47], v[46:47], v[20:21]
	s_nop 0
	v_pk_mul_f32 v[26:27], v[46:47], v[26:27]
	v_add_u32_e32 v46, 15, v222
	v_cvt_pk_bf16_f32 v11, v26, v27
	v_lshlrev_b32_e32 v26, 16, v12
	v_and_b32_e32 v27, 0xffff0000, v12
	v_pk_add_f32 v[12:13], v[26:27], v[62:63] neg_lo:[0,1] neg_hi:[0,1]
	v_lshlrev_b32_e32 v26, 16, v28
	v_pk_add_f32 v[34:35], v[34:35], v[12:13]
	v_and_b32_e32 v27, 0xffff0000, v28
	v_pk_fma_f32 v[12:13], v[36:37], v[34:35], v[64:65] op_sel_hi:[0,1,1] neg_lo:[0,0,1] neg_hi:[0,0,1]
	v_pk_mul_f32 v[12:13], v[12:13], v[14:15]
	v_sub_u32_e64 v47, v223, 8 clamp
	v_pk_mul_f32 v[12:13], v[12:13], v[26:27]
	v_lshlrev_b32_e32 v26, 16, v29
	v_and_b32_e32 v27, 0xffff0000, v29
	v_pk_fma_f32 v[28:29], v[36:37], v[4:5], v[48:49] op_sel_hi:[0,1,1] neg_lo:[0,0,1] neg_hi:[0,0,1]
	v_pk_mul_f32 v[28:29], v[28:29], v[16:17]
	v_cvt_pk_bf16_f32 v12, v12, v13
	v_pk_mul_f32 v[26:27], v[28:29], v[26:27]
	v_lshlrev_b32_e32 v28, 16, v9
	v_cvt_pk_bf16_f32 v13, v26, v27
	global_store_dwordx4 v[40:41], v[10:13], off offset:1536 sc1
	global_load_dwordx4 v[10:13], v[50:51], off offset:1536
	v_and_b32_e32 v29, 0xffff0000, v9
	v_min_u32_e32 v46, v46, v221
	v_lshlrev_b32_e32 v40, 16, v8
	v_and_b32_e32 v41, 0xffff0000, v8
	v_pk_add_f32 v[8:9], v[28:29], v[32:33] neg_lo:[0,1] neg_hi:[0,1]
	v_sub_u32_e32 v28, v46, v47
	v_cvt_f32_i32_e32 v32, v28
	v_lshlrev_b32_e32 v36, 16, v6
	v_and_b32_e32 v37, 0xffff0000, v6
	v_pk_add_f32 v[28:29], v[36:37], v[90:91] neg_lo:[0,1] neg_hi:[0,1]
	v_div_scale_f32 v33, s[16:17], v32, v32, 1.0
	v_rcp_f32_e32 v36, v33
	v_lshlrev_b32_e32 v6, 16, v7
	v_and_b32_e32 v7, 0xffff0000, v7
	v_pk_add_f32 v[2:3], v[6:7], v[2:3] neg_lo:[0,1] neg_hi:[0,1]
	v_pk_add_f32 v[6:7], v[40:41], v[30:31] neg_lo:[0,1] neg_hi:[0,1]
	v_fma_f32 v31, -v33, v36, 1.0
	v_div_scale_f32 v30, vcc, 1.0, v32, 1.0
	v_fmac_f32_e32 v36, v31, v36
	v_mul_f32_e32 v31, v30, v36
	v_fma_f32 v37, -v33, v31, v30
	v_fmac_f32_e32 v31, v37, v36
	v_fma_f32 v30, -v33, v31, v30
	v_pk_add_f32 v[8:9], v[4:5], v[8:9]
	v_pk_add_f32 v[4:5], v[44:45], v[28:29]
	v_div_fmas_f32 v28, v30, v36, v31
	v_pk_add_f32 v[2:3], v[38:39], v[2:3]
	v_div_fixup_f32 v28, v28, v32, 1.0
	v_pk_fma_f32 v[4:5], v[28:29], v[4:5], v[92:93] op_sel_hi:[0,1,1] neg_lo:[0,0,1] neg_hi:[0,0,1]
	v_pk_fma_f32 v[2:3], v[28:29], v[2:3], v[22:23] op_sel_hi:[0,1,1] neg_lo:[0,0,1] neg_hi:[0,0,1]
	v_pk_add_f32 v[6:7], v[34:35], v[6:7]
	v_pk_mul_f32 v[4:5], v[18:19], v[4:5]
	v_pk_mul_f32 v[2:3], v[20:21], v[2:3]
	v_pk_fma_f32 v[6:7], v[28:29], v[6:7], v[42:43] op_sel_hi:[0,1,1] neg_lo:[0,0,1] neg_hi:[0,0,1]
	v_lshlrev_b64 v[26:27], 10, v[114:115]
	s_waitcnt vmcnt(0)
	v_lshlrev_b32_e32 v20, 16, v10
	v_and_b32_e32 v21, 0xffff0000, v10
	v_lshlrev_b32_e32 v10, 16, v11
	v_and_b32_e32 v11, 0xffff0000, v11
	v_pk_mul_f32 v[4:5], v[4:5], v[20:21]
	v_pk_mul_f32 v[10:11], v[2:3], v[10:11]
	v_cvt_pk_bf16_f32 v2, v4, v5
	v_pk_mul_f32 v[4:5], v[14:15], v[6:7]
	v_lshlrev_b32_e32 v6, 16, v12
	v_and_b32_e32 v7, 0xffff0000, v12
	v_pk_mul_f32 v[4:5], v[4:5], v[6:7]
	v_pk_fma_f32 v[6:7], v[28:29], v[8:9], v[24:25] op_sel_hi:[0,1,1] neg_lo:[0,0,1] neg_hi:[0,0,1]
	v_lshlrev_b32_e32 v18, 16, v13
	v_and_b32_e32 v19, 0xffff0000, v13
	v_pk_mul_f32 v[6:7], v[16:17], v[6:7]
	v_cvt_pk_bf16_f32 v3, v10, v11
	v_cvt_pk_bf16_f32 v4, v4, v5
	v_pk_mul_f32 v[6:7], v[6:7], v[18:19]

.LBB0_387:
	s_or_b64 exec, exec, s[16:17]
	v_add_u32_e32 v62, v222, v94
	v_ashrrev_i32_e32 v63, 31, v62
	v_lshlrev_b64 v[136:137], 11, v[62:63]
	v_lshl_add_u64 v[62:63], v[110:111], 0, v[136:137]
	global_load_dwordx4 v[62:65], v[62:63], off offset:1024
	s_waitcnt vmcnt(0)
	v_lshlrev_b32_e32 v130, 16, v10
	v_and_b32_e32 v131, 0xffff0000, v10
	v_lshlrev_b32_e32 v128, 16, v11
	v_and_b32_e32 v129, 0xffff0000, v11
	v_lshlrev_b32_e32 v126, 16, v12
	v_and_b32_e32 v127, 0xffff0000, v12
	v_lshlrev_b32_e32 v132, 16, v13
	v_and_b32_e32 v133, 0xffff0000, v13
	global_load_dwordx4 v[10:13], v[102:103], off offset:2064
	v_lshlrev_b32_e32 v84, 16, v14
	v_and_b32_e32 v85, 0xffff0000, v14
	v_lshlrev_b32_e32 v88, 16, v15
	v_and_b32_e32 v89, 0xffff0000, v15
	v_lshlrev_b32_e32 v86, 16, v16
	v_and_b32_e32 v87, 0xffff0000, v16
	v_lshlrev_b32_e32 v90, 16, v17
	v_and_b32_e32 v91, 0xffff0000, v17
	global_load_dwordx4 v[14:17], v[102:103], off offset:2048
	v_lshlrev_b32_e32 v118, 16, v29
	v_and_b32_e32 v119, 0xffff0000, v29
	v_min_u32_e32 v29, v155, v221
	v_sub_u32_e64 v138, v222, 4 clamp
	v_sub_u32_e32 v29, v29, v138
	v_cvt_f32_i32_e32 v29, v29
	v_lshlrev_b32_e32 v116, 16, v50
	v_and_b32_e32 v117, 0xffff0000, v50
	v_lshlrev_b32_e32 v120, 16, v51
	v_and_b32_e32 v121, 0xffff0000, v51
	v_lshlrev_b32_e32 v50, 16, v44
	v_and_b32_e32 v51, 0xffff0000, v44
	v_div_scale_f32 v44, s[16:17], v29, v29, 1.0
	v_lshlrev_b32_e32 v94, 16, v58
	v_and_b32_e32 v95, 0xffff0000, v58
	v_lshlrev_b32_e32 v96, 16, v59
	v_and_b32_e32 v97, 0xffff0000, v59
	v_lshlrev_b32_e32 v92, 16, v60
	v_and_b32_e32 v93, 0xffff0000, v60
	v_lshlrev_b32_e32 v114, 16, v61
	v_and_b32_e32 v115, 0xffff0000, v61
	v_lshlrev_b32_e32 v60, 16, v42
	v_and_b32_e32 v61, 0xffff0000, v42
	v_lshlrev_b32_e32 v58, 16, v54
	v_and_b32_e32 v59, 0xffff0000, v54
	v_lshlrev_b32_e32 v74, 16, v43
	v_and_b32_e32 v75, 0xffff0000, v43
	v_lshlrev_b32_e32 v42, 16, v55
	v_and_b32_e32 v43, 0xffff0000, v55
	v_lshlrev_b32_e32 v54, 16, v48
	v_and_b32_e32 v55, 0xffff0000, v48
	v_rcp_f32_e32 v48, v44
	v_lshlrev_b32_e32 v78, 16, v46
	v_and_b32_e32 v79, 0xffff0000, v46
	v_lshlrev_b32_e32 v82, 16, v47
	v_and_b32_e32 v83, 0xffff0000, v47
	v_lshlrev_b32_e32 v46, 16, v56
	v_and_b32_e32 v47, 0xffff0000, v56
	v_fma_f32 v56, -v44, v48, 1.0
	v_lshlrev_b32_e32 v122, 16, v52
	v_and_b32_e32 v123, 0xffff0000, v52
	v_div_scale_f32 v52, vcc, 1.0, v29, 1.0
	v_fmac_f32_e32 v48, v56, v48
	v_pk_add_f32 v[164:165], v[132:133], 0 op_sel_hi:[1,0]
	v_mul_f32_e32 v56, v52, v48
	v_fma_f32 v138, -v44, v56, v52
	v_pk_add_f32 v[164:165], v[164:165], v[118:119]
	v_fmac_f32_e32 v56, v138, v48
	v_pk_add_f32 v[164:165], v[164:165], v[114:115]
	v_fma_f32 v44, -v44, v56, v52
	v_pk_add_f32 v[164:165], v[164:165], v[90:91]
	v_div_fmas_f32 v44, v44, v48, v56
	v_lshlrev_b32_e32 v48, 16, v45
	v_div_fixup_f32 v56, v44, v29, 1.0
	v_lshlrev_b32_e32 v44, 16, v57
	v_lshlrev_b32_e32 v52, 16, v53
	v_and_b32_e32 v53, 0xffff0000, v53
	v_pk_add_f32 v[162:163], v[126:127], 0 op_sel_hi:[1,0]
	v_pk_add_f32 v[142:143], v[128:129], 0 op_sel_hi:[1,0]
	v_lshlrev_b32_e32 v138, 16, v62
	v_and_b32_e32 v139, 0xffff0000, v62
	v_lshlrev_b32_e32 v144, 16, v63
	v_and_b32_e32 v145, 0xffff0000, v63
	v_lshlrev_b32_e32 v62, 16, v49
	v_and_b32_e32 v63, 0xffff0000, v49
	v_and_b32_e32 v49, 0xffff0000, v45
	v_pk_add_f32 v[164:165], v[164:165], v[62:63]
	v_and_b32_e32 v45, 0xffff0000, v57
	v_pk_add_f32 v[164:165], v[164:165], v[48:49]
	v_lshlrev_b32_e32 v166, 16, v64
	v_pk_add_f32 v[164:165], v[164:165], v[44:45]
	v_and_b32_e32 v167, 0xffff0000, v64
	v_pk_add_f32 v[164:165], v[164:165], v[52:53]
	v_lshlrev_b32_e32 v64, 16, v65
	v_pk_fma_f32 v[168:169], v[56:57], v[164:165], v[62:63] op_sel_hi:[0,1,1] neg_lo:[0,0,1] neg_hi:[0,0,1]
	v_and_b32_e32 v65, 0xffff0000, v65
	s_waitcnt vmcnt(1)
	v_pk_mul_f32 v[168:169], v[168:169], v[12:13]
	v_pk_add_f32 v[134:135], v[130:131], 0 op_sel_hi:[1,0]
	v_pk_mul_f32 v[64:65], v[168:169], v[64:65]
	v_lshlrev_b32_e32 v168, 16, v28
	v_and_b32_e32 v169, 0xffff0000, v28
	v_cvt_pk_bf16_f32 v29, v64, v65
	v_pk_add_f32 v[64:65], v[162:163], v[168:169]
	v_lshl_add_u64 v[136:137], v[112:113], 0, v[136:137]
	v_pk_add_f32 v[64:65], v[64:65], v[92:93]
	v_lshlrev_b64 v[124:125], 11, v[124:125]
	v_pk_add_f32 v[64:65], v[64:65], v[86:87]
	v_lshl_add_u64 v[140:141], v[110:111], 0, v[124:125]
	v_pk_add_f32 v[64:65], v[64:65], v[54:55]
	s_nop 0
	v_pk_add_f32 v[64:65], v[64:65], v[50:51]
	s_nop 0
	v_pk_add_f32 v[64:65], v[64:65], v[46:47]
	s_nop 0
	v_pk_add_f32 v[162:163], v[64:65], v[122:123]
	s_nop 0
	v_pk_fma_f32 v[64:65], v[56:57], v[162:163], v[54:55] op_sel_hi:[0,1,1] neg_lo:[0,0,1] neg_hi:[0,0,1]
	v_pk_mul_f32 v[64:65], v[64:65], v[10:11]
	s_nop 0
	v_pk_mul_f32 v[64:65], v[64:65], v[166:167]
	v_lshlrev_b32_e32 v166, 16, v27
	v_and_b32_e32 v167, 0xffff0000, v27
	v_cvt_pk_bf16_f32 v28, v64, v65
	v_pk_add_f32 v[64:65], v[142:143], v[166:167]
	s_nop 0
	v_pk_add_f32 v[64:65], v[64:65], v[96:97]
	s_nop 0
	v_pk_add_f32 v[64:65], v[64:65], v[88:89]
	s_nop 0
	v_pk_add_f32 v[64:65], v[64:65], v[82:83]
	s_nop 0
	v_pk_add_f32 v[64:65], v[64:65], v[74:75]
	s_nop 0
	v_pk_add_f32 v[64:65], v[64:65], v[42:43]
	s_nop 0
	v_pk_add_f32 v[142:143], v[64:65], v[120:121]
	s_nop 0
	v_pk_fma_f32 v[64:65], v[56:57], v[142:143], v[82:83] op_sel_hi:[0,1,1] neg_lo:[0,0,1] neg_hi:[0,0,1]
	s_waitcnt vmcnt(0)
	v_pk_mul_f32 v[64:65], v[64:65], v[16:17]
	s_nop 0
	v_pk_mul_f32 v[64:65], v[64:65], v[144:145]
	v_lshlrev_b32_e32 v144, 16, v26
	v_and_b32_e32 v145, 0xffff0000, v26
	v_cvt_pk_bf16_f32 v27, v64, v65
	v_pk_add_f32 v[64:65], v[134:135], v[144:145]
	s_nop 0
	v_pk_add_f32 v[64:65], v[64:65], v[94:95]
	s_nop 0
	v_pk_add_f32 v[64:65], v[64:65], v[84:85]
	s_nop 0
	v_pk_add_f32 v[64:65], v[64:65], v[78:79]
	s_nop 0
	v_pk_add_f32 v[64:65], v[64:65], v[60:61]
	s_nop 0
	v_pk_add_f32 v[64:65], v[64:65], v[58:59]
	s_nop 0
	v_pk_add_f32 v[134:135], v[64:65], v[116:117]
	v_lshlrev_b32_e32 v64, 16, v41
	v_pk_fma_f32 v[56:57], v[56:57], v[134:135], v[78:79] op_sel_hi:[0,1,1] neg_lo:[0,0,1] neg_hi:[0,0,1]
	v_pk_mul_f32 v[56:57], v[56:57], v[14:15]
	v_and_b32_e32 v65, 0xffff0000, v41
	v_pk_mul_f32 v[56:57], v[56:57], v[138:139]
	s_nop 0
	v_cvt_pk_bf16_f32 v26, v56, v57
	global_store_dwordx4 v[136:137], v[26:29], off offset:1024 sc1
	global_load_dwordx4 v[26:29], v[140:141], off offset:1024
	v_min_u32_e32 v56, v154, v221
	v_sub_u32_e64 v57, v161, 4 clamp
	v_sub_u32_e32 v56, v56, v57
	v_cvt_f32_i32_e32 v136, v56
	v_pk_add_f32 v[56:57], v[64:65], v[132:133] neg_lo:[0,1] neg_hi:[0,1]
	v_div_scale_f32 v137, s[16:17], v136, v136, 1.0
	v_rcp_f32_e32 v138, v137
	v_pk_add_f32 v[56:57], v[164:165], v[56:57]
	v_fma_f32 v41, -v137, v138, 1.0
	v_fmac_f32_e32 v138, v41, v138
	v_div_scale_f32 v41, vcc, 1.0, v136, 1.0
	v_mul_f32_e32 v132, v41, v138
	v_fma_f32 v133, -v137, v132, v41
	v_fmac_f32_e32 v132, v133, v138
	v_fma_f32 v41, -v137, v132, v41
	v_div_fmas_f32 v41, v41, v138, v132
	v_div_fixup_f32 v132, v41, v136, 1.0
	v_lshl_add_u64 v[136:137], v[112:113], 0, v[124:125]
	v_lshlrev_b64 v[138:139], 11, v[80:81]
	v_lshlrev_b32_e32 v80, 16, v38
	v_and_b32_e32 v81, 0xffff0000, v38
	v_lshlrev_b32_e32 v124, 16, v39
	v_and_b32_e32 v125, 0xffff0000, v39
	v_pk_add_f32 v[130:131], v[80:81], v[130:131] neg_lo:[0,1] neg_hi:[0,1]
	v_pk_add_f32 v[38:39], v[124:125], v[128:129] neg_lo:[0,1] neg_hi:[0,1]
	v_lshlrev_b32_e32 v128, 16, v40
	v_and_b32_e32 v129, 0xffff0000, v40
	v_pk_add_f32 v[40:41], v[128:129], v[126:127] neg_lo:[0,1] neg_hi:[0,1]
	v_pk_add_f32 v[134:135], v[134:135], v[130:131]
	v_pk_add_f32 v[162:163], v[162:163], v[40:41]
	v_pk_add_f32 v[142:143], v[142:143], v[38:39]
	v_pk_fma_f32 v[130:131], v[132:133], v[134:135], v[60:61] op_sel_hi:[0,1,1] neg_lo:[0,0,1] neg_hi:[0,0,1]
	v_pk_fma_f32 v[126:127], v[132:133], v[56:57], v[48:49] op_sel_hi:[0,1,1] neg_lo:[0,0,1] neg_hi:[0,0,1]
	v_pk_fma_f32 v[40:41], v[132:133], v[162:163], v[50:51] op_sel_hi:[0,1,1] neg_lo:[0,0,1] neg_hi:[0,0,1]
	v_pk_fma_f32 v[38:39], v[132:133], v[142:143], v[74:75] op_sel_hi:[0,1,1] neg_lo:[0,0,1] neg_hi:[0,0,1]
	v_pk_mul_f32 v[130:131], v[130:131], v[14:15]
	v_pk_mul_f32 v[38:39], v[38:39], v[16:17]
	v_pk_mul_f32 v[40:41], v[40:41], v[10:11]
	v_pk_mul_f32 v[126:127], v[126:127], v[12:13]
	v_lshl_add_u64 v[140:141], v[110:111], 0, v[138:139]
	s_waitcnt vmcnt(0)
	v_lshlrev_b32_e32 v132, 16, v26
	v_and_b32_e32 v133, 0xffff0000, v26
	v_pk_mul_f32 v[130:131], v[130:131], v[132:133]
	s_nop 0
	v_cvt_pk_bf16_f32 v26, v130, v131
	v_lshlrev_b32_e32 v130, 16, v27
	v_and_b32_e32 v131, 0xffff0000, v27
	v_pk_mul_f32 v[38:39], v[38:39], v[130:131]
	s_nop 0
	v_cvt_pk_bf16_f32 v27, v38, v39
	v_lshlrev_b32_e32 v38, 16, v28
	v_and_b32_e32 v39, 0xffff0000, v28
	v_pk_mul_f32 v[38:39], v[40:41], v[38:39]
	v_lshlrev_b32_e32 v40, 16, v30
	v_cvt_pk_bf16_f32 v28, v38, v39
	v_lshlrev_b32_e32 v38, 16, v29
	v_and_b32_e32 v39, 0xffff0000, v29
	v_pk_mul_f32 v[38:39], v[126:127], v[38:39]
	v_and_b32_e32 v41, 0xffff0000, v30
	v_cvt_pk_bf16_f32 v29, v38, v39
	global_store_dwordx4 v[136:137], v[26:29], off offset:1024 sc1
	global_load_dwordx4 v[130:133], v[140:141], off offset:1024
	v_pk_add_f32 v[126:127], v[40:41], v[144:145] neg_lo:[0,1] neg_hi:[0,1]
	v_min_u32_e32 v28, v153, v221
	v_sub_u32_e64 v29, v160, 4 clamp
	v_sub_u32_e32 v30, v28, v29
	v_lshlrev_b32_e32 v26, 16, v32
	v_and_b32_e32 v27, 0xffff0000, v32
	v_cvt_f32_i32_e32 v32, v30
	v_pk_add_f32 v[28:29], v[26:27], v[168:169] neg_lo:[0,1] neg_hi:[0,1]
	v_pk_add_f32 v[134:135], v[134:135], v[126:127]
	v_pk_add_f32 v[140:141], v[162:163], v[28:29]
	v_div_scale_f32 v144, s[16:17], v32, v32, 1.0
	v_rcp_f32_e32 v160, v144
	v_div_scale_f32 v145, vcc, 1.0, v32, 1.0
	v_lshlrev_b32_e32 v38, 16, v31
	v_fma_f32 v28, -v144, v160, 1.0
	v_fmac_f32_e32 v160, v28, v160
	v_mul_f32_e32 v28, v145, v160
	v_fma_f32 v29, -v144, v28, v145
	v_fmac_f32_e32 v28, v29, v160
	v_fma_f32 v29, -v144, v28, v145
	v_div_fmas_f32 v28, v29, v160, v28
	v_div_fixup_f32 v32, v28, v32, 1.0
	v_pk_fma_f32 v[28:29], v[32:33], v[140:141], v[46:47] op_sel_hi:[0,1,1] neg_lo:[0,0,1] neg_hi:[0,0,1]
	v_pk_fma_f32 v[126:127], v[32:33], v[134:135], v[58:59] op_sel_hi:[0,1,1] neg_lo:[0,0,1] neg_hi:[0,0,1]
	v_and_b32_e32 v39, 0xffff0000, v31
	v_pk_mul_f32 v[144:145], v[28:29], v[10:11]
	v_pk_mul_f32 v[28:29], v[126:127], v[14:15]
	v_pk_add_f32 v[30:31], v[38:39], v[166:167] neg_lo:[0,1] neg_hi:[0,1]
	v_lshlrev_b64 v[136:137], 11, v[76:77]
	v_pk_add_f32 v[142:143], v[142:143], v[30:31]
	v_lshl_add_u64 v[76:77], v[112:113], 0, v[138:139]
	v_pk_fma_f32 v[30:31], v[32:33], v[142:143], v[42:43] op_sel_hi:[0,1,1] neg_lo:[0,0,1] neg_hi:[0,0,1]
	v_pk_mul_f32 v[30:31], v[30:31], v[16:17]
	v_lshl_add_u64 v[138:139], v[110:111], 0, v[136:137]
	s_waitcnt vmcnt(0)
	v_lshlrev_b32_e32 v126, 16, v130
	v_and_b32_e32 v127, 0xffff0000, v130
	v_pk_mul_f32 v[28:29], v[28:29], v[126:127]
	v_lshlrev_b32_e32 v126, 16, v33
	v_and_b32_e32 v127, 0xffff0000, v33
	v_pk_add_f32 v[118:119], v[126:127], v[118:119] neg_lo:[0,1] neg_hi:[0,1]
	v_lshlrev_b32_e32 v130, 16, v131
	v_pk_add_f32 v[118:119], v[56:57], v[118:119]
	v_and_b32_e32 v131, 0xffff0000, v131
	v_pk_fma_f32 v[32:33], v[32:33], v[118:119], v[44:45] op_sel_hi:[0,1,1] neg_lo:[0,0,1] neg_hi:[0,0,1]
	v_lshlrev_b32_e32 v160, 16, v132
	v_and_b32_e32 v161, 0xffff0000, v132
	v_pk_mul_f32 v[30:31], v[30:31], v[130:131]
	v_lshlrev_b32_e32 v130, 16, v133
	v_and_b32_e32 v131, 0xffff0000, v133
	v_pk_mul_f32 v[32:33], v[32:33], v[12:13]
	v_cvt_pk_bf16_f32 v28, v28, v29
	v_cvt_pk_bf16_f32 v29, v30, v31
	v_pk_mul_f32 v[30:31], v[144:145], v[160:161]
	v_pk_mul_f32 v[32:33], v[32:33], v[130:131]
	v_cvt_pk_bf16_f32 v30, v30, v31
	v_cvt_pk_bf16_f32 v31, v32, v33
	global_store_dwordx4 v[76:77], v[28:31], off offset:1024 sc1
	global_load_dwordx4 v[28:31], v[138:139], off offset:1024
	v_min_u32_e32 v32, v152, v221
	v_sub_u32_e64 v33, v157, 4 clamp
	v_sub_u32_e32 v132, v32, v33
	v_lshl_add_u64 v[32:33], v[112:113], 0, v[136:137]
	v_cvt_f32_i32_e32 v136, v132
	v_lshlrev_b64 v[130:131], 11, v[72:73]
	v_lshlrev_b32_e32 v72, 16, v34
	v_and_b32_e32 v73, 0xffff0000, v34
	v_div_scale_f32 v137, s[16:17], v136, v136, 1.0
	v_rcp_f32_e32 v138, v137
	v_lshlrev_b32_e32 v76, 16, v36
	v_and_b32_e32 v77, 0xffff0000, v36
	v_pk_add_f32 v[94:95], v[72:73], v[94:95] neg_lo:[0,1] neg_hi:[0,1]
	v_fma_f32 v144, -v137, v138, 1.0
	v_pk_add_f32 v[92:93], v[76:77], v[92:93] neg_lo:[0,1] neg_hi:[0,1]
	v_div_scale_f32 v139, vcc, 1.0, v136, 1.0
	v_fmac_f32_e32 v138, v144, v138
	v_pk_add_f32 v[132:133], v[134:135], v[94:95]
	v_pk_add_f32 v[134:135], v[140:141], v[92:93]
	v_mul_f32_e32 v92, v139, v138
	v_fma_f32 v93, -v137, v92, v139
	v_fmac_f32_e32 v92, v93, v138
	v_lshlrev_b32_e32 v56, 16, v37
	v_and_b32_e32 v57, 0xffff0000, v37
	v_lshlrev_b32_e32 v34, 16, v35
	v_and_b32_e32 v35, 0xffff0000, v35
	v_fma_f32 v93, -v137, v92, v139
	v_pk_add_f32 v[114:115], v[56:57], v[114:115] neg_lo:[0,1] neg_hi:[0,1]
	v_pk_add_f32 v[96:97], v[34:35], v[96:97] neg_lo:[0,1] neg_hi:[0,1]
	v_div_fmas_f32 v92, v93, v138, v92
	v_pk_add_f32 v[96:97], v[142:143], v[96:97]
	v_pk_add_f32 v[114:115], v[118:119], v[114:115]
	v_div_fixup_f32 v92, v92, v136, 1.0
	v_pk_fma_f32 v[94:95], v[92:93], v[132:133], v[116:117] op_sel_hi:[0,1,1] neg_lo:[0,0,1] neg_hi:[0,0,1]
	v_pk_fma_f32 v[116:117], v[92:93], v[96:97], v[120:121] op_sel_hi:[0,1,1] neg_lo:[0,0,1] neg_hi:[0,0,1]
	v_pk_fma_f32 v[118:119], v[92:93], v[134:135], v[122:123] op_sel_hi:[0,1,1] neg_lo:[0,0,1] neg_hi:[0,0,1]
	v_pk_fma_f32 v[52:53], v[92:93], v[114:115], v[52:53] op_sel_hi:[0,1,1] neg_lo:[0,0,1] neg_hi:[0,0,1]
	v_pk_mul_f32 v[92:93], v[94:95], v[14:15]
	v_pk_mul_f32 v[94:95], v[116:117], v[16:17]
	v_pk_mul_f32 v[116:117], v[118:119], v[10:11]
	v_pk_mul_f32 v[52:53], v[52:53], v[12:13]
	v_lshl_add_u64 v[36:37], v[110:111], 0, v[130:131]
	s_waitcnt vmcnt(0)
	v_lshlrev_b32_e32 v118, 16, v28
	v_and_b32_e32 v119, 0xffff0000, v28
	v_lshlrev_b32_e32 v28, 16, v29
	v_and_b32_e32 v29, 0xffff0000, v29
	v_lshlrev_b32_e32 v120, 16, v30
	v_and_b32_e32 v121, 0xffff0000, v30
	v_lshlrev_b32_e32 v30, 16, v31
	v_and_b32_e32 v31, 0xffff0000, v31
	v_pk_mul_f32 v[92:93], v[92:93], v[118:119]
	v_pk_mul_f32 v[94:95], v[94:95], v[28:29]
	v_pk_mul_f32 v[116:117], v[116:117], v[120:121]
	v_pk_mul_f32 v[52:53], v[52:53], v[30:31]
	v_cvt_pk_bf16_f32 v28, v92, v93
	v_cvt_pk_bf16_f32 v29, v94, v95
	v_cvt_pk_bf16_f32 v30, v116, v117
	v_cvt_pk_bf16_f32 v31, v52, v53
	global_store_dwordx4 v[32:33], v[28:31], off offset:1024 sc1
	global_load_dwordx4 v[92:95], v[36:37], off offset:1024
	v_lshlrev_b64 v[36:37], 11, v[70:71]
	v_lshlrev_b32_e32 v28, 16, v25
	v_and_b32_e32 v29, 0xffff0000, v25
	v_min_u32_e32 v25, v159, v221
	v_sub_u32_e32 v116, v25, v155
	v_pk_add_f32 v[70:71], v[28:29], v[90:91] neg_lo:[0,1] neg_hi:[0,1]
	v_add_u32_e32 v90, 4, v116
	v_cvt_f32_i32_e32 v116, v90
	v_lshlrev_b32_e32 v30, 16, v22
	v_and_b32_e32 v31, 0xffff0000, v22
	v_pk_add_f32 v[84:85], v[30:31], v[84:85] neg_lo:[0,1] neg_hi:[0,1]
	v_div_scale_f32 v117, s[16:17], v116, v116, 1.0
	v_rcp_f32_e32 v118, v117
	v_div_scale_f32 v119, vcc, 1.0, v116, 1.0
	v_pk_add_f32 v[90:91], v[132:133], v[84:85]
	v_fma_f32 v120, -v117, v118, 1.0
	v_fmac_f32_e32 v118, v120, v118
	v_mul_f32_e32 v84, v119, v118
	v_fma_f32 v85, -v117, v84, v119
	v_fmac_f32_e32 v84, v85, v118
	v_lshlrev_b32_e32 v22, 16, v23
	v_and_b32_e32 v23, 0xffff0000, v23
	v_lshlrev_b32_e32 v32, 16, v24
	v_and_b32_e32 v33, 0xffff0000, v24
	v_fma_f32 v85, -v117, v84, v119
	v_pk_add_f32 v[88:89], v[22:23], v[88:89] neg_lo:[0,1] neg_hi:[0,1]
	v_pk_add_f32 v[86:87], v[32:33], v[86:87] neg_lo:[0,1] neg_hi:[0,1]
	v_div_fmas_f32 v84, v85, v118, v84
	v_pk_add_f32 v[88:89], v[96:97], v[88:89]
	v_pk_add_f32 v[96:97], v[134:135], v[86:87]
	v_pk_add_f32 v[70:71], v[114:115], v[70:71]
	v_div_fixup_f32 v84, v84, v116, 1.0
	v_pk_fma_f32 v[80:81], v[84:85], v[90:91], v[80:81] op_sel_hi:[0,1,1] neg_lo:[0,0,1] neg_hi:[0,0,1]
	v_pk_fma_f32 v[86:87], v[84:85], v[88:89], v[124:125] op_sel_hi:[0,1,1] neg_lo:[0,0,1] neg_hi:[0,0,1]
	v_pk_fma_f32 v[114:115], v[84:85], v[96:97], v[128:129] op_sel_hi:[0,1,1] neg_lo:[0,0,1] neg_hi:[0,0,1]
	v_pk_fma_f32 v[64:65], v[84:85], v[70:71], v[64:65] op_sel_hi:[0,1,1] neg_lo:[0,0,1] neg_hi:[0,0,1]
	v_pk_mul_f32 v[80:81], v[80:81], v[14:15]
	v_pk_mul_f32 v[84:85], v[86:87], v[16:17]
	v_pk_mul_f32 v[86:87], v[114:115], v[10:11]
	v_pk_mul_f32 v[64:65], v[64:65], v[12:13]
	v_lshl_add_u64 v[24:25], v[112:113], 0, v[130:131]
	v_lshl_add_u64 v[52:53], v[110:111], 0, v[36:37]
	v_lshl_add_u64 v[36:37], v[112:113], 0, v[36:37]
	s_waitcnt vmcnt(0)
	v_lshlrev_b32_e32 v114, 16, v92
	v_and_b32_e32 v115, 0xffff0000, v92
	v_lshlrev_b32_e32 v92, 16, v93
	v_and_b32_e32 v93, 0xffff0000, v93
	v_lshlrev_b32_e32 v116, 16, v94
	v_and_b32_e32 v117, 0xffff0000, v94
	v_lshlrev_b32_e32 v94, 16, v95
	v_and_b32_e32 v95, 0xffff0000, v95
	v_pk_mul_f32 v[80:81], v[80:81], v[114:115]
	v_pk_mul_f32 v[92:93], v[84:85], v[92:93]
	v_pk_mul_f32 v[86:87], v[86:87], v[116:117]
	v_pk_mul_f32 v[64:65], v[64:65], v[94:95]
	v_cvt_pk_bf16_f32 v84, v80, v81
	v_cvt_pk_bf16_f32 v85, v92, v93
	v_cvt_pk_bf16_f32 v86, v86, v87
	v_cvt_pk_bf16_f32 v87, v64, v65
	global_store_dwordx4 v[24:25], v[84:87], off offset:1024 sc1
	global_load_dwordx4 v[84:87], v[52:53], off offset:1024
	v_min_u32_e32 v80, v158, v221
	v_lshlrev_b32_e32 v52, 16, v21
	v_and_b32_e32 v53, 0xffff0000, v21
	v_sub_u32_e32 v92, v80, v154
	v_lshlrev_b64 v[24:25], 11, v[68:69]
	v_lshlrev_b32_e32 v68, 16, v20
	v_and_b32_e32 v69, 0xffff0000, v20
	v_pk_add_f32 v[20:21], v[52:53], v[62:63] neg_lo:[0,1] neg_hi:[0,1]
	v_add_u32_e32 v52, 4, v92
	v_cvt_f32_i32_e32 v92, v52
	v_lshlrev_b32_e32 v64, 16, v18
	v_and_b32_e32 v65, 0xffff0000, v18
	v_pk_add_f32 v[52:53], v[64:65], v[78:79] neg_lo:[0,1] neg_hi:[0,1]
	v_div_scale_f32 v78, s[16:17], v92, v92, 1.0
	v_rcp_f32_e32 v79, v78
	v_lshlrev_b32_e32 v18, 16, v19
	v_and_b32_e32 v19, 0xffff0000, v19
	v_pk_add_f32 v[18:19], v[18:19], v[82:83] neg_lo:[0,1] neg_hi:[0,1]
	v_fma_f32 v62, -v78, v79, 1.0
	v_pk_add_f32 v[54:55], v[68:69], v[54:55] neg_lo:[0,1] neg_hi:[0,1]
	v_div_scale_f32 v68, vcc, 1.0, v92, 1.0
	v_fmac_f32_e32 v79, v62, v79
	v_pk_add_f32 v[64:65], v[88:89], v[18:19]
	v_mul_f32_e32 v18, v68, v79
	v_fma_f32 v19, -v78, v18, v68
	v_fmac_f32_e32 v18, v19, v79
	v_fma_f32 v19, -v78, v18, v68
	v_div_fmas_f32 v18, v19, v79, v18
	v_pk_add_f32 v[62:63], v[70:71], v[20:21]
	v_pk_add_f32 v[52:53], v[90:91], v[52:53]
	v_pk_add_f32 v[54:55], v[96:97], v[54:55]
	v_div_fixup_f32 v18, v18, v92, 1.0
	v_pk_fma_f32 v[20:21], v[18:19], v[52:53], v[40:41] op_sel_hi:[0,1,1] neg_lo:[0,0,1] neg_hi:[0,0,1]
	v_pk_fma_f32 v[38:39], v[18:19], v[64:65], v[38:39] op_sel_hi:[0,1,1] neg_lo:[0,0,1] neg_hi:[0,0,1]
	v_pk_fma_f32 v[26:27], v[18:19], v[54:55], v[26:27] op_sel_hi:[0,1,1] neg_lo:[0,0,1] neg_hi:[0,0,1]
	v_pk_fma_f32 v[18:19], v[18:19], v[62:63], v[126:127] op_sel_hi:[0,1,1] neg_lo:[0,0,1] neg_hi:[0,0,1]
	v_pk_mul_f32 v[20:21], v[20:21], v[14:15]
	v_pk_mul_f32 v[38:39], v[38:39], v[16:17]
	v_pk_mul_f32 v[26:27], v[26:27], v[10:11]
	v_pk_mul_f32 v[18:19], v[18:19], v[12:13]
	v_lshl_add_u64 v[80:81], v[110:111], 0, v[24:25]
	v_lshl_add_u64 v[24:25], v[112:113], 0, v[24:25]
	s_waitcnt vmcnt(0)
	v_lshlrev_b32_e32 v40, 16, v87
	v_and_b32_e32 v41, 0xffff0000, v87
	v_lshlrev_b32_e32 v68, 16, v84
	v_and_b32_e32 v69, 0xffff0000, v84
	v_lshlrev_b32_e32 v70, 16, v85
	v_and_b32_e32 v71, 0xffff0000, v85
	v_lshlrev_b32_e32 v78, 16, v86
	v_and_b32_e32 v79, 0xffff0000, v86
	v_pk_mul_f32 v[20:21], v[20:21], v[68:69]
	v_pk_mul_f32 v[38:39], v[38:39], v[70:71]
	v_pk_mul_f32 v[26:27], v[26:27], v[78:79]
	v_pk_mul_f32 v[40:41], v[18:19], v[40:41]
	v_cvt_pk_bf16_f32 v18, v20, v21
	v_cvt_pk_bf16_f32 v19, v38, v39
	v_cvt_pk_bf16_f32 v20, v26, v27
	v_cvt_pk_bf16_f32 v21, v40, v41
	global_store_dwordx4 v[36:37], v[18:21], off offset:1024 sc1
	global_load_dwordx4 v[18:21], v[80:81], off offset:1024
	v_min_u32_e32 v68, v156, v221
	v_lshlrev_b32_e32 v36, 16, v9
	v_and_b32_e32 v37, 0xffff0000, v9
	v_sub_u32_e32 v68, v68, v153
	v_lshlrev_b32_e32 v40, 16, v8
	v_and_b32_e32 v41, 0xffff0000, v8
	v_pk_add_f32 v[8:9], v[36:37], v[48:49] neg_lo:[0,1] neg_hi:[0,1]
	v_add_u32_e32 v36, 4, v68
	v_cvt_f32_i32_e32 v68, v36
	v_lshlrev_b32_e32 v38, 16, v6
	v_and_b32_e32 v39, 0xffff0000, v6
	v_pk_add_f32 v[36:37], v[38:39], v[60:61] neg_lo:[0,1] neg_hi:[0,1]
	v_div_scale_f32 v60, s[16:17], v68, v68, 1.0
	v_rcp_f32_e32 v61, v60
	v_pk_add_f32 v[38:39], v[40:41], v[50:51] neg_lo:[0,1] neg_hi:[0,1]
	v_lshlrev_b32_e32 v6, 16, v7
	v_and_b32_e32 v7, 0xffff0000, v7
	v_fma_f32 v40, -v60, v61, 1.0
	v_div_scale_f32 v50, vcc, 1.0, v68, 1.0
	v_fmac_f32_e32 v61, v40, v61
	v_pk_add_f32 v[6:7], v[6:7], v[74:75] neg_lo:[0,1] neg_hi:[0,1]
	v_mul_f32_e32 v51, v50, v61
	v_pk_add_f32 v[48:49], v[64:65], v[6:7]
	v_fma_f32 v6, -v60, v51, v50
	v_fmac_f32_e32 v51, v6, v61
	v_fma_f32 v6, -v60, v51, v50
	v_div_fmas_f32 v6, v6, v61, v51
	v_pk_add_f32 v[40:41], v[62:63], v[8:9]
	v_pk_add_f32 v[36:37], v[52:53], v[36:37]
	v_pk_add_f32 v[38:39], v[54:55], v[38:39]
	v_div_fixup_f32 v6, v6, v68, 1.0
	v_pk_fma_f32 v[8:9], v[6:7], v[36:37], v[72:73] op_sel_hi:[0,1,1] neg_lo:[0,0,1] neg_hi:[0,0,1]
	v_pk_fma_f32 v[34:35], v[6:7], v[48:49], v[34:35] op_sel_hi:[0,1,1] neg_lo:[0,0,1] neg_hi:[0,0,1]
	v_pk_fma_f32 v[50:51], v[6:7], v[38:39], v[76:77] op_sel_hi:[0,1,1] neg_lo:[0,0,1] neg_hi:[0,0,1]
	v_pk_fma_f32 v[6:7], v[6:7], v[40:41], v[56:57] op_sel_hi:[0,1,1] neg_lo:[0,0,1] neg_hi:[0,0,1]
	v_pk_mul_f32 v[8:9], v[8:9], v[14:15]
	v_pk_mul_f32 v[34:35], v[34:35], v[16:17]
	v_pk_mul_f32 v[50:51], v[50:51], v[10:11]
	v_pk_mul_f32 v[6:7], v[6:7], v[12:13]
	v_lshlrev_b64 v[26:27], 11, v[66:67]
	v_lshl_add_u64 v[26:27], v[110:111], 0, v[26:27]
	s_waitcnt vmcnt(0)
	v_lshlrev_b32_e32 v52, 16, v18
	v_and_b32_e32 v53, 0xffff0000, v18
	v_lshlrev_b32_e32 v18, 16, v19
	v_and_b32_e32 v19, 0xffff0000, v19
	v_lshlrev_b32_e32 v54, 16, v20
	v_and_b32_e32 v55, 0xffff0000, v20
	v_lshlrev_b32_e32 v20, 16, v21
	v_and_b32_e32 v21, 0xffff0000, v21
	v_pk_mul_f32 v[8:9], v[8:9], v[52:53]
	v_pk_mul_f32 v[18:19], v[34:35], v[18:19]
	v_pk_mul_f32 v[34:35], v[50:51], v[54:55]
	v_pk_mul_f32 v[20:21], v[6:7], v[20:21]
	v_cvt_pk_bf16_f32 v6, v8, v9
	v_cvt_pk_bf16_f32 v7, v18, v19
	v_cvt_pk_bf16_f32 v8, v34, v35
	v_cvt_pk_bf16_f32 v9, v20, v21
	global_store_dwordx4 v[24:25], v[6:9], off offset:1024 sc1
	global_load_dwordx4 v[6:9], v[26:27], off offset:1024
	v_add_u32_e32 v34, 11, v222
	v_lshlrev_b32_e32 v18, 16, v5
	v_and_b32_e32 v19, 0xffff0000, v5
	v_min_u32_e32 v34, v34, v221
	v_lshlrev_b32_e32 v24, 16, v4
	v_and_b32_e32 v25, 0xffff0000, v4
	v_pk_add_f32 v[4:5], v[18:19], v[44:45] neg_lo:[0,1] neg_hi:[0,1]
	v_sub_u32_e32 v18, v34, v152
	v_add_u32_e32 v18, 4, v18
	v_cvt_f32_i32_e32 v34, v18
	v_lshlrev_b32_e32 v20, 16, v2
	v_and_b32_e32 v21, 0xffff0000, v2
	v_lshlrev_b32_e32 v2, 16, v3
	v_and_b32_e32 v3, 0xffff0000, v3
	v_div_scale_f32 v35, s[16:17], v34, v34, 1.0
	v_pk_add_f32 v[2:3], v[2:3], v[42:43] neg_lo:[0,1] neg_hi:[0,1]
	v_rcp_f32_e32 v42, v35
	v_pk_add_f32 v[18:19], v[20:21], v[58:59] neg_lo:[0,1] neg_hi:[0,1]
	v_pk_add_f32 v[20:21], v[24:25], v[46:47] neg_lo:[0,1] neg_hi:[0,1]
	v_div_scale_f32 v24, vcc, 1.0, v34, 1.0
	v_fma_f32 v25, -v35, v42, 1.0
	v_fmac_f32_e32 v42, v25, v42
	v_mul_f32_e32 v25, v24, v42
	v_pk_add_f32 v[18:19], v[36:37], v[18:19]
	v_fma_f32 v36, -v35, v25, v24
	v_fmac_f32_e32 v25, v36, v42
	v_fma_f32 v24, -v35, v25, v24
	v_div_fmas_f32 v24, v24, v42, v25
	v_pk_add_f32 v[2:3], v[48:49], v[2:3]
	v_pk_add_f32 v[20:21], v[38:39], v[20:21]
	v_div_fixup_f32 v24, v24, v34, 1.0
	v_pk_add_f32 v[4:5], v[40:41], v[4:5]
	v_pk_fma_f32 v[18:19], v[24:25], v[18:19], v[30:31] op_sel_hi:[0,1,1] neg_lo:[0,0,1] neg_hi:[0,0,1]
	v_pk_fma_f32 v[2:3], v[24:25], v[2:3], v[22:23] op_sel_hi:[0,1,1] neg_lo:[0,0,1] neg_hi:[0,0,1]
	v_pk_fma_f32 v[20:21], v[24:25], v[20:21], v[32:33] op_sel_hi:[0,1,1] neg_lo:[0,0,1] neg_hi:[0,0,1]
	v_pk_fma_f32 v[4:5], v[24:25], v[4:5], v[28:29] op_sel_hi:[0,1,1] neg_lo:[0,0,1] neg_hi:[0,0,1]
	v_pk_mul_f32 v[14:15], v[14:15], v[18:19]
	v_pk_mul_f32 v[2:3], v[16:17], v[2:3]
	v_pk_mul_f32 v[10:11], v[10:11], v[20:21]
	v_pk_mul_f32 v[4:5], v[12:13], v[4:5]
	v_lshlrev_b64 v[26:27], 10, v[66:67]
	s_waitcnt vmcnt(0)
	v_lshlrev_b32_e32 v16, 16, v6
	v_and_b32_e32 v17, 0xffff0000, v6
	v_lshlrev_b32_e32 v6, 16, v7
	v_and_b32_e32 v7, 0xffff0000, v7
	v_lshlrev_b32_e32 v18, 16, v8
	v_and_b32_e32 v19, 0xffff0000, v8
	v_lshlrev_b32_e32 v12, 16, v9
	v_and_b32_e32 v13, 0xffff0000, v9
	v_pk_mul_f32 v[8:9], v[14:15], v[16:17]
	v_pk_mul_f32 v[14:15], v[2:3], v[6:7]
	v_pk_mul_f32 v[10:11], v[10:11], v[18:19]
	v_pk_mul_f32 v[6:7], v[4:5], v[12:13]
	v_cvt_pk_bf16_f32 v2, v8, v9
	v_cvt_pk_bf16_f32 v3, v14, v15
	v_cvt_pk_bf16_f32 v4, v10, v11
	v_mov_b64_e32 v[8:9], v[104:105]

.LBB0_409:
	s_or_b64 exec, exec, s[16:17]
	v_add_u32_e32 v46, v222, v94
	v_ashrrev_i32_e32 v47, 31, v46
	v_lshlrev_b64 v[82:83], 11, v[46:47]
	v_lshl_add_u64 v[46:47], v[110:111], 0, v[82:83]
	global_load_dwordx4 v[6:9], v[102:103], off offset:16
	global_load_dwordx4 v[10:13], v[102:103], off
	v_min_u32_e32 v81, v80, v221
	global_load_dwordx4 v[46:49], v[46:47], off
	v_sub_u32_e64 v86, v222, 1 clamp
	v_sub_u32_e32 v81, v81, v86
	v_cvt_f32_i32_e32 v81, v81
	s_waitcnt vmcnt(0)
	v_lshlrev_b32_e32 v68, 16, v42
	v_and_b32_e32 v69, 0xffff0000, v42
	v_lshlrev_b32_e32 v64, 16, v38
	v_and_b32_e32 v65, 0xffff0000, v38
	v_lshlrev_b32_e32 v72, 16, v44
	v_and_b32_e32 v73, 0xffff0000, v44
	v_lshlrev_b32_e32 v84, 16, v45
	v_and_b32_e32 v85, 0xffff0000, v45
	v_pk_add_f32 v[44:45], v[68:69], 0 op_sel_hi:[1,0]
	v_div_scale_f32 v96, vcc, 1.0, v81, 1.0
	v_pk_add_f32 v[94:95], v[44:45], v[64:65]
	v_div_scale_f32 v44, s[16:17], v81, v81, 1.0
	v_rcp_f32_e32 v45, v44
	v_lshlrev_b32_e32 v70, 16, v43
	v_and_b32_e32 v71, 0xffff0000, v43
	v_lshlrev_b32_e32 v38, 16, v39
	v_fma_f32 v97, -v44, v45, 1.0
	v_fmac_f32_e32 v45, v97, v45
	v_mul_f32_e32 v97, v96, v45
	v_fma_f32 v114, -v44, v97, v96
	v_fmac_f32_e32 v97, v114, v45
	v_fma_f32 v44, -v44, v97, v96
	v_and_b32_e32 v39, 0xffff0000, v39
	v_lshlrev_b32_e32 v42, 16, v40
	v_and_b32_e32 v43, 0xffff0000, v40
	v_lshlrev_b32_e32 v40, 16, v41
	v_and_b32_e32 v41, 0xffff0000, v41
	v_pk_add_f32 v[86:87], v[70:71], 0 op_sel_hi:[1,0]
	v_pk_add_f32 v[88:89], v[72:73], 0 op_sel_hi:[1,0]
	v_pk_add_f32 v[92:93], v[84:85], 0 op_sel_hi:[1,0]
	v_div_fmas_f32 v44, v44, v45, v97
	v_pk_add_f32 v[86:87], v[86:87], v[38:39]
	v_pk_add_f32 v[88:89], v[88:89], v[42:43]
	v_pk_add_f32 v[92:93], v[92:93], v[40:41]
	v_div_fixup_f32 v44, v44, v81, 1.0
	v_pk_fma_f32 v[96:97], v[44:45], v[94:95], v[64:65] op_sel_hi:[0,1,1] neg_lo:[0,0,1] neg_hi:[0,0,1]
	v_pk_fma_f32 v[114:115], v[44:45], v[86:87], v[38:39] op_sel_hi:[0,1,1] neg_lo:[0,0,1] neg_hi:[0,0,1]
	v_pk_fma_f32 v[116:117], v[44:45], v[88:89], v[42:43] op_sel_hi:[0,1,1] neg_lo:[0,0,1] neg_hi:[0,0,1]
	v_pk_fma_f32 v[44:45], v[44:45], v[92:93], v[40:41] op_sel_hi:[0,1,1] neg_lo:[0,0,1] neg_hi:[0,0,1]
	v_lshlrev_b64 v[66:67], 11, v[66:67]
	v_lshl_add_u64 v[82:83], v[112:113], 0, v[82:83]
	v_lshl_add_u64 v[90:91], v[110:111], 0, v[66:67]
	v_lshlrev_b64 v[62:63], 11, v[62:63]
	v_lshl_add_u64 v[66:67], v[112:113], 0, v[66:67]
	v_pk_mul_f32 v[116:117], v[116:117], v[6:7]
	v_pk_mul_f32 v[96:97], v[96:97], v[10:11]
	v_pk_mul_f32 v[114:115], v[114:115], v[12:13]
	v_pk_mul_f32 v[44:45], v[44:45], v[8:9]
	v_lshlrev_b32_e32 v118, 16, v46
	v_and_b32_e32 v119, 0xffff0000, v46
	v_lshlrev_b32_e32 v46, 16, v47
	v_and_b32_e32 v47, 0xffff0000, v47
	v_lshlrev_b32_e32 v120, 16, v48
	v_and_b32_e32 v121, 0xffff0000, v48
	v_lshlrev_b32_e32 v48, 16, v49
	v_and_b32_e32 v49, 0xffff0000, v49
	v_pk_mul_f32 v[96:97], v[96:97], v[118:119]
	v_pk_mul_f32 v[46:47], v[114:115], v[46:47]
	v_pk_mul_f32 v[114:115], v[116:117], v[120:121]
	v_pk_mul_f32 v[48:49], v[44:45], v[48:49]
	v_cvt_pk_bf16_f32 v44, v96, v97
	v_cvt_pk_bf16_f32 v45, v46, v47
	v_cvt_pk_bf16_f32 v46, v114, v115
	v_cvt_pk_bf16_f32 v47, v48, v49
	global_store_dwordx4 v[82:83], v[44:47], off sc1
	global_load_dwordx4 v[44:47], v[90:91], off
	v_lshlrev_b32_e32 v48, 16, v37
	v_and_b32_e32 v49, 0xffff0000, v37
	v_min_u32_e32 v37, v79, v221
	v_lshlrev_b32_e32 v82, 16, v34
	v_and_b32_e32 v83, 0xffff0000, v34
	v_lshlrev_b32_e32 v90, 16, v35
	v_and_b32_e32 v91, 0xffff0000, v35
	v_lshlrev_b32_e32 v96, 16, v36
	v_and_b32_e32 v97, 0xffff0000, v36
	v_sub_u32_e32 v114, v37, v80
	v_pk_add_f32 v[36:37], v[82:83], v[68:69] neg_lo:[0,1] neg_hi:[0,1]
	v_pk_add_f32 v[68:69], v[90:91], v[70:71] neg_lo:[0,1] neg_hi:[0,1]
	v_pk_add_f32 v[70:71], v[96:97], v[72:73] neg_lo:[0,1] neg_hi:[0,1]
	v_add_u32_e32 v72, 1, v114
	v_cvt_f32_i32_e32 v114, v72
	v_pk_add_f32 v[34:35], v[48:49], v[84:85] neg_lo:[0,1] neg_hi:[0,1]
	v_pk_add_f32 v[84:85], v[94:95], v[36:37]
	v_pk_add_f32 v[72:73], v[92:93], v[34:35]
	v_div_scale_f32 v34, s[16:17], v114, v114, 1.0
	v_rcp_f32_e32 v35, v34
	v_div_scale_f32 v36, vcc, 1.0, v114, 1.0
	v_pk_add_f32 v[68:69], v[86:87], v[68:69]
	v_fma_f32 v37, -v34, v35, 1.0
	v_fmac_f32_e32 v35, v37, v35
	v_mul_f32_e32 v37, v36, v35
	v_fma_f32 v86, -v34, v37, v36
	v_fmac_f32_e32 v37, v86, v35
	v_fma_f32 v34, -v34, v37, v36
	v_div_fmas_f32 v34, v34, v35, v37
	v_pk_add_f32 v[70:71], v[88:89], v[70:71]
	v_div_fixup_f32 v34, v34, v114, 1.0
	v_pk_fma_f32 v[36:37], v[34:35], v[84:85], v[82:83] op_sel_hi:[0,1,1] neg_lo:[0,0,1] neg_hi:[0,0,1]
	v_pk_fma_f32 v[86:87], v[34:35], v[68:69], v[90:91] op_sel_hi:[0,1,1] neg_lo:[0,0,1] neg_hi:[0,0,1]
	v_pk_fma_f32 v[88:89], v[34:35], v[70:71], v[96:97] op_sel_hi:[0,1,1] neg_lo:[0,0,1] neg_hi:[0,0,1]
	v_pk_fma_f32 v[34:35], v[34:35], v[72:73], v[48:49] op_sel_hi:[0,1,1] neg_lo:[0,0,1] neg_hi:[0,0,1]
	v_pk_mul_f32 v[36:37], v[36:37], v[10:11]
	v_pk_mul_f32 v[86:87], v[86:87], v[12:13]
	v_pk_mul_f32 v[88:89], v[88:89], v[6:7]
	v_pk_mul_f32 v[34:35], v[34:35], v[8:9]
	v_lshl_add_u64 v[80:81], v[110:111], 0, v[62:63]
	v_lshl_add_u64 v[62:63], v[112:113], 0, v[62:63]
	s_waitcnt vmcnt(0)
	v_lshlrev_b32_e32 v92, 16, v44
	v_and_b32_e32 v93, 0xffff0000, v44
	v_lshlrev_b32_e32 v44, 16, v45
	v_and_b32_e32 v45, 0xffff0000, v45
	v_lshlrev_b32_e32 v94, 16, v46
	v_and_b32_e32 v95, 0xffff0000, v46
	v_lshlrev_b32_e32 v46, 16, v47
	v_and_b32_e32 v47, 0xffff0000, v47
	v_pk_mul_f32 v[36:37], v[36:37], v[92:93]
	v_pk_mul_f32 v[44:45], v[86:87], v[44:45]
	v_pk_mul_f32 v[86:87], v[88:89], v[94:95]
	v_pk_mul_f32 v[46:47], v[34:35], v[46:47]
	v_cvt_pk_bf16_f32 v34, v36, v37
	v_cvt_pk_bf16_f32 v35, v44, v45
	v_cvt_pk_bf16_f32 v36, v86, v87
	v_cvt_pk_bf16_f32 v37, v46, v47
	global_store_dwordx4 v[66:67], v[34:37], off sc1
	global_load_dwordx4 v[34:37], v[80:81], off
	v_lshlrev_b32_e32 v44, 16, v33
	v_and_b32_e32 v45, 0xffff0000, v33
	v_min_u32_e32 v33, v78, v221
	v_lshlrev_b32_e32 v80, 16, v32
	v_and_b32_e32 v81, 0xffff0000, v32
	v_sub_u32_e32 v79, v33, v79
	v_lshlrev_b64 v[46:47], 11, v[60:61]
	v_lshlrev_b32_e32 v60, 16, v30
	v_and_b32_e32 v61, 0xffff0000, v30
	v_lshlrev_b32_e32 v66, 16, v31
	v_and_b32_e32 v67, 0xffff0000, v31
	v_pk_add_f32 v[30:31], v[44:45], v[40:41] neg_lo:[0,1] neg_hi:[0,1]
	v_pk_add_f32 v[40:41], v[80:81], v[42:43] neg_lo:[0,1] neg_hi:[0,1]
	v_add_u32_e32 v42, 1, v79
	v_cvt_f32_i32_e32 v79, v42
	v_pk_add_f32 v[42:43], v[72:73], v[30:31]
	v_pk_add_f32 v[32:33], v[60:61], v[64:65] neg_lo:[0,1] neg_hi:[0,1]
	v_pk_add_f32 v[38:39], v[66:67], v[38:39] neg_lo:[0,1] neg_hi:[0,1]
	v_div_scale_f32 v30, s[16:17], v79, v79, 1.0
	v_rcp_f32_e32 v31, v30
	v_pk_add_f32 v[64:65], v[84:85], v[32:33]
	v_div_scale_f32 v32, vcc, 1.0, v79, 1.0
	v_fma_f32 v33, -v30, v31, 1.0
	v_fmac_f32_e32 v31, v33, v31
	v_mul_f32_e32 v33, v32, v31
	v_pk_add_f32 v[38:39], v[68:69], v[38:39]
	v_fma_f32 v68, -v30, v33, v32
	v_fmac_f32_e32 v33, v68, v31
	v_fma_f32 v30, -v30, v33, v32
	v_div_fmas_f32 v30, v30, v31, v33
	v_pk_add_f32 v[40:41], v[70:71], v[40:41]
	v_div_fixup_f32 v30, v30, v79, 1.0
	v_pk_fma_f32 v[32:33], v[30:31], v[64:65], v[60:61] op_sel_hi:[0,1,1] neg_lo:[0,0,1] neg_hi:[0,0,1]
	v_pk_fma_f32 v[68:69], v[30:31], v[38:39], v[66:67] op_sel_hi:[0,1,1] neg_lo:[0,0,1] neg_hi:[0,0,1]
	v_pk_fma_f32 v[70:71], v[30:31], v[40:41], v[80:81] op_sel_hi:[0,1,1] neg_lo:[0,0,1] neg_hi:[0,0,1]
	v_pk_fma_f32 v[30:31], v[30:31], v[42:43], v[44:45] op_sel_hi:[0,1,1] neg_lo:[0,0,1] neg_hi:[0,0,1]
	v_pk_mul_f32 v[32:33], v[32:33], v[10:11]
	v_pk_mul_f32 v[68:69], v[68:69], v[12:13]
	v_pk_mul_f32 v[70:71], v[70:71], v[6:7]
	v_pk_mul_f32 v[30:31], v[30:31], v[8:9]
	v_lshl_add_u64 v[86:87], v[110:111], 0, v[46:47]
	v_lshl_add_u64 v[46:47], v[112:113], 0, v[46:47]
	s_waitcnt vmcnt(0)
	v_lshlrev_b32_e32 v72, 16, v34
	v_and_b32_e32 v73, 0xffff0000, v34
	v_lshlrev_b32_e32 v34, 16, v35
	v_and_b32_e32 v35, 0xffff0000, v35
	v_lshlrev_b32_e32 v84, 16, v36
	v_and_b32_e32 v85, 0xffff0000, v36
	v_lshlrev_b32_e32 v36, 16, v37
	v_and_b32_e32 v37, 0xffff0000, v37
	v_pk_mul_f32 v[32:33], v[32:33], v[72:73]
	v_pk_mul_f32 v[34:35], v[68:69], v[34:35]
	v_pk_mul_f32 v[68:69], v[70:71], v[84:85]
	v_pk_mul_f32 v[36:37], v[30:31], v[36:37]
	v_cvt_pk_bf16_f32 v30, v32, v33
	v_cvt_pk_bf16_f32 v31, v34, v35
	v_cvt_pk_bf16_f32 v32, v68, v69
	v_cvt_pk_bf16_f32 v33, v36, v37
	global_store_dwordx4 v[62:63], v[30:33], off sc1
	global_load_dwordx4 v[30:33], v[86:87], off
	v_lshlrev_b32_e32 v34, 16, v29
	v_and_b32_e32 v35, 0xffff0000, v29
	v_min_u32_e32 v29, v77, v221
	v_sub_u32_e32 v78, v29, v78
	v_add_u32_e32 v78, 1, v78
	v_cvt_f32_i32_e32 v78, v78
	v_lshlrev_b64 v[36:37], 11, v[58:59]
	v_lshlrev_b32_e32 v58, 16, v26
	v_and_b32_e32 v59, 0xffff0000, v26
	v_lshlrev_b32_e32 v62, 16, v27
	v_and_b32_e32 v63, 0xffff0000, v27
	v_pk_add_f32 v[26:27], v[34:35], v[48:49] neg_lo:[0,1] neg_hi:[0,1]
	v_lshlrev_b32_e32 v68, 16, v28
	v_pk_add_f32 v[42:43], v[42:43], v[26:27]
	v_div_scale_f32 v26, s[16:17], v78, v78, 1.0
	v_rcp_f32_e32 v27, v26
	v_and_b32_e32 v69, 0xffff0000, v28
	v_pk_add_f32 v[28:29], v[58:59], v[82:83] neg_lo:[0,1] neg_hi:[0,1]
	v_pk_add_f32 v[48:49], v[62:63], v[90:91] neg_lo:[0,1] neg_hi:[0,1]
	v_pk_add_f32 v[64:65], v[64:65], v[28:29]
	v_fma_f32 v29, -v26, v27, 1.0
	v_div_scale_f32 v28, vcc, 1.0, v78, 1.0
	v_fmac_f32_e32 v27, v29, v27
	v_mul_f32_e32 v29, v28, v27
	v_pk_add_f32 v[38:39], v[38:39], v[48:49]
	v_fma_f32 v48, -v26, v29, v28
	v_fmac_f32_e32 v29, v48, v27
	v_fma_f32 v26, -v26, v29, v28
	v_pk_add_f32 v[72:73], v[68:69], v[96:97] neg_lo:[0,1] neg_hi:[0,1]
	v_div_fmas_f32 v26, v26, v27, v29
	v_pk_add_f32 v[40:41], v[40:41], v[72:73]
	v_div_fixup_f32 v26, v26, v78, 1.0
	v_pk_fma_f32 v[28:29], v[26:27], v[64:65], v[58:59] op_sel_hi:[0,1,1] neg_lo:[0,0,1] neg_hi:[0,0,1]
	v_pk_fma_f32 v[48:49], v[26:27], v[38:39], v[62:63] op_sel_hi:[0,1,1] neg_lo:[0,0,1] neg_hi:[0,0,1]
	v_pk_fma_f32 v[72:73], v[26:27], v[40:41], v[68:69] op_sel_hi:[0,1,1] neg_lo:[0,0,1] neg_hi:[0,0,1]
	v_pk_fma_f32 v[26:27], v[26:27], v[42:43], v[34:35] op_sel_hi:[0,1,1] neg_lo:[0,0,1] neg_hi:[0,0,1]
	v_pk_mul_f32 v[28:29], v[28:29], v[10:11]
	v_pk_mul_f32 v[48:49], v[48:49], v[12:13]
	v_pk_mul_f32 v[72:73], v[72:73], v[6:7]
	v_pk_mul_f32 v[26:27], v[26:27], v[8:9]
	v_lshl_add_u64 v[70:71], v[110:111], 0, v[36:37]
	v_lshl_add_u64 v[36:37], v[112:113], 0, v[36:37]
	s_waitcnt vmcnt(0)
	v_lshlrev_b32_e32 v78, 16, v30
	v_and_b32_e32 v79, 0xffff0000, v30
	v_lshlrev_b32_e32 v30, 16, v31
	v_and_b32_e32 v31, 0xffff0000, v31
	v_lshlrev_b32_e32 v82, 16, v32
	v_and_b32_e32 v83, 0xffff0000, v32
	v_lshlrev_b32_e32 v32, 16, v33
	v_and_b32_e32 v33, 0xffff0000, v33
	v_pk_mul_f32 v[28:29], v[28:29], v[78:79]
	v_pk_mul_f32 v[30:31], v[48:49], v[30:31]
	v_pk_mul_f32 v[48:49], v[72:73], v[82:83]
	v_pk_mul_f32 v[32:33], v[26:27], v[32:33]
	v_cvt_pk_bf16_f32 v26, v28, v29
	v_cvt_pk_bf16_f32 v27, v30, v31
	v_cvt_pk_bf16_f32 v28, v48, v49
	v_cvt_pk_bf16_f32 v29, v32, v33
	global_store_dwordx4 v[46:47], v[26:29], off sc1
	global_load_dwordx4 v[26:29], v[70:71], off
	v_lshlrev_b32_e32 v30, 16, v25
	v_and_b32_e32 v31, 0xffff0000, v25
	v_min_u32_e32 v25, v76, v221
	v_lshlrev_b32_e32 v48, 16, v23
	v_and_b32_e32 v49, 0xffff0000, v23
	v_sub_u32_e32 v72, v25, v77
	v_lshlrev_b32_e32 v46, 16, v22
	v_and_b32_e32 v47, 0xffff0000, v22
	v_pk_add_f32 v[22:23], v[30:31], v[44:45] neg_lo:[0,1] neg_hi:[0,1]
	v_pk_add_f32 v[44:45], v[48:49], v[66:67] neg_lo:[0,1] neg_hi:[0,1]
	v_add_u32_e32 v66, 1, v72
	v_cvt_f32_i32_e32 v66, v66
	v_pk_add_f32 v[42:43], v[42:43], v[22:23]
	v_lshlrev_b64 v[32:33], 11, v[56:57]
	v_lshlrev_b32_e32 v56, 16, v24
	v_div_scale_f32 v22, s[16:17], v66, v66, 1.0
	v_rcp_f32_e32 v23, v22
	v_and_b32_e32 v57, 0xffff0000, v24
	v_pk_add_f32 v[24:25], v[46:47], v[60:61] neg_lo:[0,1] neg_hi:[0,1]
	v_pk_add_f32 v[38:39], v[38:39], v[44:45]
	v_pk_add_f32 v[64:65], v[64:65], v[24:25]
	v_fma_f32 v25, -v22, v23, 1.0
	v_div_scale_f32 v24, vcc, 1.0, v66, 1.0
	v_fmac_f32_e32 v23, v25, v23
	v_mul_f32_e32 v25, v24, v23
	v_fma_f32 v44, -v22, v25, v24
	v_fmac_f32_e32 v25, v44, v23
	v_fma_f32 v22, -v22, v25, v24
	v_pk_add_f32 v[60:61], v[56:57], v[80:81] neg_lo:[0,1] neg_hi:[0,1]
	v_div_fmas_f32 v22, v22, v23, v25
	v_pk_add_f32 v[40:41], v[40:41], v[60:61]
	v_div_fixup_f32 v22, v22, v66, 1.0
	v_pk_fma_f32 v[24:25], v[22:23], v[64:65], v[46:47] op_sel_hi:[0,1,1] neg_lo:[0,0,1] neg_hi:[0,0,1]
	v_pk_fma_f32 v[44:45], v[22:23], v[38:39], v[48:49] op_sel_hi:[0,1,1] neg_lo:[0,0,1] neg_hi:[0,0,1]
	v_pk_fma_f32 v[60:61], v[22:23], v[40:41], v[56:57] op_sel_hi:[0,1,1] neg_lo:[0,0,1] neg_hi:[0,0,1]
	v_pk_fma_f32 v[22:23], v[22:23], v[42:43], v[30:31] op_sel_hi:[0,1,1] neg_lo:[0,0,1] neg_hi:[0,0,1]
	v_pk_mul_f32 v[24:25], v[24:25], v[10:11]
	v_pk_mul_f32 v[44:45], v[44:45], v[12:13]
	v_pk_mul_f32 v[60:61], v[60:61], v[6:7]
	v_pk_mul_f32 v[22:23], v[22:23], v[8:9]
	v_lshl_add_u64 v[70:71], v[110:111], 0, v[32:33]
	v_lshl_add_u64 v[32:33], v[112:113], 0, v[32:33]
	s_waitcnt vmcnt(0)
	v_lshlrev_b32_e32 v66, 16, v26
	v_and_b32_e32 v67, 0xffff0000, v26
	v_lshlrev_b32_e32 v26, 16, v27
	v_and_b32_e32 v27, 0xffff0000, v27
	v_lshlrev_b32_e32 v72, 16, v28
	v_and_b32_e32 v73, 0xffff0000, v28
	v_lshlrev_b32_e32 v28, 16, v29
	v_and_b32_e32 v29, 0xffff0000, v29
	v_pk_mul_f32 v[24:25], v[24:25], v[66:67]
	v_pk_mul_f32 v[26:27], v[44:45], v[26:27]
	v_pk_mul_f32 v[44:45], v[60:61], v[72:73]
	v_pk_mul_f32 v[28:29], v[22:23], v[28:29]
	v_cvt_pk_bf16_f32 v22, v24, v25
	v_cvt_pk_bf16_f32 v23, v26, v27
	v_cvt_pk_bf16_f32 v24, v44, v45
	v_cvt_pk_bf16_f32 v25, v28, v29
	global_store_dwordx4 v[36:37], v[22:25], off sc1
	global_load_dwordx4 v[22:25], v[70:71], off
	v_min_u32_e32 v60, v75, v221
	v_lshlrev_b32_e32 v28, 16, v21
	v_and_b32_e32 v29, 0xffff0000, v21
	v_sub_u32_e32 v66, v60, v76
	v_lshlrev_b32_e32 v36, 16, v18
	v_and_b32_e32 v37, 0xffff0000, v18
	v_lshlrev_b32_e32 v44, 16, v19
	v_and_b32_e32 v45, 0xffff0000, v19
	v_pk_add_f32 v[18:19], v[28:29], v[34:35] neg_lo:[0,1] neg_hi:[0,1]
	v_add_u32_e32 v34, 1, v66
	v_cvt_f32_i32_e32 v66, v34
	v_pk_add_f32 v[42:43], v[42:43], v[18:19]
	v_lshlrev_b64 v[26:27], 11, v[54:55]
	v_lshlrev_b32_e32 v54, 16, v20
	v_div_scale_f32 v67, s[16:17], v66, v66, 1.0
	v_rcp_f32_e32 v18, v67
	v_and_b32_e32 v55, 0xffff0000, v20
	v_pk_add_f32 v[20:21], v[36:37], v[58:59] neg_lo:[0,1] neg_hi:[0,1]
	v_pk_add_f32 v[58:59], v[54:55], v[68:69] neg_lo:[0,1] neg_hi:[0,1]
	v_fma_f32 v19, -v67, v18, 1.0
	v_div_scale_f32 v68, vcc, 1.0, v66, 1.0
	v_fmac_f32_e32 v18, v19, v18
	v_mul_f32_e32 v19, v68, v18
	v_pk_add_f32 v[34:35], v[44:45], v[62:63] neg_lo:[0,1] neg_hi:[0,1]
	v_pk_add_f32 v[62:63], v[64:65], v[20:21]
	v_fma_f32 v20, -v67, v19, v68
	v_fmac_f32_e32 v19, v20, v18
	v_fma_f32 v20, -v67, v19, v68
	v_div_fmas_f32 v18, v20, v18, v19
	v_pk_add_f32 v[34:35], v[38:39], v[34:35]
	v_pk_add_f32 v[38:39], v[40:41], v[58:59]
	v_div_fixup_f32 v18, v18, v66, 1.0
	v_pk_fma_f32 v[20:21], v[18:19], v[62:63], v[36:37] op_sel_hi:[0,1,1] neg_lo:[0,0,1] neg_hi:[0,0,1]
	v_pk_fma_f32 v[40:41], v[18:19], v[34:35], v[44:45] op_sel_hi:[0,1,1] neg_lo:[0,0,1] neg_hi:[0,0,1]
	v_pk_fma_f32 v[58:59], v[18:19], v[38:39], v[54:55] op_sel_hi:[0,1,1] neg_lo:[0,0,1] neg_hi:[0,0,1]
	v_pk_fma_f32 v[18:19], v[18:19], v[42:43], v[28:29] op_sel_hi:[0,1,1] neg_lo:[0,0,1] neg_hi:[0,0,1]
	v_pk_mul_f32 v[20:21], v[20:21], v[10:11]
	v_pk_mul_f32 v[40:41], v[40:41], v[12:13]
	v_pk_mul_f32 v[58:59], v[58:59], v[6:7]
	v_pk_mul_f32 v[18:19], v[18:19], v[8:9]
	v_lshl_add_u64 v[60:61], v[110:111], 0, v[26:27]
	v_lshl_add_u64 v[26:27], v[112:113], 0, v[26:27]
	s_waitcnt vmcnt(0)
	v_lshlrev_b32_e32 v64, 16, v22
	v_and_b32_e32 v65, 0xffff0000, v22
	v_lshlrev_b32_e32 v22, 16, v23
	v_and_b32_e32 v23, 0xffff0000, v23
	v_lshlrev_b32_e32 v66, 16, v24
	v_and_b32_e32 v67, 0xffff0000, v24
	v_lshlrev_b32_e32 v24, 16, v25
	v_and_b32_e32 v25, 0xffff0000, v25
	v_pk_mul_f32 v[20:21], v[20:21], v[64:65]
	v_pk_mul_f32 v[22:23], v[40:41], v[22:23]
	v_pk_mul_f32 v[40:41], v[58:59], v[66:67]
	v_pk_mul_f32 v[24:25], v[18:19], v[24:25]
	v_cvt_pk_bf16_f32 v18, v20, v21
	v_cvt_pk_bf16_f32 v19, v22, v23
	v_cvt_pk_bf16_f32 v20, v40, v41
	v_cvt_pk_bf16_f32 v21, v24, v25
	global_store_dwordx4 v[32:33], v[18:21], off sc1
	global_load_dwordx4 v[18:21], v[60:61], off
	v_min_u32_e32 v58, v74, v221
	v_lshl_add_u64 v[22:23], v[110:111], 0, v[52:53]
	v_lshlrev_b32_e32 v24, 16, v17
	v_and_b32_e32 v25, 0xffff0000, v17
	v_lshlrev_b32_e32 v32, 16, v14
	v_and_b32_e32 v33, 0xffff0000, v14
	v_sub_u32_e32 v52, v58, v75
	v_lshlrev_b32_e32 v40, 16, v16
	v_and_b32_e32 v41, 0xffff0000, v16
	v_pk_add_f32 v[16:17], v[24:25], v[30:31] neg_lo:[0,1] neg_hi:[0,1]
	v_pk_add_f32 v[30:31], v[32:33], v[46:47] neg_lo:[0,1] neg_hi:[0,1]
	v_add_u32_e32 v46, 1, v52
	v_cvt_f32_i32_e32 v52, v46
	v_lshlrev_b32_e32 v14, 16, v15
	v_and_b32_e32 v15, 0xffff0000, v15
	v_pk_add_f32 v[46:47], v[14:15], v[48:49] neg_lo:[0,1] neg_hi:[0,1]
	v_div_scale_f32 v53, s[16:17], v52, v52, 1.0
	v_pk_add_f32 v[48:49], v[40:41], v[56:57] neg_lo:[0,1] neg_hi:[0,1]
	v_rcp_f32_e32 v57, v53
	v_pk_add_f32 v[42:43], v[42:43], v[16:17]
	v_div_scale_f32 v56, vcc, 1.0, v52, 1.0
	v_fma_f32 v16, -v53, v57, 1.0
	v_fmac_f32_e32 v57, v16, v57
	v_mul_f32_e32 v16, v56, v57
	v_fma_f32 v17, -v53, v16, v56
	v_fmac_f32_e32 v16, v17, v57
	v_fma_f32 v17, -v53, v16, v56
	v_div_fmas_f32 v16, v17, v57, v16
	v_pk_add_f32 v[30:31], v[62:63], v[30:31]
	v_pk_add_f32 v[34:35], v[34:35], v[46:47]
	v_pk_add_f32 v[38:39], v[38:39], v[48:49]
	v_div_fixup_f32 v16, v16, v52, 1.0
	v_pk_fma_f32 v[32:33], v[16:17], v[30:31], v[32:33] op_sel_hi:[0,1,1] neg_lo:[0,0,1] neg_hi:[0,0,1]
	v_pk_fma_f32 v[14:15], v[16:17], v[34:35], v[14:15] op_sel_hi:[0,1,1] neg_lo:[0,0,1] neg_hi:[0,0,1]
	v_pk_fma_f32 v[40:41], v[16:17], v[38:39], v[40:41] op_sel_hi:[0,1,1] neg_lo:[0,0,1] neg_hi:[0,0,1]
	v_pk_fma_f32 v[16:17], v[16:17], v[42:43], v[24:25] op_sel_hi:[0,1,1] neg_lo:[0,0,1] neg_hi:[0,0,1]
	v_pk_mul_f32 v[24:25], v[32:33], v[10:11]
	v_pk_mul_f32 v[14:15], v[14:15], v[12:13]
	v_pk_mul_f32 v[32:33], v[40:41], v[6:7]
	v_pk_mul_f32 v[16:17], v[16:17], v[8:9]
	s_waitcnt vmcnt(0)
	v_lshlrev_b32_e32 v40, 16, v18
	v_and_b32_e32 v41, 0xffff0000, v18
	v_lshlrev_b32_e32 v18, 16, v19
	v_and_b32_e32 v19, 0xffff0000, v19
	v_lshlrev_b32_e32 v46, 16, v20
	v_and_b32_e32 v47, 0xffff0000, v20
	v_lshlrev_b32_e32 v20, 16, v21
	v_and_b32_e32 v21, 0xffff0000, v21
	v_pk_mul_f32 v[24:25], v[24:25], v[40:41]
	v_pk_mul_f32 v[18:19], v[14:15], v[18:19]
	v_pk_mul_f32 v[32:33], v[32:33], v[46:47]
	v_pk_mul_f32 v[20:21], v[16:17], v[20:21]
	v_cvt_pk_bf16_f32 v14, v24, v25
	v_cvt_pk_bf16_f32 v15, v18, v19
	v_cvt_pk_bf16_f32 v16, v32, v33
	v_cvt_pk_bf16_f32 v17, v20, v21
	global_store_dwordx4 v[26:27], v[14:17], off sc1
	global_load_dwordx4 v[14:17], v[22:23], off
	v_add_u32_e32 v24, 8, v222
	v_lshlrev_b32_e32 v18, 16, v5
	v_and_b32_e32 v19, 0xffff0000, v5
	v_min_u32_e32 v32, v24, v221
	v_lshlrev_b32_e32 v22, 16, v4
	v_and_b32_e32 v23, 0xffff0000, v4
	v_pk_add_f32 v[4:5], v[18:19], v[28:29] neg_lo:[0,1] neg_hi:[0,1]
	v_sub_u32_e32 v28, v32, v74
	v_lshlrev_b32_e32 v20, 16, v2
	v_and_b32_e32 v21, 0xffff0000, v2
	v_add_u32_e32 v28, 1, v28
	v_pk_add_f32 v[24:25], v[20:21], v[36:37] neg_lo:[0,1] neg_hi:[0,1]
	v_cvt_f32_i32_e32 v36, v28
	v_pk_add_f32 v[32:33], v[22:23], v[54:55] neg_lo:[0,1] neg_hi:[0,1]
	v_pk_add_f32 v[24:25], v[30:31], v[24:25]
	v_pk_add_f32 v[30:31], v[38:39], v[32:33]
	v_div_scale_f32 v37, s[16:17], v36, v36, 1.0
	v_rcp_f32_e32 v41, v37
	v_div_scale_f32 v40, vcc, 1.0, v36, 1.0
	v_lshlrev_b32_e32 v2, 16, v3
	v_fma_f32 v32, -v37, v41, 1.0
	v_fmac_f32_e32 v41, v32, v41
	v_mul_f32_e32 v32, v40, v41
	v_fma_f32 v33, -v37, v32, v40
	v_fmac_f32_e32 v32, v33, v41
	v_and_b32_e32 v3, 0xffff0000, v3
	v_fma_f32 v33, -v37, v32, v40
	v_pk_add_f32 v[28:29], v[2:3], v[44:45] neg_lo:[0,1] neg_hi:[0,1]
	v_div_fmas_f32 v32, v33, v41, v32
	v_pk_add_f32 v[4:5], v[42:43], v[4:5]
	v_pk_add_f32 v[28:29], v[34:35], v[28:29]
	v_div_fixup_f32 v32, v32, v36, 1.0
	v_pk_fma_f32 v[20:21], v[32:33], v[24:25], v[20:21] op_sel_hi:[0,1,1] neg_lo:[0,0,1] neg_hi:[0,0,1]
	v_pk_fma_f32 v[2:3], v[32:33], v[28:29], v[2:3] op_sel_hi:[0,1,1] neg_lo:[0,0,1] neg_hi:[0,0,1]
	v_pk_fma_f32 v[22:23], v[32:33], v[30:31], v[22:23] op_sel_hi:[0,1,1] neg_lo:[0,0,1] neg_hi:[0,0,1]
	v_pk_fma_f32 v[4:5], v[32:33], v[4:5], v[18:19] op_sel_hi:[0,1,1] neg_lo:[0,0,1] neg_hi:[0,0,1]
	v_pk_mul_f32 v[10:11], v[10:11], v[20:21]
	v_pk_mul_f32 v[2:3], v[12:13], v[2:3]
	v_pk_mul_f32 v[6:7], v[6:7], v[22:23]
	v_pk_mul_f32 v[8:9], v[8:9], v[4:5]
	v_lshlrev_b64 v[26:27], 10, v[50:51]
	s_waitcnt vmcnt(0)
	v_lshlrev_b32_e32 v4, 16, v14
	v_and_b32_e32 v5, 0xffff0000, v14
	v_lshlrev_b32_e32 v14, 16, v15
	v_and_b32_e32 v15, 0xffff0000, v15
	v_lshlrev_b32_e32 v18, 16, v16
	v_and_b32_e32 v19, 0xffff0000, v16
	v_lshlrev_b32_e32 v12, 16, v17
	v_and_b32_e32 v13, 0xffff0000, v17
	v_pk_mul_f32 v[4:5], v[10:11], v[4:5]
	v_pk_mul_f32 v[10:11], v[2:3], v[14:15]
	v_pk_mul_f32 v[6:7], v[6:7], v[18:19]
	v_cvt_pk_bf16_f32 v2, v4, v5
	v_cvt_pk_bf16_f32 v3, v10, v11
	v_cvt_pk_bf16_f32 v4, v6, v7
	v_pk_mul_f32 v[6:7], v[8:9], v[12:13]

.LBB0_433:
	s_or_b64 exec, exec, s[4:5]
	s_load_dword s66, s[0:1], 0x468
	s_waitcnt lgkmcnt(0)
	s_cmpk_lg_u32 s66, 0x200
	s_cbranch_scc1 FUSE3_ORIG
	s_cmp_lt_i32 s23, 5
	s_cbranch_scc1 FUSE3_ORIG
	s_waitcnt vmcnt(0)
	s_barrier
	v_bfe_u32 v5, v0, 6, 2
	s_and_b32 s73, s2, 0x1ff
	s_nop 1
	v_readfirstlane_b32 s67, v5
	s_cmp_lg_u32 s67, 0
	s_cbranch_scc1 FUSE3_WAIT
	s_and_b32 s67, s73, 63
	s_lshl_b32 s68, s67, 6
	s_and_b32 s69, s67, 32
	s_lshl_b32 s69, s69, 6
	s_add_u32 s68, s68, s69
	s_add_u32 s68, s68, 0x1c00
	v_mov_b32_e32 v2, s68
	v_mov_b32_e32 v3, 1
	s_mov_b64 s[70:71], exec
	s_mov_b64 exec, 1
	s_mov_b32 s74, 0
	global_atomic_add v2, v3, s[20:21]
FUSE3_SPIN:
	global_load_dword v4, v2, s[20:21] sc1
	s_waitcnt vmcnt(0)
	v_readfirstlane_b32 s69, v4
	s_cmp_ge_u32 s69, 8
	s_cbranch_scc1 FUSE3_GOT
	s_add_i32 s74, s74, 1
	s_cmp_gt_u32 s74, 0x20000
	s_cbranch_scc1 FUSE3_GOT
	s_sleep 1
	s_branch FUSE3_SPIN
FUSE3_GOT:
	s_mov_b64 exec, s[70:71]
FUSE3_WAIT:
	s_barrier
	s_branch .LBB0_486
FUSE3_ORIG:
	s_cmp_lt_i32 s23, 5
	s_cbranch_scc1 .LBB0_486
	s_waitcnt vmcnt(0)
	v_cmp_eq_u32_e32 vcc, 0, v147
	v_mov_b32_e32 v2, v146
	v_mov_b32_e32 v4, v148
	s_waitcnt vmcnt(0) lgkmcnt(0)
	s_barrier
	s_and_saveexec_b64 s[4:5], vcc
	s_cbranch_execz .LBB0_483
	v_cmp_eq_u32_e32 vcc, 0, v148
	v_mov_b32_e32 v2, v146
	v_mov_b32_e32 v4, v148
	s_waitcnt vmcnt(0) expcnt(0) lgkmcnt(0)
	s_and_saveexec_b64 s[6:7], vcc
	s_cbranch_execz .LBB0_450
	s_load_dwordx2 s[12:13], s[0:1], 0x468
	s_load_dword s3, s[0:1], 0x470
	s_add_u32 s8, s20, 0x1000
	s_addc_u32 s9, s21, 0
	s_add_u32 s10, s20, 0x1100
	s_waitcnt lgkmcnt(0)
	s_mul_i32 s11, s13, s12
	s_mul_i32 s3, s11, s3
	s_addc_u32 s11, s21, 0
	s_add_u32 s12, s20, 0x1200
	s_addc_u32 s13, s21, 0
	s_add_u32 s14, s20, 0x1300
	s_addc_u32 s15, s21, 0
	s_mov_b32 s26, 1
	v_mov_b32_e32 v18, 0
	s_branch .LBB0_438

FUSE5_SPIN:
	global_load_dword v4, v2, s[20:21] sc1
	s_waitcnt vmcnt(0)
	v_readfirstlane_b32 s69, v4
	s_cmp_ge_u32 s69, 16
	s_cbranch_scc1 FUSE5_GOT
	s_add_i32 s74, s74, 1
	s_cmp_gt_u32 s74, 0x20000
	s_cbranch_scc1 FUSE5_GOT
	s_sleep 1
	s_branch FUSE5_SPIN

FUSE11_SPIN:
	global_load_dword v4, v2, s[20:21] sc1
	s_waitcnt vmcnt(0)
	v_readfirstlane_b32 s69, v4
	s_cmp_ge_u32 s69, 24
	s_cbranch_scc1 FUSE11_GOT
	s_add_i32 s74, s74, 1
	s_cmp_gt_u32 s74, 0x20000
	s_cbranch_scc1 FUSE11_GOT
	s_sleep 1
	s_branch FUSE11_SPIN

FUSE15_SPIN:
	global_load_dword v4, v2, s[20:21] sc1
	s_waitcnt vmcnt(0)
	v_readfirstlane_b32 s69, v4
	s_cmp_ge_u32 s69, 32
	s_cbranch_scc1 FUSE15_GOT
	s_add_i32 s74, s74, 1
	s_cmp_gt_u32 s74, 0x20000
	s_cbranch_scc1 FUSE15_GOT
	s_sleep 1
	s_branch FUSE15_SPIN

.LBB0_2143:
	s_cmp_gt_i32 s22, 18
	s_cselect_b64 s[4:5], -1, 0
	s_cmp_lt_i32 s23, 19
	s_cselect_b64 s[6:7], -1, 0
	s_or_b64 s[4:5], s[4:5], s[6:7]
	s_and_b64 vcc, exec, s[4:5]
	s_cbranch_vccnz .LBB0_2328
	s_load_dword s66, s[0:1], 0x468
	s_mov_b32 s75, s2
	s_movk_i32 s76, 0xc00
	s_waitcnt lgkmcnt(0)
	s_mov_b32 s77, s66
	s_cmpk_lg_u32 s66, 0x200
	s_cbranch_scc1 FUSE18_PAR
	s_and_b32 s67, s2, 63
	s_lshr_b32 s68, s2, 6
	s_mul_i32 s75, s67, 12
	s_add_i32 s75, s75, s68
	s_mul_i32 s76, s67, 48
	s_add_i32 s76, s76, 48
	s_mov_b32 s77, 8
FUSE18_PAR:
	v_lshl_or_b32 v149, s75, 2, v1
	s_waitcnt lgkmcnt(0)
	s_mov_b32 s3, s76
	v_and_b32_e32 v147, 0x3ff, v0
	v_cmp_gt_i32_e32 vcc, s3, v149
	s_and_saveexec_b64 s[4:5], vcc
	s_cbranch_execz .LBB0_2275
	s_load_dwordx2 s[8:9], s[0:1], 0x60
	s_waitcnt vmcnt(0)
	v_lshlrev_b32_e32 v2, 3, v147
	v_and_b32_e32 v98, 0xf8, v2
	v_or_b32_e32 v100, 0x300, v98
	v_lshrrev_b32_e32 v2, 2, v147
	s_waitcnt lgkmcnt(0)
	s_add_u32 s8, s8, 0x1000
	v_mov_b32_e32 v101, 0
	s_load_dwordx2 s[10:11], s[0:1], 0x98
	s_load_dwordx2 s[12:13], s[0:1], 0x108
	s_load_dwordx2 s[6:7], s[0:1], 0x118
	s_addc_u32 s9, s9, 0
	v_and_b32_e32 v151, 8, v2
	v_lshlrev_b32_e32 v2, 2, v100
	v_mov_b32_e32 v3, v101
	v_or_b32_e32 v104, 0x200, v98
	v_lshl_add_u64 v[102:103], s[8:9], 0, v[2:3]
	v_lshlrev_b32_e32 v2, 2, v104
	v_or_b32_e32 v108, 0x100, v98
	v_lshl_add_u64 v[106:107], s[8:9], 0, v[2:3]
	v_lshlrev_b32_e32 v2, 2, v108
	v_lshl_add_u64 v[110:111], s[8:9], 0, v[2:3]
	v_lshlrev_b32_e32 v2, 2, v98
	v_lshl_add_u64 v[112:113], s[8:9], 0, v[2:3]
	s_add_u32 s8, s0, 0x468
	v_lshlrev_b32_e32 v2, 1, v98
	v_mov_b32_e32 v105, v101
	v_mov_b32_e32 v109, v101
	v_mov_b32_e32 v99, v101
	s_addc_u32 s9, s1, 0
	s_waitcnt lgkmcnt(0)
	v_lshl_add_u64 v[114:115], s[12:13], 0, v[2:3]
	v_lshl_add_u64 v[116:117], s[10:11], 0, v[2:3]
	v_lshl_add_u64 v[118:119], s[6:7], 0, v[2:3]
	s_mov_b64 s[10:11], 0
	s_movk_i32 s3, 0x1000
	v_mov_b32_e32 v195, 0x7f8
	v_mov_b32_e32 v222, 0xf8
	v_mov_b32_e32 v223, 0x800
	v_mov_b32_e32 v224, 0x100
	v_mov_b32_e32 v225, 0xfffff800
	v_mov_b32_e32 v226, 0xffffff00
	s_add_i32 s18, s76, -1
	s_branch .LBB0_2149
.LBB0_2146:
	s_or_b64 exec, exec, s[16:17]
	v_lshlrev_b64 v[92:93], 11, v[54:55]
	v_lshl_add_u64 v[54:55], v[116:117], 0, v[92:93]
	global_load_dwordx4 v[6:9], v[110:111], off offset:16
	global_load_dwordx4 v[10:13], v[110:111], off
	s_waitcnt vmcnt(2)
	v_lshlrev_b32_e32 v74, 16, v53
	global_load_dwordx4 v[54:57], v[54:55], off offset:512
	v_and_b32_e32 v75, 0xffff0000, v53
	v_lshlrev_b32_e32 v66, 16, v49
	v_and_b32_e32 v67, 0xffff0000, v49
	v_min_u32_e32 v49, v123, v227
	v_sub_u32_e64 v53, v228, 2 clamp
	v_lshlrev_b32_e32 v82, 16, v36
	v_and_b32_e32 v83, 0xffff0000, v36
	v_sub_u32_e32 v36, v49, v53
	v_lshlrev_b32_e32 v86, 16, v38
	v_and_b32_e32 v87, 0xffff0000, v38
	v_cvt_f32_i32_e32 v36, v36
	v_lshlrev_b32_e32 v78, 16, v34
	v_and_b32_e32 v79, 0xffff0000, v34
	v_lshlrev_b32_e32 v88, 16, v39
	v_and_b32_e32 v89, 0xffff0000, v39
	v_lshlrev_b32_e32 v38, 16, v48
	v_and_b32_e32 v39, 0xffff0000, v48
	v_pk_add_f32 v[48:49], v[86:87], 0 op_sel_hi:[1,0]
	v_lshlrev_b32_e32 v76, 16, v50
	v_and_b32_e32 v77, 0xffff0000, v50
	v_pk_add_f32 v[48:49], v[48:49], v[78:79]
	v_lshlrev_b32_e32 v70, 16, v46
	v_and_b32_e32 v71, 0xffff0000, v46
	v_pk_add_f32 v[48:49], v[48:49], v[76:77]
	v_lshlrev_b32_e32 v80, 16, v35
	v_pk_add_f32 v[130:131], v[48:49], v[70:71]
	v_div_scale_f32 v48, s[16:17], v36, v36, 1.0
	v_rcp_f32_e32 v49, v48
	v_and_b32_e32 v81, 0xffff0000, v35
	v_lshlrev_b32_e32 v34, 16, v47
	v_and_b32_e32 v35, 0xffff0000, v47
	v_lshlrev_b32_e32 v46, 16, v52
	v_and_b32_e32 v47, 0xffff0000, v52
	v_pk_add_f32 v[52:53], v[88:89], 0 op_sel_hi:[1,0]
	v_lshlrev_b32_e32 v50, 16, v51
	v_and_b32_e32 v51, 0xffff0000, v51
	v_pk_add_f32 v[52:53], v[52:53], v[80:81]
	v_lshlrev_b32_e32 v90, 16, v40
	v_pk_add_f32 v[52:53], v[52:53], v[50:51]
	v_and_b32_e32 v91, 0xffff0000, v40
	v_pk_add_f32 v[132:133], v[52:53], v[34:35]
	v_fma_f32 v53, -v48, v49, 1.0
	v_div_scale_f32 v52, vcc, 1.0, v36, 1.0
	v_fmac_f32_e32 v49, v53, v49
	v_mul_f32_e32 v53, v52, v49
	v_fma_f32 v94, -v48, v53, v52
	v_fmac_f32_e32 v53, v94, v49
	v_fma_f32 v48, -v48, v53, v52
	v_div_fmas_f32 v48, v48, v49, v53
	v_div_fixup_f32 v36, v48, v36, 1.0
	v_pk_add_f32 v[126:127], v[90:91], 0 op_sel_hi:[1,0]
	v_pk_fma_f32 v[48:49], v[36:37], v[130:131], v[76:77] op_sel_hi:[0,1,1] neg_lo:[0,0,1] neg_hi:[0,0,1]
	v_pk_add_f32 v[126:127], v[126:127], v[82:83]
	v_pk_fma_f32 v[52:53], v[36:37], v[132:133], v[50:51] op_sel_hi:[0,1,1] neg_lo:[0,0,1] neg_hi:[0,0,1]
	v_lshlrev_b32_e32 v40, 16, v41
	v_pk_add_f32 v[126:127], v[126:127], v[46:47]
	v_and_b32_e32 v41, 0xffff0000, v41
	v_pk_add_f32 v[134:135], v[126:127], v[38:39]
	v_lshlrev_b64 v[84:85], 11, v[84:85]
	v_pk_fma_f32 v[126:127], v[36:37], v[134:135], v[46:47] op_sel_hi:[0,1,1] neg_lo:[0,0,1] neg_hi:[0,0,1]
	v_lshl_add_u64 v[92:93], v[118:119], 0, v[92:93]
	v_lshl_add_u64 v[128:129], v[116:117], 0, v[84:85]
	v_lshlrev_b64 v[64:65], 11, v[64:65]
	v_lshlrev_b64 v[62:63], 11, v[62:63]
	s_waitcnt vmcnt(2)
	v_pk_mul_f32 v[126:127], v[126:127], v[6:7]
	s_waitcnt vmcnt(1)
	v_pk_mul_f32 v[48:49], v[48:49], v[10:11]
	v_pk_mul_f32 v[52:53], v[52:53], v[12:13]
	s_waitcnt vmcnt(0)
	v_lshlrev_b32_e32 v136, 16, v54
	v_and_b32_e32 v137, 0xffff0000, v54
	v_lshlrev_b32_e32 v54, 16, v55
	v_and_b32_e32 v55, 0xffff0000, v55
	v_pk_mul_f32 v[48:49], v[48:49], v[136:137]
	v_pk_mul_f32 v[54:55], v[52:53], v[54:55]
	v_cvt_pk_bf16_f32 v52, v48, v49
	v_pk_add_f32 v[48:49], v[40:41], 0 op_sel_hi:[1,0]
	v_lshlrev_b32_e32 v136, 16, v37
	v_and_b32_e32 v137, 0xffff0000, v37
	v_pk_add_f32 v[48:49], v[48:49], v[136:137]
	v_lshlrev_b32_e32 v138, 16, v56
	v_and_b32_e32 v139, 0xffff0000, v56
	v_pk_add_f32 v[48:49], v[48:49], v[74:75]
	v_pk_mul_f32 v[126:127], v[126:127], v[138:139]
	v_pk_add_f32 v[138:139], v[48:49], v[66:67]
	v_lshlrev_b32_e32 v56, 16, v57
	v_pk_fma_f32 v[36:37], v[36:37], v[138:139], v[74:75] op_sel_hi:[0,1,1] neg_lo:[0,0,1] neg_hi:[0,0,1]
	v_and_b32_e32 v57, 0xffff0000, v57
	v_pk_mul_f32 v[36:37], v[36:37], v[8:9]
	v_cvt_pk_bf16_f32 v53, v54, v55
	v_pk_mul_f32 v[36:37], v[36:37], v[56:57]
	v_cvt_pk_bf16_f32 v54, v126, v127
	v_cvt_pk_bf16_f32 v55, v36, v37
	global_store_dwordx4 v[92:93], v[52:55], off offset:512 sc1
	global_load_dwordx4 v[126:129], v[128:129], off offset:512
	v_min_u32_e32 v36, v122, v227
	v_sub_u32_e64 v37, v124, 2 clamp
	v_sub_u32_e32 v92, v36, v37
	v_cvt_f32_i32_e32 v94, v92
	v_lshlrev_b32_e32 v48, 16, v45
	v_and_b32_e32 v49, 0xffff0000, v45
	v_lshlrev_b32_e32 v54, 16, v43
	v_and_b32_e32 v55, 0xffff0000, v43
	v_pk_add_f32 v[40:41], v[48:49], v[40:41] neg_lo:[0,1] neg_hi:[0,1]
	v_lshl_add_u64 v[36:37], v[118:119], 0, v[84:85]
	v_pk_add_f32 v[84:85], v[54:55], v[88:89] neg_lo:[0,1] neg_hi:[0,1]
	v_pk_add_f32 v[88:89], v[138:139], v[40:41]
	v_div_scale_f32 v40, s[16:17], v94, v94, 1.0
	v_rcp_f32_e32 v41, v40
	v_lshlrev_b32_e32 v52, 16, v42
	v_and_b32_e32 v53, 0xffff0000, v42
	v_lshlrev_b64 v[56:57], 11, v[72:73]
	v_lshlrev_b32_e32 v72, 16, v44
	v_and_b32_e32 v73, 0xffff0000, v44
	v_pk_add_f32 v[42:43], v[52:53], v[86:87] neg_lo:[0,1] neg_hi:[0,1]
	v_pk_add_f32 v[86:87], v[72:73], v[90:91] neg_lo:[0,1] neg_hi:[0,1]
	v_pk_add_f32 v[90:91], v[130:131], v[42:43]
	v_fma_f32 v43, -v40, v41, 1.0
	v_div_scale_f32 v42, vcc, 1.0, v94, 1.0
	v_fmac_f32_e32 v41, v43, v41
	v_mul_f32_e32 v43, v42, v41
	v_pk_add_f32 v[92:93], v[132:133], v[84:85]
	v_fma_f32 v84, -v40, v43, v42
	v_fmac_f32_e32 v43, v84, v41
	v_fma_f32 v40, -v40, v43, v42
	v_div_fmas_f32 v40, v40, v41, v43
	v_pk_add_f32 v[124:125], v[134:135], v[86:87]
	v_div_fixup_f32 v40, v40, v94, 1.0
	v_pk_fma_f32 v[42:43], v[40:41], v[90:91], v[70:71] op_sel_hi:[0,1,1] neg_lo:[0,0,1] neg_hi:[0,0,1]
	v_pk_fma_f32 v[84:85], v[40:41], v[92:93], v[34:35] op_sel_hi:[0,1,1] neg_lo:[0,0,1] neg_hi:[0,0,1]
	v_pk_fma_f32 v[86:87], v[40:41], v[124:125], v[38:39] op_sel_hi:[0,1,1] neg_lo:[0,0,1] neg_hi:[0,0,1]
	v_pk_fma_f32 v[40:41], v[40:41], v[88:89], v[66:67] op_sel_hi:[0,1,1] neg_lo:[0,0,1] neg_hi:[0,0,1]
	v_pk_mul_f32 v[42:43], v[42:43], v[10:11]
	v_pk_mul_f32 v[84:85], v[84:85], v[12:13]
	v_pk_mul_f32 v[86:87], v[86:87], v[6:7]
	v_pk_mul_f32 v[40:41], v[40:41], v[8:9]
	v_lshl_add_u64 v[44:45], v[116:117], 0, v[56:57]
	s_waitcnt vmcnt(0)
	v_lshlrev_b32_e32 v130, 16, v126
	v_and_b32_e32 v131, 0xffff0000, v126
	v_lshlrev_b32_e32 v126, 16, v127
	v_and_b32_e32 v127, 0xffff0000, v127
	v_lshlrev_b32_e32 v132, 16, v128
	v_and_b32_e32 v133, 0xffff0000, v128
	v_lshlrev_b32_e32 v128, 16, v129
	v_and_b32_e32 v129, 0xffff0000, v129
	v_pk_mul_f32 v[42:43], v[42:43], v[130:131]
	v_pk_mul_f32 v[84:85], v[84:85], v[126:127]
	v_pk_mul_f32 v[86:87], v[86:87], v[132:133]
	v_pk_mul_f32 v[126:127], v[40:41], v[128:129]
	v_cvt_pk_bf16_f32 v40, v42, v43
	v_cvt_pk_bf16_f32 v41, v84, v85
	v_cvt_pk_bf16_f32 v42, v86, v87
	v_cvt_pk_bf16_f32 v43, v126, v127
	global_store_dwordx4 v[36:37], v[40:43], off offset:512 sc1
	global_load_dwordx4 v[84:87], v[44:45], off offset:512
	v_lshlrev_b64 v[126:127], 11, v[68:69]
	v_min_u32_e32 v42, v121, v227
	v_lshlrev_b32_e32 v40, 16, v30
	v_and_b32_e32 v41, 0xffff0000, v30
	v_lshlrev_b32_e32 v44, 16, v31
	v_and_b32_e32 v45, 0xffff0000, v31
	v_lshlrev_b32_e32 v68, 16, v32
	v_and_b32_e32 v69, 0xffff0000, v32
	v_sub_u32_e32 v94, v42, v123
	v_lshlrev_b32_e32 v36, 16, v33
	v_and_b32_e32 v37, 0xffff0000, v33
	v_pk_add_f32 v[32:33], v[40:41], v[78:79] neg_lo:[0,1] neg_hi:[0,1]
	v_pk_add_f32 v[78:79], v[44:45], v[80:81] neg_lo:[0,1] neg_hi:[0,1]
	v_pk_add_f32 v[80:81], v[68:69], v[82:83] neg_lo:[0,1] neg_hi:[0,1]
	v_add_u32_e32 v82, 2, v94
	v_cvt_f32_i32_e32 v94, v82
	v_pk_add_f32 v[30:31], v[36:37], v[136:137] neg_lo:[0,1] neg_hi:[0,1]
	v_lshl_add_u64 v[42:43], v[118:119], 0, v[56:57]
	v_pk_add_f32 v[82:83], v[88:89], v[30:31]
	v_div_scale_f32 v30, s[16:17], v94, v94, 1.0
	v_rcp_f32_e32 v31, v30
	v_pk_add_f32 v[88:89], v[90:91], v[32:33]
	v_div_scale_f32 v32, vcc, 1.0, v94, 1.0
	v_fma_f32 v33, -v30, v31, 1.0
	v_fmac_f32_e32 v31, v33, v31
	v_mul_f32_e32 v33, v32, v31
	v_pk_add_f32 v[90:91], v[92:93], v[78:79]
	v_fma_f32 v78, -v30, v33, v32
	v_fmac_f32_e32 v33, v78, v31
	v_fma_f32 v30, -v30, v33, v32
	v_div_fmas_f32 v30, v30, v31, v33
	v_pk_add_f32 v[92:93], v[124:125], v[80:81]
	v_div_fixup_f32 v30, v30, v94, 1.0
	v_pk_fma_f32 v[32:33], v[30:31], v[88:89], v[52:53] op_sel_hi:[0,1,1] neg_lo:[0,0,1] neg_hi:[0,0,1]
	v_pk_fma_f32 v[78:79], v[30:31], v[90:91], v[54:55] op_sel_hi:[0,1,1] neg_lo:[0,0,1] neg_hi:[0,0,1]
	v_pk_fma_f32 v[80:81], v[30:31], v[92:93], v[72:73] op_sel_hi:[0,1,1] neg_lo:[0,0,1] neg_hi:[0,0,1]
	v_pk_fma_f32 v[30:31], v[30:31], v[82:83], v[48:49] op_sel_hi:[0,1,1] neg_lo:[0,0,1] neg_hi:[0,0,1]
	v_pk_mul_f32 v[32:33], v[32:33], v[10:11]
	v_pk_mul_f32 v[78:79], v[78:79], v[12:13]
	v_pk_mul_f32 v[80:81], v[80:81], v[6:7]
	v_pk_mul_f32 v[30:31], v[30:31], v[8:9]
	v_lshl_add_u64 v[56:57], v[116:117], 0, v[126:127]
	s_waitcnt vmcnt(0)
	v_lshlrev_b32_e32 v124, 16, v84
	v_and_b32_e32 v125, 0xffff0000, v84
	v_lshlrev_b32_e32 v84, 16, v85
	v_and_b32_e32 v85, 0xffff0000, v85
	v_lshlrev_b32_e32 v128, 16, v86
	v_and_b32_e32 v129, 0xffff0000, v86
	v_lshlrev_b32_e32 v86, 16, v87
	v_and_b32_e32 v87, 0xffff0000, v87
	v_pk_mul_f32 v[32:33], v[32:33], v[124:125]
	v_pk_mul_f32 v[78:79], v[78:79], v[84:85]
	v_pk_mul_f32 v[80:81], v[80:81], v[128:129]
	v_pk_mul_f32 v[84:85], v[30:31], v[86:87]
	v_cvt_pk_bf16_f32 v30, v32, v33
	v_cvt_pk_bf16_f32 v31, v78, v79
	v_cvt_pk_bf16_f32 v32, v80, v81
	v_cvt_pk_bf16_f32 v33, v84, v85
	global_store_dwordx4 v[42:43], v[30:33], off offset:512 sc1
	global_load_dwordx4 v[78:81], v[56:57], off offset:512
	v_lshlrev_b32_e32 v42, 16, v27
	v_lshlrev_b32_e32 v30, 16, v29
	v_and_b32_e32 v31, 0xffff0000, v29
	v_min_u32_e32 v29, v97, v227
	v_sub_u32_e32 v94, v29, v122
	v_lshlrev_b32_e32 v32, 16, v26
	v_and_b32_e32 v33, 0xffff0000, v26
	v_and_b32_e32 v43, 0xffff0000, v27
	v_pk_add_f32 v[26:27], v[30:31], v[74:75] neg_lo:[0,1] neg_hi:[0,1]
	v_add_u32_e32 v74, 2, v94
	v_cvt_f32_i32_e32 v94, v74
	v_pk_add_f32 v[74:75], v[82:83], v[26:27]
	v_lshlrev_b32_e32 v56, 16, v28
	v_and_b32_e32 v57, 0xffff0000, v28
	v_div_scale_f32 v122, s[16:17], v94, v94, 1.0
	v_rcp_f32_e32 v26, v122
	v_div_scale_f32 v123, vcc, 1.0, v94, 1.0
	v_pk_add_f32 v[28:29], v[32:33], v[76:77] neg_lo:[0,1] neg_hi:[0,1]
	v_fma_f32 v27, -v122, v26, 1.0
	v_fmac_f32_e32 v26, v27, v26
	v_mul_f32_e32 v27, v123, v26
	v_pk_add_f32 v[76:77], v[88:89], v[28:29]
	v_fma_f32 v28, -v122, v27, v123
	v_fmac_f32_e32 v27, v28, v26
	v_fma_f32 v28, -v122, v27, v123
	v_pk_add_f32 v[50:51], v[42:43], v[50:51] neg_lo:[0,1] neg_hi:[0,1]
	v_pk_add_f32 v[46:47], v[56:57], v[46:47] neg_lo:[0,1] neg_hi:[0,1]
	v_div_fmas_f32 v26, v28, v26, v27
	v_pk_add_f32 v[50:51], v[90:91], v[50:51]
	v_pk_add_f32 v[46:47], v[92:93], v[46:47]
	v_div_fixup_f32 v26, v26, v94, 1.0
	v_pk_fma_f32 v[28:29], v[26:27], v[76:77], v[40:41] op_sel_hi:[0,1,1] neg_lo:[0,0,1] neg_hi:[0,0,1]
	v_pk_fma_f32 v[82:83], v[26:27], v[50:51], v[44:45] op_sel_hi:[0,1,1] neg_lo:[0,0,1] neg_hi:[0,0,1]
	v_pk_fma_f32 v[88:89], v[26:27], v[46:47], v[68:69] op_sel_hi:[0,1,1] neg_lo:[0,0,1] neg_hi:[0,0,1]
	v_pk_fma_f32 v[26:27], v[26:27], v[74:75], v[36:37] op_sel_hi:[0,1,1] neg_lo:[0,0,1] neg_hi:[0,0,1]
	v_pk_mul_f32 v[28:29], v[28:29], v[10:11]
	v_pk_mul_f32 v[82:83], v[82:83], v[12:13]
	v_pk_mul_f32 v[88:89], v[88:89], v[6:7]
	v_pk_mul_f32 v[26:27], v[26:27], v[8:9]
	v_lshl_add_u64 v[84:85], v[118:119], 0, v[126:127]
	v_lshl_add_u64 v[86:87], v[116:117], 0, v[64:65]
	v_lshl_add_u64 v[64:65], v[118:119], 0, v[64:65]
	s_waitcnt vmcnt(0)
	v_lshlrev_b32_e32 v90, 16, v78
	v_and_b32_e32 v91, 0xffff0000, v78
	v_lshlrev_b32_e32 v78, 16, v79
	v_and_b32_e32 v79, 0xffff0000, v79
	v_lshlrev_b32_e32 v92, 16, v80
	v_and_b32_e32 v93, 0xffff0000, v80
	v_lshlrev_b32_e32 v80, 16, v81
	v_and_b32_e32 v81, 0xffff0000, v81
	v_pk_mul_f32 v[28:29], v[28:29], v[90:91]
	v_pk_mul_f32 v[78:79], v[82:83], v[78:79]
	v_pk_mul_f32 v[82:83], v[88:89], v[92:93]
	v_pk_mul_f32 v[80:81], v[26:27], v[80:81]
	v_cvt_pk_bf16_f32 v26, v28, v29
	v_cvt_pk_bf16_f32 v27, v78, v79
	v_cvt_pk_bf16_f32 v28, v82, v83
	v_cvt_pk_bf16_f32 v29, v80, v81
	global_store_dwordx4 v[84:85], v[26:29], off offset:512 sc1
	global_load_dwordx4 v[26:29], v[86:87], off offset:512
	v_lshlrev_b32_e32 v78, 16, v25
	v_and_b32_e32 v79, 0xffff0000, v25
	v_min_u32_e32 v25, v96, v227
	v_sub_u32_e32 v88, v25, v121
	v_lshlrev_b32_e32 v80, 16, v22
	v_and_b32_e32 v81, 0xffff0000, v22
	v_lshlrev_b32_e32 v82, 16, v23
	v_and_b32_e32 v83, 0xffff0000, v23
	v_pk_add_f32 v[22:23], v[78:79], v[66:67] neg_lo:[0,1] neg_hi:[0,1]
	v_add_u32_e32 v66, 2, v88
	v_cvt_f32_i32_e32 v88, v66
	v_pk_add_f32 v[66:67], v[74:75], v[22:23]
	v_lshlrev_b32_e32 v84, 16, v24
	v_and_b32_e32 v85, 0xffff0000, v24
	v_div_scale_f32 v89, s[16:17], v88, v88, 1.0
	v_rcp_f32_e32 v91, v89
	v_div_scale_f32 v90, vcc, 1.0, v88, 1.0
	v_pk_add_f32 v[24:25], v[80:81], v[70:71] neg_lo:[0,1] neg_hi:[0,1]
	v_fma_f32 v22, -v89, v91, 1.0
	v_fmac_f32_e32 v91, v22, v91
	v_mul_f32_e32 v22, v90, v91
	v_fma_f32 v23, -v89, v22, v90
	v_fmac_f32_e32 v22, v23, v91
	v_fma_f32 v23, -v89, v22, v90
	v_pk_add_f32 v[34:35], v[82:83], v[34:35] neg_lo:[0,1] neg_hi:[0,1]
	v_pk_add_f32 v[38:39], v[84:85], v[38:39] neg_lo:[0,1] neg_hi:[0,1]
	v_div_fmas_f32 v22, v23, v91, v22
	v_pk_add_f32 v[70:71], v[76:77], v[24:25]
	v_pk_add_f32 v[34:35], v[50:51], v[34:35]
	v_pk_add_f32 v[38:39], v[46:47], v[38:39]
	v_div_fixup_f32 v22, v22, v88, 1.0
	v_pk_fma_f32 v[24:25], v[22:23], v[70:71], v[32:33] op_sel_hi:[0,1,1] neg_lo:[0,0,1] neg_hi:[0,0,1]
	v_pk_fma_f32 v[46:47], v[22:23], v[34:35], v[42:43] op_sel_hi:[0,1,1] neg_lo:[0,0,1] neg_hi:[0,0,1]
	v_pk_fma_f32 v[50:51], v[22:23], v[38:39], v[56:57] op_sel_hi:[0,1,1] neg_lo:[0,0,1] neg_hi:[0,0,1]
	v_pk_fma_f32 v[22:23], v[22:23], v[66:67], v[30:31] op_sel_hi:[0,1,1] neg_lo:[0,0,1] neg_hi:[0,0,1]
	v_pk_mul_f32 v[24:25], v[24:25], v[10:11]
	v_pk_mul_f32 v[46:47], v[46:47], v[12:13]
	v_pk_mul_f32 v[50:51], v[50:51], v[6:7]
	v_pk_mul_f32 v[22:23], v[22:23], v[8:9]
	v_lshl_add_u64 v[86:87], v[116:117], 0, v[62:63]
	v_lshl_add_u64 v[62:63], v[118:119], 0, v[62:63]
	s_waitcnt vmcnt(0)
	v_lshlrev_b32_e32 v74, 16, v26
	v_and_b32_e32 v75, 0xffff0000, v26
	v_lshlrev_b32_e32 v26, 16, v27
	v_and_b32_e32 v27, 0xffff0000, v27
	v_lshlrev_b32_e32 v76, 16, v28
	v_and_b32_e32 v77, 0xffff0000, v28
	v_lshlrev_b32_e32 v28, 16, v29
	v_and_b32_e32 v29, 0xffff0000, v29
	v_pk_mul_f32 v[24:25], v[24:25], v[74:75]
	v_pk_mul_f32 v[26:27], v[46:47], v[26:27]
	v_pk_mul_f32 v[46:47], v[50:51], v[76:77]
	v_pk_mul_f32 v[28:29], v[22:23], v[28:29]
	v_cvt_pk_bf16_f32 v22, v24, v25
	v_cvt_pk_bf16_f32 v23, v26, v27
	v_cvt_pk_bf16_f32 v24, v46, v47
	v_cvt_pk_bf16_f32 v25, v28, v29
	global_store_dwordx4 v[64:65], v[22:25], off offset:512 sc1
	global_load_dwordx4 v[22:25], v[86:87], off offset:512
	v_min_u32_e32 v64, v95, v227
	v_lshlrev_b32_e32 v28, 16, v21
	v_and_b32_e32 v29, 0xffff0000, v21
	v_sub_u32_e32 v74, v64, v97
	v_lshlrev_b32_e32 v46, 16, v18
	v_and_b32_e32 v47, 0xffff0000, v18
	v_lshlrev_b32_e32 v50, 16, v19
	v_and_b32_e32 v51, 0xffff0000, v19
	v_pk_add_f32 v[18:19], v[28:29], v[48:49] neg_lo:[0,1] neg_hi:[0,1]
	v_add_u32_e32 v48, 2, v74
	v_cvt_f32_i32_e32 v74, v48
	v_lshlrev_b64 v[26:27], 11, v[60:61]
	v_lshlrev_b32_e32 v60, 16, v20
	v_and_b32_e32 v61, 0xffff0000, v20
	v_pk_add_f32 v[20:21], v[46:47], v[52:53] neg_lo:[0,1] neg_hi:[0,1]
	v_pk_add_f32 v[52:53], v[60:61], v[72:73] neg_lo:[0,1] neg_hi:[0,1]
	v_div_scale_f32 v72, s[16:17], v74, v74, 1.0
	v_rcp_f32_e32 v75, v72
	v_pk_add_f32 v[48:49], v[50:51], v[54:55] neg_lo:[0,1] neg_hi:[0,1]
	v_pk_add_f32 v[54:55], v[66:67], v[18:19]
	v_div_scale_f32 v73, vcc, 1.0, v74, 1.0
	v_fma_f32 v18, -v72, v75, 1.0
	v_fmac_f32_e32 v75, v18, v75
	v_mul_f32_e32 v18, v73, v75
	v_fma_f32 v19, -v72, v18, v73
	v_fmac_f32_e32 v18, v19, v75
	v_fma_f32 v19, -v72, v18, v73
	v_div_fmas_f32 v18, v19, v75, v18
	v_pk_add_f32 v[66:67], v[70:71], v[20:21]
	v_pk_add_f32 v[34:35], v[34:35], v[48:49]
	v_pk_add_f32 v[38:39], v[38:39], v[52:53]
	v_div_fixup_f32 v18, v18, v74, 1.0
	v_pk_fma_f32 v[20:21], v[18:19], v[66:67], v[80:81] op_sel_hi:[0,1,1] neg_lo:[0,0,1] neg_hi:[0,0,1]
	v_pk_fma_f32 v[48:49], v[18:19], v[34:35], v[82:83] op_sel_hi:[0,1,1] neg_lo:[0,0,1] neg_hi:[0,0,1]
	v_pk_fma_f32 v[52:53], v[18:19], v[38:39], v[84:85] op_sel_hi:[0,1,1] neg_lo:[0,0,1] neg_hi:[0,0,1]
	v_pk_fma_f32 v[18:19], v[18:19], v[54:55], v[78:79] op_sel_hi:[0,1,1] neg_lo:[0,0,1] neg_hi:[0,0,1]
	v_pk_mul_f32 v[20:21], v[20:21], v[10:11]
	v_pk_mul_f32 v[48:49], v[48:49], v[12:13]
	v_pk_mul_f32 v[52:53], v[52:53], v[6:7]
	v_pk_mul_f32 v[18:19], v[18:19], v[8:9]
	v_lshl_add_u64 v[64:65], v[116:117], 0, v[26:27]
	v_lshl_add_u64 v[26:27], v[118:119], 0, v[26:27]
	s_waitcnt vmcnt(0)
	v_lshlrev_b32_e32 v70, 16, v22
	v_and_b32_e32 v71, 0xffff0000, v22
	v_lshlrev_b32_e32 v22, 16, v23
	v_and_b32_e32 v23, 0xffff0000, v23
	v_lshlrev_b32_e32 v72, 16, v24
	v_and_b32_e32 v73, 0xffff0000, v24
	v_lshlrev_b32_e32 v24, 16, v25
	v_and_b32_e32 v25, 0xffff0000, v25
	v_pk_mul_f32 v[20:21], v[20:21], v[70:71]
	v_pk_mul_f32 v[22:23], v[48:49], v[22:23]
	v_pk_mul_f32 v[48:49], v[52:53], v[72:73]
	v_pk_mul_f32 v[24:25], v[18:19], v[24:25]
	v_cvt_pk_bf16_f32 v18, v20, v21
	v_cvt_pk_bf16_f32 v19, v22, v23
	v_cvt_pk_bf16_f32 v20, v48, v49
	v_cvt_pk_bf16_f32 v21, v24, v25
	global_store_dwordx4 v[62:63], v[18:21], off offset:512 sc1
	global_load_dwordx4 v[18:21], v[64:65], off offset:512
	v_min_u32_e32 v64, v120, v227
	v_lshlrev_b32_e32 v24, 16, v17
	v_and_b32_e32 v25, 0xffff0000, v17
	v_sub_u32_e32 v64, v64, v96
	v_lshlrev_b32_e32 v48, 16, v14
	v_and_b32_e32 v49, 0xffff0000, v14
	v_lshlrev_b32_e32 v52, 16, v15
	v_and_b32_e32 v53, 0xffff0000, v15
	v_pk_add_f32 v[14:15], v[24:25], v[36:37] neg_lo:[0,1] neg_hi:[0,1]
	v_add_u32_e32 v36, 2, v64
	v_cvt_f32_i32_e32 v64, v36
	v_lshlrev_b32_e32 v62, 16, v16
	v_and_b32_e32 v63, 0xffff0000, v16
	v_pk_add_f32 v[16:17], v[48:49], v[40:41] neg_lo:[0,1] neg_hi:[0,1]
	v_div_scale_f32 v65, s[16:17], v64, v64, 1.0
	v_pk_add_f32 v[40:41], v[62:63], v[68:69] neg_lo:[0,1] neg_hi:[0,1]
	v_rcp_f32_e32 v69, v65
	v_pk_add_f32 v[36:37], v[52:53], v[44:45] neg_lo:[0,1] neg_hi:[0,1]
	v_pk_add_f32 v[44:45], v[54:55], v[14:15]
	v_div_scale_f32 v68, vcc, 1.0, v64, 1.0
	v_fma_f32 v14, -v65, v69, 1.0
	v_fmac_f32_e32 v69, v14, v69
	v_mul_f32_e32 v14, v68, v69
	v_fma_f32 v15, -v65, v14, v68
	v_fmac_f32_e32 v14, v15, v69
	v_fma_f32 v15, -v65, v14, v68
	v_div_fmas_f32 v14, v15, v69, v14
	v_pk_add_f32 v[54:55], v[66:67], v[16:17]
	v_pk_add_f32 v[34:35], v[34:35], v[36:37]
	v_pk_add_f32 v[36:37], v[38:39], v[40:41]
	v_div_fixup_f32 v14, v14, v64, 1.0
	v_pk_fma_f32 v[16:17], v[14:15], v[54:55], v[46:47] op_sel_hi:[0,1,1] neg_lo:[0,0,1] neg_hi:[0,0,1]
	v_pk_fma_f32 v[38:39], v[14:15], v[34:35], v[50:51] op_sel_hi:[0,1,1] neg_lo:[0,0,1] neg_hi:[0,0,1]
	v_pk_fma_f32 v[40:41], v[14:15], v[36:37], v[60:61] op_sel_hi:[0,1,1] neg_lo:[0,0,1] neg_hi:[0,0,1]
	v_pk_fma_f32 v[14:15], v[14:15], v[44:45], v[28:29] op_sel_hi:[0,1,1] neg_lo:[0,0,1] neg_hi:[0,0,1]
	v_pk_mul_f32 v[16:17], v[16:17], v[10:11]
	v_pk_mul_f32 v[28:29], v[38:39], v[12:13]
	v_pk_mul_f32 v[38:39], v[40:41], v[6:7]
	v_pk_mul_f32 v[14:15], v[14:15], v[8:9]
	v_lshlrev_b64 v[22:23], 11, v[58:59]
	v_lshl_add_u64 v[22:23], v[116:117], 0, v[22:23]
	s_waitcnt vmcnt(0)
	v_lshlrev_b32_e32 v40, 16, v18
	v_and_b32_e32 v41, 0xffff0000, v18
	v_lshlrev_b32_e32 v18, 16, v19
	v_and_b32_e32 v19, 0xffff0000, v19
	v_lshlrev_b32_e32 v46, 16, v20
	v_and_b32_e32 v47, 0xffff0000, v20
	v_lshlrev_b32_e32 v20, 16, v21
	v_and_b32_e32 v21, 0xffff0000, v21
	v_pk_mul_f32 v[16:17], v[16:17], v[40:41]
	v_pk_mul_f32 v[18:19], v[28:29], v[18:19]
	v_pk_mul_f32 v[28:29], v[38:39], v[46:47]
	v_pk_mul_f32 v[20:21], v[14:15], v[20:21]
	v_cvt_pk_bf16_f32 v14, v16, v17
	v_cvt_pk_bf16_f32 v15, v18, v19
	v_cvt_pk_bf16_f32 v16, v28, v29
	v_cvt_pk_bf16_f32 v17, v20, v21
	global_store_dwordx4 v[26:27], v[14:17], off offset:512 sc1
	global_load_dwordx4 v[14:17], v[22:23], off offset:512
	v_add_u32_e32 v28, 9, v228
	v_lshlrev_b32_e32 v18, 16, v5
	v_and_b32_e32 v19, 0xffff0000, v5
	v_lshlrev_b32_e32 v20, 16, v2
	v_and_b32_e32 v21, 0xffff0000, v2
	v_min_u32_e32 v28, v28, v227
	v_lshlrev_b32_e32 v22, 16, v4
	v_and_b32_e32 v23, 0xffff0000, v4
	v_pk_add_f32 v[4:5], v[18:19], v[30:31] neg_lo:[0,1] neg_hi:[0,1]
	v_pk_add_f32 v[18:19], v[20:21], v[32:33] neg_lo:[0,1] neg_hi:[0,1]
	v_sub_u32_e32 v20, v28, v95
	v_add_u32_e32 v20, 2, v20
	v_cvt_f32_i32_e32 v28, v20
	v_pk_add_f32 v[20:21], v[22:23], v[56:57] neg_lo:[0,1] neg_hi:[0,1]
	v_lshlrev_b32_e32 v2, 16, v3
	v_and_b32_e32 v3, 0xffff0000, v3
	v_div_scale_f32 v22, s[16:17], v28, v28, 1.0
	v_rcp_f32_e32 v29, v22
	v_div_scale_f32 v23, vcc, 1.0, v28, 1.0
	v_pk_add_f32 v[2:3], v[2:3], v[42:43] neg_lo:[0,1] neg_hi:[0,1]
	v_fma_f32 v30, -v22, v29, 1.0
	v_fmac_f32_e32 v29, v30, v29
	v_mul_f32_e32 v30, v23, v29
	v_fma_f32 v31, -v22, v30, v23
	v_fmac_f32_e32 v30, v31, v29
	v_fma_f32 v22, -v22, v30, v23
	v_div_fmas_f32 v22, v22, v29, v30
	v_pk_add_f32 v[18:19], v[54:55], v[18:19]
	v_pk_add_f32 v[2:3], v[34:35], v[2:3]
	v_pk_add_f32 v[20:21], v[36:37], v[20:21]
	v_div_fixup_f32 v22, v22, v28, 1.0
	v_pk_add_f32 v[4:5], v[44:45], v[4:5]
	v_pk_fma_f32 v[18:19], v[22:23], v[18:19], v[48:49] op_sel_hi:[0,1,1] neg_lo:[0,0,1] neg_hi:[0,0,1]
	v_pk_fma_f32 v[2:3], v[22:23], v[2:3], v[52:53] op_sel_hi:[0,1,1] neg_lo:[0,0,1] neg_hi:[0,0,1]
	v_pk_fma_f32 v[20:21], v[22:23], v[20:21], v[62:63] op_sel_hi:[0,1,1] neg_lo:[0,0,1] neg_hi:[0,0,1]
	v_pk_fma_f32 v[4:5], v[22:23], v[4:5], v[24:25] op_sel_hi:[0,1,1] neg_lo:[0,0,1] neg_hi:[0,0,1]
	v_pk_mul_f32 v[10:11], v[10:11], v[18:19]
	v_pk_mul_f32 v[2:3], v[12:13], v[2:3]
	v_pk_mul_f32 v[6:7], v[6:7], v[20:21]
	v_pk_mul_f32 v[4:5], v[8:9], v[4:5]
	v_lshlrev_b64 v[26:27], 10, v[58:59]
	s_waitcnt vmcnt(0)
	v_lshlrev_b32_e32 v12, 16, v14
	v_and_b32_e32 v13, 0xffff0000, v14
	v_lshlrev_b32_e32 v14, 16, v15
	v_and_b32_e32 v15, 0xffff0000, v15
	v_lshlrev_b32_e32 v18, 16, v16
	v_and_b32_e32 v19, 0xffff0000, v16
	v_lshlrev_b32_e32 v8, 16, v17
	v_and_b32_e32 v9, 0xffff0000, v17
	v_pk_mul_f32 v[10:11], v[10:11], v[12:13]
	v_pk_mul_f32 v[12:13], v[2:3], v[14:15]
	v_pk_mul_f32 v[14:15], v[6:7], v[18:19]
	v_pk_mul_f32 v[6:7], v[4:5], v[8:9]
	v_cvt_pk_bf16_f32 v2, v10, v11
	v_cvt_pk_bf16_f32 v3, v12, v13
	v_cvt_pk_bf16_f32 v4, v14, v15
	v_mov_b64_e32 v[8:9], v[108:109]

.LBB0_2197:
	s_or_b64 exec, exec, s[16:17]
	v_add_u32_e32 v94, v228, v94
	v_ashrrev_i32_e32 v95, 31, v94
	v_lshlrev_b64 v[198:199], 11, v[94:95]
	v_lshl_add_u64 v[94:95], v[116:117], 0, v[198:199]
	global_load_dwordx4 v[94:97], v[94:95], off offset:1536
	s_waitcnt vmcnt(1)
	v_lshlrev_b32_e32 v178, 16, v14
	v_and_b32_e32 v179, 0xffff0000, v14
	v_lshlrev_b32_e32 v184, 16, v15
	v_and_b32_e32 v185, 0xffff0000, v15
	v_min_u32_e32 v14, v132, v227
	v_sub_u32_e64 v15, v228, 8 clamp
	v_sub_u32_e32 v14, v14, v15
	v_cvt_f32_i32_e32 v14, v14
	v_lshlrev_b32_e32 v186, 16, v16
	v_and_b32_e32 v187, 0xffff0000, v16
	v_lshlrev_b32_e32 v188, 16, v17
	v_div_scale_f32 v15, s[16:17], v14, v14, 1.0
	v_rcp_f32_e32 v16, v15
	v_and_b32_e32 v189, 0xffff0000, v17
	v_lshlrev_b32_e32 v162, 16, v18
	v_and_b32_e32 v163, 0xffff0000, v18
	v_fma_f32 v17, -v15, v16, 1.0
	v_fmac_f32_e32 v16, v17, v16
	v_div_scale_f32 v17, vcc, 1.0, v14, 1.0
	v_mul_f32_e32 v18, v17, v16
	v_lshlrev_b32_e32 v156, 16, v19
	v_and_b32_e32 v157, 0xffff0000, v19
	v_fma_f32 v19, -v15, v18, v17
	v_fmac_f32_e32 v18, v19, v16
	v_fma_f32 v15, -v15, v18, v17
	v_div_fmas_f32 v15, v15, v16, v18
	v_lshlrev_b32_e32 v154, 16, v20
	v_and_b32_e32 v155, 0xffff0000, v20
	v_lshlrev_b32_e32 v152, 16, v21
	v_and_b32_e32 v153, 0xffff0000, v21
	v_div_fixup_f32 v194, v15, v14, 1.0
	global_load_dwordx4 v[14:17], v[102:103], off offset:16
	global_load_dwordx4 v[18:21], v[102:103], off
	v_lshlrev_b32_e32 v196, 16, v58
	v_and_b32_e32 v197, 0xffff0000, v58
	v_lshlrev_b32_e32 v204, 16, v59
	v_and_b32_e32 v205, 0xffff0000, v59
	v_pk_add_f32 v[58:59], v[184:185], 0 op_sel_hi:[1,0]
	v_lshlrev_b32_e32 v190, 16, v3
	v_and_b32_e32 v191, 0xffff0000, v3
	v_lshlrev_b32_e32 v182, 16, v2
	v_and_b32_e32 v183, 0xffff0000, v2
	v_pk_add_f32 v[2:3], v[58:59], v[190:191]
	v_lshlrev_b32_e32 v180, 16, v67
	v_and_b32_e32 v181, 0xffff0000, v67
	v_lshlrev_b32_e32 v176, 16, v90
	v_and_b32_e32 v177, 0xffff0000, v90
	v_lshlrev_b32_e32 v174, 16, v91
	v_and_b32_e32 v175, 0xffff0000, v91
	v_pk_add_f32 v[90:91], v[178:179], 0 op_sel_hi:[1,0]
	v_pk_add_f32 v[2:3], v[2:3], v[180:181]
	v_lshlrev_b32_e32 v164, 16, v63
	v_and_b32_e32 v165, 0xffff0000, v63
	v_pk_add_f32 v[90:91], v[90:91], v[182:183]
	v_lshlrev_b32_e32 v168, 16, v66
	v_and_b32_e32 v169, 0xffff0000, v66
	v_pk_add_f32 v[2:3], v[2:3], v[164:165]
	v_lshlrev_b32_e32 v66, 16, v31
	v_and_b32_e32 v67, 0xffff0000, v31
	v_pk_add_f32 v[90:91], v[90:91], v[168:169]
	v_lshlrev_b32_e32 v144, 16, v62
	v_and_b32_e32 v145, 0xffff0000, v62
	v_pk_add_f32 v[2:3], v[2:3], v[66:67]
	v_lshlrev_b32_e32 v58, 16, v23
	v_and_b32_e32 v59, 0xffff0000, v23
	v_pk_add_f32 v[90:91], v[90:91], v[144:145]
	v_lshlrev_b32_e32 v136, 16, v30
	v_and_b32_e32 v137, 0xffff0000, v30
	v_lshlrev_b32_e32 v132, 16, v22
	v_and_b32_e32 v133, 0xffff0000, v22
	v_pk_add_f32 v[22:23], v[2:3], v[58:59]
	v_lshlrev_b32_e32 v2, 16, v47
	v_and_b32_e32 v3, 0xffff0000, v47
	v_pk_add_f32 v[90:91], v[90:91], v[136:137]
	v_pk_add_f32 v[22:23], v[22:23], v[2:3]
	v_lshlrev_b32_e32 v30, 16, v43
	v_and_b32_e32 v31, 0xffff0000, v43
	v_lshlrev_b32_e32 v172, 16, v92
	v_and_b32_e32 v173, 0xffff0000, v92
	v_lshlrev_b32_e32 v166, 16, v93
	v_and_b32_e32 v167, 0xffff0000, v93
	v_pk_add_f32 v[92:93], v[90:91], v[132:133]
	v_lshlrev_b32_e32 v90, 16, v46
	v_and_b32_e32 v91, 0xffff0000, v46
	v_pk_add_f32 v[22:23], v[22:23], v[30:31]
	v_pk_add_f32 v[30:31], v[186:187], 0 op_sel_hi:[1,0]
	v_lshlrev_b32_e32 v192, 16, v4
	v_and_b32_e32 v193, 0xffff0000, v4
	v_pk_add_f32 v[92:93], v[92:93], v[90:91]
	v_lshlrev_b32_e32 v134, 16, v42
	v_and_b32_e32 v135, 0xffff0000, v42
	s_waitcnt vmcnt(2)
	v_lshlrev_b32_e32 v202, 16, v94
	v_and_b32_e32 v203, 0xffff0000, v94
	v_lshlrev_b32_e32 v208, 16, v95
	v_and_b32_e32 v209, 0xffff0000, v95
	v_pk_add_f32 v[30:31], v[30:31], v[192:193]
	v_lshlrev_b32_e32 v94, 16, v68
	v_and_b32_e32 v95, 0xffff0000, v68
	v_pk_add_f32 v[92:93], v[92:93], v[134:135]
	v_lshlrev_b32_e32 v134, 16, v82
	v_and_b32_e32 v135, 0xffff0000, v82
	v_lshlrev_b32_e32 v46, 16, v83
	v_and_b32_e32 v47, 0xffff0000, v83
	v_pk_add_f32 v[30:31], v[30:31], v[94:95]
	v_lshlrev_b32_e32 v82, 16, v64
	v_and_b32_e32 v83, 0xffff0000, v64
	v_lshlrev_b32_e32 v160, 16, v69
	v_and_b32_e32 v161, 0xffff0000, v69
	v_pk_add_f32 v[30:31], v[30:31], v[82:83]
	v_lshlrev_b32_e32 v68, 16, v32
	v_and_b32_e32 v69, 0xffff0000, v32
	v_pk_add_f32 v[30:31], v[30:31], v[68:69]
	v_lshlrev_b32_e32 v62, 16, v24
	v_and_b32_e32 v63, 0xffff0000, v24
	v_pk_add_f32 v[42:43], v[30:31], v[62:63]
	v_lshlrev_b32_e32 v30, 16, v48
	v_and_b32_e32 v31, 0xffff0000, v48
	v_lshlrev_b32_e32 v140, 16, v65
	v_and_b32_e32 v141, 0xffff0000, v65
	v_pk_add_f32 v[42:43], v[42:43], v[30:31]
	v_lshlrev_b32_e32 v64, 16, v44
	v_and_b32_e32 v65, 0xffff0000, v44
	v_pk_add_f32 v[42:43], v[42:43], v[64:65]
	v_lshlrev_b32_e32 v64, 16, v84
	v_and_b32_e32 v65, 0xffff0000, v84
	v_lshl_add_u64 v[212:213], v[118:119], 0, v[198:199]
	v_lshlrev_b32_e32 v198, 16, v33
	v_and_b32_e32 v199, 0xffff0000, v33
	v_lshlrev_b32_e32 v32, 16, v49
	v_and_b32_e32 v33, 0xffff0000, v49
	v_lshlrev_b32_e32 v48, 16, v85
	v_and_b32_e32 v49, 0xffff0000, v85
	v_pk_add_f32 v[84:85], v[188:189], 0 op_sel_hi:[1,0]
	v_lshlrev_b32_e32 v4, 16, v5
	v_and_b32_e32 v5, 0xffff0000, v5
	v_pk_add_f32 v[84:85], v[84:85], v[4:5]
	v_lshlrev_b64 v[214:215], 11, v[142:143]
	v_pk_add_f32 v[84:85], v[84:85], v[160:161]
	v_lshlrev_b32_e32 v142, 16, v25
	v_pk_add_f32 v[84:85], v[84:85], v[140:141]
	v_and_b32_e32 v143, 0xffff0000, v25
	v_pk_add_f32 v[84:85], v[84:85], v[198:199]
	v_lshlrev_b32_e32 v210, 16, v60
	v_pk_add_f32 v[84:85], v[84:85], v[142:143]
	v_and_b32_e32 v211, 0xffff0000, v60
	v_lshlrev_b32_e32 v44, 16, v45
	v_and_b32_e32 v45, 0xffff0000, v45
	v_pk_add_f32 v[84:85], v[84:85], v[32:33]
	v_pk_add_f32 v[218:219], v[42:43], v[210:211]
	v_lshlrev_b32_e32 v42, 16, v88
	v_and_b32_e32 v43, 0xffff0000, v88
	v_lshlrev_b32_e32 v24, 16, v89
	v_and_b32_e32 v25, 0xffff0000, v89
	v_lshlrev_b32_e32 v88, 16, v61
	v_and_b32_e32 v89, 0xffff0000, v61
	v_pk_add_f32 v[44:45], v[84:85], v[44:45]
	v_lshlrev_b32_e32 v84, 16, v37
	v_pk_add_f32 v[44:45], v[44:45], v[88:89]
	v_and_b32_e32 v85, 0xffff0000, v37
	v_pk_add_f32 v[44:45], v[44:45], v[84:85]
	v_pk_add_f32 v[200:201], v[92:93], v[196:197]
	v_pk_add_f32 v[44:45], v[44:45], v[166:167]
	v_lshlrev_b32_e32 v92, 16, v86
	v_and_b32_e32 v93, 0xffff0000, v86
	v_pk_add_f32 v[206:207], v[22:23], v[204:205]
	v_lshlrev_b32_e32 v22, 16, v87
	v_and_b32_e32 v23, 0xffff0000, v87
	v_lshlrev_b32_e32 v86, 16, v80
	v_and_b32_e32 v87, 0xffff0000, v80
	v_lshlrev_b32_e32 v80, 16, v81
	v_and_b32_e32 v81, 0xffff0000, v81
	v_pk_add_f32 v[44:45], v[44:45], v[152:153]
	v_lshlrev_b32_e32 v60, 16, v77
	v_and_b32_e32 v61, 0xffff0000, v77
	v_pk_add_f32 v[44:45], v[44:45], v[80:81]
	v_lshlrev_b32_e32 v158, 16, v78
	v_pk_add_f32 v[44:45], v[44:45], v[60:61]
	v_and_b32_e32 v159, 0xffff0000, v78
	v_pk_add_f32 v[44:45], v[44:45], v[48:49]
	v_lshlrev_b32_e32 v170, 16, v79
	v_pk_add_f32 v[44:45], v[44:45], v[24:25]
	v_and_b32_e32 v171, 0xffff0000, v79
	v_pk_fma_f32 v[88:89], v[194:195], v[44:45], v[88:89] op_sel_hi:[0,1,1] neg_lo:[0,0,1] neg_hi:[0,0,1]
	v_lshlrev_b32_e32 v78, 16, v76
	v_and_b32_e32 v79, 0xffff0000, v76
	v_lshlrev_b32_e32 v76, 16, v97
	v_and_b32_e32 v77, 0xffff0000, v97
	s_waitcnt vmcnt(1)
	v_pk_mul_f32 v[88:89], v[88:89], v[16:17]
	v_lshlrev_b32_e32 v220, 16, v96
	v_pk_mul_f32 v[76:77], v[88:89], v[76:77]
	v_and_b32_e32 v221, 0xffff0000, v96
	v_cvt_pk_bf16_f32 v37, v76, v77
	v_lshlrev_b32_e32 v76, 16, v36
	v_and_b32_e32 v77, 0xffff0000, v36
	v_pk_add_f32 v[88:89], v[218:219], v[76:77]
	v_lshlrev_b32_e32 v138, 16, v74
	v_pk_add_f32 v[88:89], v[88:89], v[172:173]
	v_and_b32_e32 v139, 0xffff0000, v74
	v_pk_add_f32 v[88:89], v[88:89], v[154:155]
	v_lshlrev_b32_e32 v74, 16, v75
	v_pk_add_f32 v[88:89], v[88:89], v[86:87]
	v_and_b32_e32 v75, 0xffff0000, v75
	v_pk_add_f32 v[88:89], v[88:89], v[78:79]
	v_lshl_add_u64 v[216:217], v[116:117], 0, v[214:215]
	v_pk_add_f32 v[88:89], v[88:89], v[64:65]
	v_lshlrev_b64 v[130:131], 11, v[130:131]
	v_pk_add_f32 v[88:89], v[88:89], v[42:43]
	v_lshlrev_b64 v[128:129], 11, v[128:129]
	v_pk_fma_f32 v[96:97], v[194:195], v[88:89], v[210:211] op_sel_hi:[0,1,1] neg_lo:[0,0,1] neg_hi:[0,0,1]
	v_pk_mul_f32 v[96:97], v[96:97], v[14:15]
	s_nop 0
	v_pk_mul_f32 v[96:97], v[96:97], v[220:221]
	s_nop 0
	v_cvt_pk_bf16_f32 v36, v96, v97
	v_lshlrev_b32_e32 v96, 16, v35
	v_and_b32_e32 v97, 0xffff0000, v35
	v_pk_add_f32 v[206:207], v[206:207], v[96:97]
	s_nop 0
	v_pk_add_f32 v[206:207], v[206:207], v[174:175]
	s_nop 0
	v_pk_add_f32 v[206:207], v[206:207], v[156:157]
	s_nop 0
	v_pk_add_f32 v[206:207], v[206:207], v[170:171]
	s_nop 0
	v_pk_add_f32 v[206:207], v[206:207], v[74:75]
	s_nop 0
	v_pk_add_f32 v[206:207], v[206:207], v[46:47]
	s_nop 0
	v_pk_add_f32 v[206:207], v[206:207], v[22:23]
	s_nop 0
	v_pk_fma_f32 v[204:205], v[194:195], v[206:207], v[204:205] op_sel_hi:[0,1,1] neg_lo:[0,0,1] neg_hi:[0,0,1]
	s_waitcnt vmcnt(0)
	v_pk_mul_f32 v[204:205], v[204:205], v[20:21]
	s_nop 0
	v_pk_mul_f32 v[204:205], v[204:205], v[208:209]
	v_and_b32_e32 v209, 0xffff0000, v73
	v_cvt_pk_bf16_f32 v35, v204, v205
	v_lshlrev_b32_e32 v204, 16, v34
	v_and_b32_e32 v205, 0xffff0000, v34
	v_pk_add_f32 v[200:201], v[200:201], v[204:205]
	s_nop 0
	v_pk_add_f32 v[200:201], v[200:201], v[176:177]
	s_nop 0
	v_pk_add_f32 v[200:201], v[200:201], v[162:163]
	s_nop 0
	v_pk_add_f32 v[200:201], v[200:201], v[158:159]
	s_nop 0
	v_pk_add_f32 v[200:201], v[200:201], v[138:139]
	s_nop 0
	v_pk_add_f32 v[200:201], v[200:201], v[134:135]
	s_nop 0
	v_pk_add_f32 v[200:201], v[200:201], v[92:93]
	s_nop 0
	v_pk_fma_f32 v[196:197], v[194:195], v[200:201], v[196:197] op_sel_hi:[0,1,1] neg_lo:[0,0,1] neg_hi:[0,0,1]
	v_pk_mul_f32 v[196:197], v[196:197], v[18:19]
	v_min_u32_e32 v194, v241, v227
	v_pk_mul_f32 v[196:197], v[196:197], v[202:203]
	s_nop 0
	v_cvt_pk_bf16_f32 v34, v196, v197
	global_store_dwordx4 v[212:213], v[34:37], off offset:1536 sc1
	global_load_dwordx4 v[34:37], v[216:217], off offset:1536
	v_sub_u32_e64 v196, v235, 8 clamp
	v_sub_u32_e32 v194, v194, v196
	v_cvt_f32_i32_e32 v194, v194
	v_div_scale_f32 v196, s[16:17], v194, v194, 1.0
	v_rcp_f32_e32 v197, v196
	s_nop 0
	v_fma_f32 v202, -v196, v197, 1.0
	v_fmac_f32_e32 v197, v202, v197
	v_div_scale_f32 v202, vcc, 1.0, v194, 1.0
	v_mul_f32_e32 v203, v202, v197
	v_fma_f32 v208, -v196, v203, v202
	v_fmac_f32_e32 v203, v208, v197
	v_lshlrev_b32_e32 v208, 16, v73
	v_pk_add_f32 v[188:189], v[208:209], v[188:189] neg_lo:[0,1] neg_hi:[0,1]
	v_fma_f32 v196, -v196, v203, v202
	v_pk_add_f32 v[44:45], v[44:45], v[188:189]
	v_lshlrev_b32_e32 v188, 16, v72
	v_and_b32_e32 v189, 0xffff0000, v72
	v_pk_add_f32 v[72:73], v[188:189], v[186:187] neg_lo:[0,1] neg_hi:[0,1]
	v_div_fmas_f32 v196, v196, v197, v203
	v_pk_add_f32 v[72:73], v[88:89], v[72:73]
	v_lshlrev_b32_e32 v88, 16, v71
	v_and_b32_e32 v89, 0xffff0000, v71
	v_pk_add_f32 v[88:89], v[88:89], v[184:185] neg_lo:[0,1] neg_hi:[0,1]
	v_lshlrev_b32_e32 v184, 16, v70
	v_and_b32_e32 v185, 0xffff0000, v70
	v_pk_add_f32 v[70:71], v[184:185], v[178:179] neg_lo:[0,1] neg_hi:[0,1]
	v_div_fixup_f32 v194, v196, v194, 1.0
	v_pk_add_f32 v[88:89], v[206:207], v[88:89]
	v_pk_add_f32 v[70:71], v[200:201], v[70:71]
	v_pk_fma_f32 v[96:97], v[194:195], v[88:89], v[96:97] op_sel_hi:[0,1,1] neg_lo:[0,0,1] neg_hi:[0,0,1]
	v_pk_fma_f32 v[178:179], v[194:195], v[70:71], v[204:205] op_sel_hi:[0,1,1] neg_lo:[0,0,1] neg_hi:[0,0,1]
	v_pk_fma_f32 v[76:77], v[194:195], v[72:73], v[76:77] op_sel_hi:[0,1,1] neg_lo:[0,0,1] neg_hi:[0,0,1]
	v_pk_mul_f32 v[96:97], v[96:97], v[20:21]
	v_pk_mul_f32 v[178:179], v[178:179], v[18:19]
	v_pk_mul_f32 v[76:77], v[76:77], v[14:15]
	v_lshl_add_u64 v[196:197], v[118:119], 0, v[214:215]
	v_lshl_add_u64 v[202:203], v[116:117], 0, v[130:131]
	s_waitcnt vmcnt(0)
	v_lshlrev_b32_e32 v184, 16, v34
	v_and_b32_e32 v185, 0xffff0000, v34
	v_lshlrev_b32_e32 v186, 16, v35
	v_and_b32_e32 v187, 0xffff0000, v35
	v_lshlrev_b32_e32 v188, 16, v36
	v_and_b32_e32 v189, 0xffff0000, v36
	v_lshlrev_b32_e32 v200, 16, v37
	v_and_b32_e32 v201, 0xffff0000, v37
	v_pk_mul_f32 v[34:35], v[178:179], v[184:185]
	v_pk_mul_f32 v[36:37], v[96:97], v[186:187]
	v_cvt_pk_bf16_f32 v34, v34, v35
	v_cvt_pk_bf16_f32 v35, v36, v37
	v_pk_mul_f32 v[36:37], v[76:77], v[188:189]
	v_pk_fma_f32 v[76:77], v[194:195], v[44:45], v[84:85] op_sel_hi:[0,1,1] neg_lo:[0,0,1] neg_hi:[0,0,1]
	v_pk_mul_f32 v[76:77], v[76:77], v[16:17]
	v_cvt_pk_bf16_f32 v36, v36, v37
	v_pk_mul_f32 v[76:77], v[76:77], v[200:201]
	s_nop 0
	v_cvt_pk_bf16_f32 v37, v76, v77
	global_store_dwordx4 v[196:197], v[34:37], off offset:1536 sc1
	global_load_dwordx4 v[34:37], v[202:203], off offset:1536
	v_min_u32_e32 v76, v240, v227
	v_sub_u32_e64 v77, v234, 8 clamp
	v_sub_u32_e32 v76, v76, v77
	v_cvt_f32_i32_e32 v84, v76
	v_lshlrev_b32_e32 v76, 16, v57
	v_and_b32_e32 v77, 0xffff0000, v57
	v_pk_add_f32 v[4:5], v[76:77], v[4:5] neg_lo:[0,1] neg_hi:[0,1]
	v_div_scale_f32 v85, s[16:17], v84, v84, 1.0
	v_rcp_f32_e32 v96, v85
	v_pk_add_f32 v[4:5], v[44:45], v[4:5]
	v_lshlrev_b32_e32 v44, 16, v54
	v_and_b32_e32 v45, 0xffff0000, v54
	v_fma_f32 v57, -v85, v96, 1.0
	v_fmac_f32_e32 v96, v57, v96
	v_div_scale_f32 v57, vcc, 1.0, v84, 1.0
	v_mul_f32_e32 v97, v57, v96
	v_fma_f32 v178, -v85, v97, v57
	v_fmac_f32_e32 v97, v178, v96
	v_fma_f32 v57, -v85, v97, v57
	v_div_fmas_f32 v57, v57, v96, v97
	v_pk_add_f32 v[44:45], v[44:45], v[182:183] neg_lo:[0,1] neg_hi:[0,1]
	v_div_fixup_f32 v84, v57, v84, 1.0
	v_pk_add_f32 v[44:45], v[70:71], v[44:45]
	v_lshlrev_b32_e32 v54, 16, v55
	v_pk_fma_f32 v[70:71], v[84:85], v[44:45], v[176:177] op_sel_hi:[0,1,1] neg_lo:[0,0,1] neg_hi:[0,0,1]
	v_and_b32_e32 v55, 0xffff0000, v55
	v_pk_mul_f32 v[70:71], v[70:71], v[18:19]
	v_pk_add_f32 v[54:55], v[54:55], v[190:191] neg_lo:[0,1] neg_hi:[0,1]
	v_lshl_add_u64 v[96:97], v[118:119], 0, v[130:131]
	v_pk_add_f32 v[54:55], v[88:89], v[54:55]
	v_lshl_add_u64 v[130:131], v[116:117], 0, v[128:129]
	s_waitcnt vmcnt(0)
	v_lshlrev_b32_e32 v76, 16, v34
	v_and_b32_e32 v77, 0xffff0000, v34
	v_pk_mul_f32 v[70:71], v[70:71], v[76:77]
	v_lshlrev_b32_e32 v76, 16, v35
	v_cvt_pk_bf16_f32 v34, v70, v71
	v_pk_fma_f32 v[70:71], v[84:85], v[54:55], v[174:175] op_sel_hi:[0,1,1] neg_lo:[0,0,1] neg_hi:[0,0,1]
	v_pk_mul_f32 v[70:71], v[70:71], v[20:21]
	v_and_b32_e32 v77, 0xffff0000, v35
	v_pk_mul_f32 v[70:71], v[70:71], v[76:77]
	s_nop 0
	v_cvt_pk_bf16_f32 v35, v70, v71
	v_lshlrev_b32_e32 v70, 16, v56
	v_and_b32_e32 v71, 0xffff0000, v56
	v_pk_add_f32 v[56:57], v[70:71], v[192:193] neg_lo:[0,1] neg_hi:[0,1]
	s_nop 0
	v_pk_add_f32 v[56:57], v[72:73], v[56:57]
	v_lshlrev_b32_e32 v72, 16, v36
	v_pk_fma_f32 v[70:71], v[84:85], v[56:57], v[172:173] op_sel_hi:[0,1,1] neg_lo:[0,0,1] neg_hi:[0,0,1]
	v_pk_mul_f32 v[70:71], v[70:71], v[14:15]
	v_and_b32_e32 v73, 0xffff0000, v36
	v_pk_mul_f32 v[70:71], v[70:71], v[72:73]
	v_pk_fma_f32 v[72:73], v[84:85], v[4:5], v[166:167] op_sel_hi:[0,1,1] neg_lo:[0,0,1] neg_hi:[0,0,1]
	v_cvt_pk_bf16_f32 v36, v70, v71
	v_lshlrev_b32_e32 v70, 16, v37
	v_and_b32_e32 v71, 0xffff0000, v37
	v_pk_mul_f32 v[72:73], v[72:73], v[16:17]
	s_nop 0
	v_pk_mul_f32 v[70:71], v[72:73], v[70:71]
	s_nop 0
	v_cvt_pk_bf16_f32 v37, v70, v71
	global_store_dwordx4 v[96:97], v[34:37], off offset:1536 sc1
	global_load_dwordx4 v[34:37], v[130:131], off offset:1536
	v_min_u32_e32 v70, v239, v227
	v_sub_u32_e64 v71, v233, 8 clamp
	v_sub_u32_e32 v70, v70, v71
	v_cvt_f32_i32_e32 v72, v70
	v_lshlrev_b32_e32 v70, 16, v53
	v_and_b32_e32 v71, 0xffff0000, v53
	v_pk_add_f32 v[70:71], v[70:71], v[160:161] neg_lo:[0,1] neg_hi:[0,1]
	v_div_scale_f32 v73, s[16:17], v72, v72, 1.0
	v_rcp_f32_e32 v76, v73
	v_pk_add_f32 v[4:5], v[4:5], v[70:71]
	v_lshlrev_b32_e32 v70, 16, v50
	v_and_b32_e32 v71, 0xffff0000, v50
	v_fma_f32 v53, -v73, v76, 1.0
	v_fmac_f32_e32 v76, v53, v76
	v_div_scale_f32 v53, vcc, 1.0, v72, 1.0
	v_mul_f32_e32 v77, v53, v76
	v_fma_f32 v84, -v73, v77, v53
	v_fmac_f32_e32 v77, v84, v76
	v_fma_f32 v53, -v73, v77, v53
	v_div_fmas_f32 v53, v53, v76, v77
	v_pk_add_f32 v[70:71], v[70:71], v[168:169] neg_lo:[0,1] neg_hi:[0,1]
	v_div_fixup_f32 v72, v53, v72, 1.0
	v_pk_add_f32 v[44:45], v[44:45], v[70:71]
	v_lshlrev_b32_e32 v50, 16, v51
	v_and_b32_e32 v51, 0xffff0000, v51
	v_pk_fma_f32 v[70:71], v[72:73], v[44:45], v[162:163] op_sel_hi:[0,1,1] neg_lo:[0,0,1] neg_hi:[0,0,1]
	v_pk_add_f32 v[50:51], v[50:51], v[180:181] neg_lo:[0,1] neg_hi:[0,1]
	v_pk_mul_f32 v[70:71], v[70:71], v[18:19]
	v_pk_add_f32 v[50:51], v[54:55], v[50:51]
	v_lshl_add_u64 v[76:77], v[118:119], 0, v[128:129]
	v_pk_fma_f32 v[54:55], v[72:73], v[50:51], v[156:157] op_sel_hi:[0,1,1] neg_lo:[0,0,1] neg_hi:[0,0,1]
	v_pk_mul_f32 v[54:55], v[54:55], v[20:21]
	v_lshlrev_b64 v[84:85], 11, v[126:127]
	v_lshl_add_u64 v[88:89], v[116:117], 0, v[84:85]
	s_waitcnt vmcnt(0)
	v_lshlrev_b32_e32 v96, 16, v34
	v_and_b32_e32 v97, 0xffff0000, v34
	v_pk_mul_f32 v[70:71], v[70:71], v[96:97]
	s_nop 0
	v_cvt_pk_bf16_f32 v34, v70, v71
	v_lshlrev_b32_e32 v70, 16, v35
	v_and_b32_e32 v71, 0xffff0000, v35
	v_pk_mul_f32 v[54:55], v[54:55], v[70:71]
	s_nop 0
	v_cvt_pk_bf16_f32 v35, v54, v55
	v_lshlrev_b32_e32 v54, 16, v52
	v_and_b32_e32 v55, 0xffff0000, v52
	v_pk_add_f32 v[52:53], v[54:55], v[94:95] neg_lo:[0,1] neg_hi:[0,1]
	s_nop 0
	v_pk_add_f32 v[52:53], v[56:57], v[52:53]
	v_lshlrev_b32_e32 v56, 16, v36
	v_pk_fma_f32 v[54:55], v[72:73], v[52:53], v[154:155] op_sel_hi:[0,1,1] neg_lo:[0,0,1] neg_hi:[0,0,1]
	v_pk_mul_f32 v[54:55], v[54:55], v[14:15]
	v_and_b32_e32 v57, 0xffff0000, v36
	v_pk_mul_f32 v[54:55], v[54:55], v[56:57]
	v_pk_fma_f32 v[56:57], v[72:73], v[4:5], v[152:153] op_sel_hi:[0,1,1] neg_lo:[0,0,1] neg_hi:[0,0,1]
	v_cvt_pk_bf16_f32 v36, v54, v55
	v_lshlrev_b32_e32 v54, 16, v37
	v_and_b32_e32 v55, 0xffff0000, v37
	v_pk_mul_f32 v[56:57], v[56:57], v[16:17]
	s_nop 0
	v_pk_mul_f32 v[54:55], v[56:57], v[54:55]
	s_nop 0
	v_cvt_pk_bf16_f32 v37, v54, v55
	global_store_dwordx4 v[76:77], v[34:37], off offset:1536 sc1
	global_load_dwordx4 v[34:37], v[88:89], off offset:1536
	v_min_u32_e32 v54, v238, v227
	v_sub_u32_e64 v55, v232, 8 clamp
	v_sub_u32_e32 v54, v54, v55
	v_cvt_f32_i32_e32 v56, v54
	v_lshlrev_b32_e32 v54, 16, v41
	v_and_b32_e32 v55, 0xffff0000, v41
	v_pk_add_f32 v[54:55], v[54:55], v[140:141] neg_lo:[0,1] neg_hi:[0,1]
	v_div_scale_f32 v57, s[16:17], v56, v56, 1.0
	v_rcp_f32_e32 v70, v57
	v_pk_add_f32 v[4:5], v[4:5], v[54:55]
	v_lshlrev_b32_e32 v54, 16, v38
	v_and_b32_e32 v55, 0xffff0000, v38
	v_fma_f32 v41, -v57, v70, 1.0
	v_fmac_f32_e32 v70, v41, v70
	v_div_scale_f32 v41, vcc, 1.0, v56, 1.0
	v_mul_f32_e32 v71, v41, v70
	v_fma_f32 v72, -v57, v71, v41
	v_fmac_f32_e32 v71, v72, v70
	v_fma_f32 v41, -v57, v71, v41
	v_div_fmas_f32 v41, v41, v70, v71
	v_pk_add_f32 v[54:55], v[54:55], v[144:145] neg_lo:[0,1] neg_hi:[0,1]
	v_div_fixup_f32 v56, v41, v56, 1.0
	v_pk_add_f32 v[44:45], v[44:45], v[54:55]
	v_lshlrev_b32_e32 v38, 16, v39
	v_and_b32_e32 v39, 0xffff0000, v39
	v_pk_fma_f32 v[54:55], v[56:57], v[44:45], v[158:159] op_sel_hi:[0,1,1] neg_lo:[0,0,1] neg_hi:[0,0,1]
	v_pk_add_f32 v[38:39], v[38:39], v[164:165] neg_lo:[0,1] neg_hi:[0,1]
	v_lshl_add_u64 v[70:71], v[118:119], 0, v[84:85]
	v_pk_mul_f32 v[54:55], v[54:55], v[18:19]
	v_pk_add_f32 v[38:39], v[50:51], v[38:39]
	v_lshlrev_b64 v[72:73], 11, v[124:125]
	v_pk_fma_f32 v[50:51], v[56:57], v[38:39], v[170:171] op_sel_hi:[0,1,1] neg_lo:[0,0,1] neg_hi:[0,0,1]
	v_pk_mul_f32 v[50:51], v[50:51], v[20:21]
	v_lshl_add_u64 v[76:77], v[116:117], 0, v[72:73]
	s_waitcnt vmcnt(0)
	v_lshlrev_b32_e32 v84, 16, v34
	v_and_b32_e32 v85, 0xffff0000, v34
	v_pk_mul_f32 v[54:55], v[54:55], v[84:85]
	s_nop 0
	v_cvt_pk_bf16_f32 v34, v54, v55
	v_lshlrev_b32_e32 v54, 16, v35
	v_and_b32_e32 v55, 0xffff0000, v35
	v_pk_mul_f32 v[50:51], v[50:51], v[54:55]
	s_nop 0
	v_cvt_pk_bf16_f32 v35, v50, v51
	v_lshlrev_b32_e32 v50, 16, v40
	v_and_b32_e32 v51, 0xffff0000, v40
	v_pk_add_f32 v[40:41], v[50:51], v[82:83] neg_lo:[0,1] neg_hi:[0,1]
	s_nop 0
	v_pk_add_f32 v[40:41], v[52:53], v[40:41]
	v_lshlrev_b32_e32 v52, 16, v36
	v_pk_fma_f32 v[50:51], v[56:57], v[40:41], v[86:87] op_sel_hi:[0,1,1] neg_lo:[0,0,1] neg_hi:[0,0,1]
	v_pk_mul_f32 v[50:51], v[50:51], v[14:15]
	v_and_b32_e32 v53, 0xffff0000, v36
	v_pk_mul_f32 v[50:51], v[50:51], v[52:53]
	v_pk_fma_f32 v[52:53], v[56:57], v[4:5], v[80:81] op_sel_hi:[0,1,1] neg_lo:[0,0,1] neg_hi:[0,0,1]
	v_cvt_pk_bf16_f32 v36, v50, v51
	v_lshlrev_b32_e32 v50, 16, v37
	v_and_b32_e32 v51, 0xffff0000, v37
	v_pk_mul_f32 v[52:53], v[52:53], v[16:17]
	s_nop 0
	v_pk_mul_f32 v[50:51], v[52:53], v[50:51]
	s_nop 0
	v_cvt_pk_bf16_f32 v37, v50, v51
	global_store_dwordx4 v[70:71], v[34:37], off offset:1536 sc1
	global_load_dwordx4 v[34:37], v[76:77], off offset:1536
	v_min_u32_e32 v50, v237, v227
	v_sub_u32_e64 v51, v231, 8 clamp
	v_sub_u32_e32 v50, v50, v51
	v_cvt_f32_i32_e32 v50, v50
	v_lshlrev_b32_e32 v70, 16, v29
	v_and_b32_e32 v71, 0xffff0000, v29
	v_pk_add_f32 v[70:71], v[70:71], v[198:199] neg_lo:[0,1] neg_hi:[0,1]
	v_div_scale_f32 v51, s[16:17], v50, v50, 1.0
	v_rcp_f32_e32 v52, v51
	v_pk_add_f32 v[4:5], v[4:5], v[70:71]
	v_lshlrev_b32_e32 v70, 16, v26
	v_and_b32_e32 v71, 0xffff0000, v26
	v_fma_f32 v53, -v51, v52, 1.0
	v_fmac_f32_e32 v52, v53, v52
	v_div_scale_f32 v53, vcc, 1.0, v50, 1.0
	v_mul_f32_e32 v54, v53, v52
	v_fma_f32 v55, -v51, v54, v53
	v_fmac_f32_e32 v54, v55, v52
	v_fma_f32 v51, -v51, v54, v53
	v_div_fmas_f32 v51, v51, v52, v54
	v_pk_add_f32 v[70:71], v[70:71], v[136:137] neg_lo:[0,1] neg_hi:[0,1]
	v_div_fixup_f32 v50, v51, v50, 1.0
	v_pk_add_f32 v[44:45], v[44:45], v[70:71]
	v_lshl_add_u64 v[52:53], v[118:119], 0, v[72:73]
	v_pk_fma_f32 v[70:71], v[50:51], v[44:45], v[138:139] op_sel_hi:[0,1,1] neg_lo:[0,0,1] neg_hi:[0,0,1]
	v_pk_mul_f32 v[70:71], v[70:71], v[18:19]
	v_lshlrev_b64 v[54:55], 11, v[122:123]
	v_lshl_add_u64 v[56:57], v[116:117], 0, v[54:55]
	s_waitcnt vmcnt(0)
	v_lshlrev_b32_e32 v72, 16, v34
	v_and_b32_e32 v73, 0xffff0000, v34
	v_pk_mul_f32 v[70:71], v[70:71], v[72:73]
	v_lshlrev_b32_e32 v34, 16, v35
	v_cvt_pk_bf16_f32 v26, v70, v71
	v_lshlrev_b32_e32 v70, 16, v27
	v_and_b32_e32 v71, 0xffff0000, v27
	v_pk_add_f32 v[66:67], v[70:71], v[66:67] neg_lo:[0,1] neg_hi:[0,1]
	v_and_b32_e32 v35, 0xffff0000, v35
	v_pk_add_f32 v[38:39], v[38:39], v[66:67]
	s_nop 0
	v_pk_fma_f32 v[66:67], v[50:51], v[38:39], v[74:75] op_sel_hi:[0,1,1] neg_lo:[0,0,1] neg_hi:[0,0,1]
	v_pk_mul_f32 v[66:67], v[66:67], v[20:21]
	s_nop 0
	v_pk_mul_f32 v[34:35], v[66:67], v[34:35]
	s_nop 0
	v_cvt_pk_bf16_f32 v27, v34, v35
	v_lshlrev_b32_e32 v34, 16, v28
	v_and_b32_e32 v35, 0xffff0000, v28
	v_pk_add_f32 v[28:29], v[34:35], v[68:69] neg_lo:[0,1] neg_hi:[0,1]
	s_nop 0
	v_pk_add_f32 v[34:35], v[40:41], v[28:29]
	v_lshlrev_b32_e32 v40, 16, v36
	v_pk_fma_f32 v[28:29], v[50:51], v[34:35], v[78:79] op_sel_hi:[0,1,1] neg_lo:[0,0,1] neg_hi:[0,0,1]
	v_pk_mul_f32 v[28:29], v[28:29], v[14:15]
	v_and_b32_e32 v41, 0xffff0000, v36
	v_pk_mul_f32 v[28:29], v[28:29], v[40:41]
	v_pk_fma_f32 v[40:41], v[50:51], v[4:5], v[60:61] op_sel_hi:[0,1,1] neg_lo:[0,0,1] neg_hi:[0,0,1]
	v_lshlrev_b32_e32 v36, 16, v37
	v_and_b32_e32 v37, 0xffff0000, v37
	v_pk_mul_f32 v[40:41], v[40:41], v[16:17]
	v_cvt_pk_bf16_f32 v28, v28, v29
	v_pk_mul_f32 v[36:37], v[40:41], v[36:37]
	s_nop 0
	v_cvt_pk_bf16_f32 v29, v36, v37
	global_store_dwordx4 v[52:53], v[26:29], off offset:1536 sc1
	global_load_dwordx4 v[26:29], v[56:57], off offset:1536
	v_min_u32_e32 v36, v236, v227
	v_sub_u32_e64 v37, v230, 8 clamp
	v_sub_u32_e32 v36, v36, v37
	v_cvt_f32_i32_e32 v36, v36
	v_lshlrev_b32_e32 v52, 16, v13
	v_and_b32_e32 v53, 0xffff0000, v13
	v_pk_add_f32 v[52:53], v[52:53], v[142:143] neg_lo:[0,1] neg_hi:[0,1]
	v_div_scale_f32 v37, s[16:17], v36, v36, 1.0
	v_rcp_f32_e32 v40, v37
	v_pk_add_f32 v[4:5], v[4:5], v[52:53]
	v_lshlrev_b32_e32 v52, 16, v10
	v_and_b32_e32 v53, 0xffff0000, v10
	v_fma_f32 v41, -v37, v40, 1.0
	v_fmac_f32_e32 v40, v41, v40
	v_div_scale_f32 v41, vcc, 1.0, v36, 1.0
	v_mul_f32_e32 v50, v41, v40
	v_fma_f32 v51, -v37, v50, v41
	v_fmac_f32_e32 v50, v51, v40
	v_fma_f32 v37, -v37, v50, v41
	v_div_fmas_f32 v37, v37, v40, v50
	v_pk_add_f32 v[52:53], v[52:53], v[132:133] neg_lo:[0,1] neg_hi:[0,1]
	v_div_fixup_f32 v36, v37, v36, 1.0
	v_pk_add_f32 v[44:45], v[44:45], v[52:53]
	v_lshl_add_u64 v[40:41], v[118:119], 0, v[54:55]
	v_pk_fma_f32 v[52:53], v[36:37], v[44:45], v[134:135] op_sel_hi:[0,1,1] neg_lo:[0,0,1] neg_hi:[0,0,1]
	v_pk_mul_f32 v[52:53], v[52:53], v[18:19]
	v_lshlrev_b64 v[50:51], 11, v[120:121]
	v_lshl_add_u64 v[50:51], v[116:117], 0, v[50:51]
	s_waitcnt vmcnt(0)
	v_lshlrev_b32_e32 v54, 16, v26
	v_and_b32_e32 v55, 0xffff0000, v26
	v_pk_mul_f32 v[52:53], v[52:53], v[54:55]
	v_lshlrev_b32_e32 v26, 16, v27
	v_cvt_pk_bf16_f32 v10, v52, v53
	v_lshlrev_b32_e32 v52, 16, v11
	v_and_b32_e32 v53, 0xffff0000, v11
	v_pk_add_f32 v[52:53], v[52:53], v[58:59] neg_lo:[0,1] neg_hi:[0,1]
	v_and_b32_e32 v27, 0xffff0000, v27
	v_pk_add_f32 v[38:39], v[38:39], v[52:53]
	s_nop 0
	v_pk_fma_f32 v[46:47], v[36:37], v[38:39], v[46:47] op_sel_hi:[0,1,1] neg_lo:[0,0,1] neg_hi:[0,0,1]
	v_pk_mul_f32 v[46:47], v[46:47], v[20:21]
	s_nop 0
	v_pk_mul_f32 v[26:27], v[46:47], v[26:27]
	v_add_u32_e32 v46, 15, v228
	v_cvt_pk_bf16_f32 v11, v26, v27
	v_lshlrev_b32_e32 v26, 16, v12
	v_and_b32_e32 v27, 0xffff0000, v12
	v_pk_add_f32 v[12:13], v[26:27], v[62:63] neg_lo:[0,1] neg_hi:[0,1]
	v_lshlrev_b32_e32 v26, 16, v28
	v_pk_add_f32 v[34:35], v[34:35], v[12:13]
	v_and_b32_e32 v27, 0xffff0000, v28
	v_pk_fma_f32 v[12:13], v[36:37], v[34:35], v[64:65] op_sel_hi:[0,1,1] neg_lo:[0,0,1] neg_hi:[0,0,1]
	v_pk_mul_f32 v[12:13], v[12:13], v[14:15]
	v_sub_u32_e64 v47, v229, 8 clamp
	v_pk_mul_f32 v[12:13], v[12:13], v[26:27]
	v_lshlrev_b32_e32 v26, 16, v29
	v_and_b32_e32 v27, 0xffff0000, v29
	v_pk_fma_f32 v[28:29], v[36:37], v[4:5], v[48:49] op_sel_hi:[0,1,1] neg_lo:[0,0,1] neg_hi:[0,0,1]
	v_pk_mul_f32 v[28:29], v[28:29], v[16:17]
	v_cvt_pk_bf16_f32 v12, v12, v13
	v_pk_mul_f32 v[26:27], v[28:29], v[26:27]
	v_lshlrev_b32_e32 v28, 16, v9
	v_cvt_pk_bf16_f32 v13, v26, v27
	global_store_dwordx4 v[40:41], v[10:13], off offset:1536 sc1
	global_load_dwordx4 v[10:13], v[50:51], off offset:1536
	v_and_b32_e32 v29, 0xffff0000, v9
	v_min_u32_e32 v46, v46, v227
	v_lshlrev_b32_e32 v40, 16, v8
	v_and_b32_e32 v41, 0xffff0000, v8
	v_pk_add_f32 v[8:9], v[28:29], v[32:33] neg_lo:[0,1] neg_hi:[0,1]
	v_sub_u32_e32 v28, v46, v47
	v_cvt_f32_i32_e32 v32, v28
	v_lshlrev_b32_e32 v36, 16, v6
	v_and_b32_e32 v37, 0xffff0000, v6
	v_pk_add_f32 v[28:29], v[36:37], v[90:91] neg_lo:[0,1] neg_hi:[0,1]
	v_div_scale_f32 v33, s[16:17], v32, v32, 1.0
	v_rcp_f32_e32 v36, v33
	v_lshlrev_b32_e32 v6, 16, v7
	v_and_b32_e32 v7, 0xffff0000, v7
	v_pk_add_f32 v[2:3], v[6:7], v[2:3] neg_lo:[0,1] neg_hi:[0,1]
	v_pk_add_f32 v[6:7], v[40:41], v[30:31] neg_lo:[0,1] neg_hi:[0,1]
	v_fma_f32 v31, -v33, v36, 1.0
	v_div_scale_f32 v30, vcc, 1.0, v32, 1.0
	v_fmac_f32_e32 v36, v31, v36
	v_mul_f32_e32 v31, v30, v36
	v_fma_f32 v37, -v33, v31, v30
	v_fmac_f32_e32 v31, v37, v36
	v_fma_f32 v30, -v33, v31, v30
	v_pk_add_f32 v[8:9], v[4:5], v[8:9]
	v_pk_add_f32 v[4:5], v[44:45], v[28:29]
	v_div_fmas_f32 v28, v30, v36, v31
	v_pk_add_f32 v[2:3], v[38:39], v[2:3]
	v_div_fixup_f32 v28, v28, v32, 1.0
	v_pk_fma_f32 v[4:5], v[28:29], v[4:5], v[92:93] op_sel_hi:[0,1,1] neg_lo:[0,0,1] neg_hi:[0,0,1]
	v_pk_fma_f32 v[2:3], v[28:29], v[2:3], v[22:23] op_sel_hi:[0,1,1] neg_lo:[0,0,1] neg_hi:[0,0,1]
	v_pk_add_f32 v[6:7], v[34:35], v[6:7]
	v_pk_mul_f32 v[4:5], v[18:19], v[4:5]
	v_pk_mul_f32 v[2:3], v[20:21], v[2:3]
	v_pk_fma_f32 v[6:7], v[28:29], v[6:7], v[42:43] op_sel_hi:[0,1,1] neg_lo:[0,0,1] neg_hi:[0,0,1]
	v_lshlrev_b64 v[26:27], 10, v[120:121]
	s_waitcnt vmcnt(0)
	v_lshlrev_b32_e32 v20, 16, v10
	v_and_b32_e32 v21, 0xffff0000, v10
	v_lshlrev_b32_e32 v10, 16, v11
	v_and_b32_e32 v11, 0xffff0000, v11
	v_pk_mul_f32 v[4:5], v[4:5], v[20:21]
	v_pk_mul_f32 v[10:11], v[2:3], v[10:11]
	v_cvt_pk_bf16_f32 v2, v4, v5
	v_pk_mul_f32 v[4:5], v[14:15], v[6:7]
	v_lshlrev_b32_e32 v6, 16, v12
	v_and_b32_e32 v7, 0xffff0000, v12
	v_pk_mul_f32 v[4:5], v[4:5], v[6:7]
	v_pk_fma_f32 v[6:7], v[28:29], v[8:9], v[24:25] op_sel_hi:[0,1,1] neg_lo:[0,0,1] neg_hi:[0,0,1]
	v_lshlrev_b32_e32 v18, 16, v13
	v_and_b32_e32 v19, 0xffff0000, v13
	v_pk_mul_f32 v[6:7], v[16:17], v[6:7]
	v_cvt_pk_bf16_f32 v3, v10, v11
	v_cvt_pk_bf16_f32 v4, v4, v5
	v_pk_mul_f32 v[6:7], v[6:7], v[18:19]

.LBB0_2229:
	s_or_b64 exec, exec, s[16:17]
	v_add_u32_e32 v62, v228, v94
	v_ashrrev_i32_e32 v63, 31, v62
	v_lshlrev_b64 v[142:143], 11, v[62:63]
	v_lshl_add_u64 v[62:63], v[116:117], 0, v[142:143]
	global_load_dwordx4 v[62:65], v[62:63], off offset:1024
	s_waitcnt vmcnt(1)
	v_lshlrev_b32_e32 v136, 16, v10
	v_and_b32_e32 v137, 0xffff0000, v10
	v_lshlrev_b32_e32 v134, 16, v11
	v_and_b32_e32 v135, 0xffff0000, v11
	v_lshlrev_b32_e32 v132, 16, v12
	v_and_b32_e32 v133, 0xffff0000, v12
	v_lshlrev_b32_e32 v138, 16, v13
	v_and_b32_e32 v139, 0xffff0000, v13
	global_load_dwordx4 v[10:13], v[106:107], off offset:16
	v_lshlrev_b32_e32 v84, 16, v14
	v_and_b32_e32 v85, 0xffff0000, v14
	v_lshlrev_b32_e32 v88, 16, v15
	v_and_b32_e32 v89, 0xffff0000, v15
	v_lshlrev_b32_e32 v86, 16, v16
	v_and_b32_e32 v87, 0xffff0000, v16
	v_lshlrev_b32_e32 v90, 16, v17
	v_and_b32_e32 v91, 0xffff0000, v17
	global_load_dwordx4 v[14:17], v[106:107], off
	v_lshlrev_b32_e32 v124, 16, v29
	v_and_b32_e32 v125, 0xffff0000, v29
	v_min_u32_e32 v29, v161, v227
	v_sub_u32_e64 v144, v228, 4 clamp
	v_sub_u32_e32 v29, v29, v144
	v_cvt_f32_i32_e32 v29, v29
	v_lshlrev_b32_e32 v122, 16, v50
	v_and_b32_e32 v123, 0xffff0000, v50
	v_lshlrev_b32_e32 v126, 16, v51
	v_and_b32_e32 v127, 0xffff0000, v51
	v_lshlrev_b32_e32 v50, 16, v44
	v_and_b32_e32 v51, 0xffff0000, v44
	v_div_scale_f32 v44, s[16:17], v29, v29, 1.0
	v_lshlrev_b32_e32 v94, 16, v58
	v_and_b32_e32 v95, 0xffff0000, v58
	v_lshlrev_b32_e32 v96, 16, v59
	v_and_b32_e32 v97, 0xffff0000, v59
	v_lshlrev_b32_e32 v92, 16, v60
	v_and_b32_e32 v93, 0xffff0000, v60
	v_lshlrev_b32_e32 v120, 16, v61
	v_and_b32_e32 v121, 0xffff0000, v61
	v_lshlrev_b32_e32 v60, 16, v42
	v_and_b32_e32 v61, 0xffff0000, v42
	v_lshlrev_b32_e32 v58, 16, v54
	v_and_b32_e32 v59, 0xffff0000, v54
	v_lshlrev_b32_e32 v74, 16, v43
	v_and_b32_e32 v75, 0xffff0000, v43
	v_lshlrev_b32_e32 v42, 16, v55
	v_and_b32_e32 v43, 0xffff0000, v55
	v_lshlrev_b32_e32 v54, 16, v48
	v_and_b32_e32 v55, 0xffff0000, v48
	v_rcp_f32_e32 v48, v44
	v_lshlrev_b32_e32 v78, 16, v46
	v_and_b32_e32 v79, 0xffff0000, v46
	v_lshlrev_b32_e32 v82, 16, v47
	v_and_b32_e32 v83, 0xffff0000, v47
	v_lshlrev_b32_e32 v46, 16, v56
	v_and_b32_e32 v47, 0xffff0000, v56
	v_fma_f32 v56, -v44, v48, 1.0
	v_lshlrev_b32_e32 v128, 16, v52
	v_and_b32_e32 v129, 0xffff0000, v52
	v_div_scale_f32 v52, vcc, 1.0, v29, 1.0
	v_fmac_f32_e32 v48, v56, v48
	v_pk_add_f32 v[170:171], v[138:139], 0 op_sel_hi:[1,0]
	v_mul_f32_e32 v56, v52, v48
	v_fma_f32 v144, -v44, v56, v52
	v_pk_add_f32 v[170:171], v[170:171], v[124:125]
	v_fmac_f32_e32 v56, v144, v48
	v_pk_add_f32 v[170:171], v[170:171], v[120:121]
	v_fma_f32 v44, -v44, v56, v52
	v_pk_add_f32 v[170:171], v[170:171], v[90:91]
	v_div_fmas_f32 v44, v44, v48, v56
	v_lshlrev_b32_e32 v48, 16, v45
	v_div_fixup_f32 v56, v44, v29, 1.0
	v_lshlrev_b32_e32 v44, 16, v57
	v_lshlrev_b32_e32 v52, 16, v53
	v_and_b32_e32 v53, 0xffff0000, v53
	v_pk_add_f32 v[168:169], v[132:133], 0 op_sel_hi:[1,0]
	v_pk_add_f32 v[154:155], v[134:135], 0 op_sel_hi:[1,0]
	s_waitcnt vmcnt(2)
	v_lshlrev_b32_e32 v144, 16, v62
	v_and_b32_e32 v145, 0xffff0000, v62
	v_lshlrev_b32_e32 v156, 16, v63
	v_and_b32_e32 v157, 0xffff0000, v63
	v_lshlrev_b32_e32 v62, 16, v49
	v_and_b32_e32 v63, 0xffff0000, v49
	v_and_b32_e32 v49, 0xffff0000, v45
	v_pk_add_f32 v[170:171], v[170:171], v[62:63]
	v_and_b32_e32 v45, 0xffff0000, v57
	v_pk_add_f32 v[170:171], v[170:171], v[48:49]
	v_lshlrev_b32_e32 v172, 16, v64
	v_pk_add_f32 v[170:171], v[170:171], v[44:45]
	v_and_b32_e32 v173, 0xffff0000, v64
	v_pk_add_f32 v[170:171], v[170:171], v[52:53]
	v_lshlrev_b32_e32 v64, 16, v65
	v_pk_fma_f32 v[174:175], v[56:57], v[170:171], v[62:63] op_sel_hi:[0,1,1] neg_lo:[0,0,1] neg_hi:[0,0,1]
	v_and_b32_e32 v65, 0xffff0000, v65
	s_waitcnt vmcnt(1)
	v_pk_mul_f32 v[174:175], v[174:175], v[12:13]
	v_pk_add_f32 v[140:141], v[136:137], 0 op_sel_hi:[1,0]
	v_pk_mul_f32 v[64:65], v[174:175], v[64:65]
	v_lshlrev_b32_e32 v174, 16, v28
	v_and_b32_e32 v175, 0xffff0000, v28
	v_cvt_pk_bf16_f32 v29, v64, v65
	v_pk_add_f32 v[64:65], v[168:169], v[174:175]
	v_lshl_add_u64 v[142:143], v[118:119], 0, v[142:143]
	v_pk_add_f32 v[64:65], v[64:65], v[92:93]
	v_lshlrev_b64 v[130:131], 11, v[130:131]
	v_pk_add_f32 v[64:65], v[64:65], v[86:87]
	v_lshl_add_u64 v[152:153], v[116:117], 0, v[130:131]
	v_pk_add_f32 v[64:65], v[64:65], v[54:55]
	s_nop 0
	v_pk_add_f32 v[64:65], v[64:65], v[50:51]
	s_nop 0
	v_pk_add_f32 v[64:65], v[64:65], v[46:47]
	s_nop 0
	v_pk_add_f32 v[168:169], v[64:65], v[128:129]
	s_nop 0
	v_pk_fma_f32 v[64:65], v[56:57], v[168:169], v[54:55] op_sel_hi:[0,1,1] neg_lo:[0,0,1] neg_hi:[0,0,1]
	v_pk_mul_f32 v[64:65], v[64:65], v[10:11]
	s_nop 0
	v_pk_mul_f32 v[64:65], v[64:65], v[172:173]
	v_lshlrev_b32_e32 v172, 16, v27
	v_and_b32_e32 v173, 0xffff0000, v27
	v_cvt_pk_bf16_f32 v28, v64, v65
	v_pk_add_f32 v[64:65], v[154:155], v[172:173]
	s_nop 0
	v_pk_add_f32 v[64:65], v[64:65], v[96:97]
	s_nop 0
	v_pk_add_f32 v[64:65], v[64:65], v[88:89]
	s_nop 0
	v_pk_add_f32 v[64:65], v[64:65], v[82:83]
	s_nop 0
	v_pk_add_f32 v[64:65], v[64:65], v[74:75]
	s_nop 0
	v_pk_add_f32 v[64:65], v[64:65], v[42:43]
	s_nop 0
	v_pk_add_f32 v[154:155], v[64:65], v[126:127]
	s_nop 0
	v_pk_fma_f32 v[64:65], v[56:57], v[154:155], v[82:83] op_sel_hi:[0,1,1] neg_lo:[0,0,1] neg_hi:[0,0,1]
	s_waitcnt vmcnt(0)
	v_pk_mul_f32 v[64:65], v[64:65], v[16:17]
	s_nop 0
	v_pk_mul_f32 v[64:65], v[64:65], v[156:157]
	v_lshlrev_b32_e32 v156, 16, v26
	v_and_b32_e32 v157, 0xffff0000, v26
	v_cvt_pk_bf16_f32 v27, v64, v65
	v_pk_add_f32 v[64:65], v[140:141], v[156:157]
	s_nop 0
	v_pk_add_f32 v[64:65], v[64:65], v[94:95]
	s_nop 0
	v_pk_add_f32 v[64:65], v[64:65], v[84:85]
	s_nop 0
	v_pk_add_f32 v[64:65], v[64:65], v[78:79]
	s_nop 0
	v_pk_add_f32 v[64:65], v[64:65], v[60:61]
	s_nop 0
	v_pk_add_f32 v[64:65], v[64:65], v[58:59]
	s_nop 0
	v_pk_add_f32 v[140:141], v[64:65], v[122:123]
	v_lshlrev_b32_e32 v64, 16, v41
	v_pk_fma_f32 v[56:57], v[56:57], v[140:141], v[78:79] op_sel_hi:[0,1,1] neg_lo:[0,0,1] neg_hi:[0,0,1]
	v_pk_mul_f32 v[56:57], v[56:57], v[14:15]
	v_and_b32_e32 v65, 0xffff0000, v41
	v_pk_mul_f32 v[56:57], v[56:57], v[144:145]
	s_nop 0
	v_cvt_pk_bf16_f32 v26, v56, v57
	global_store_dwordx4 v[142:143], v[26:29], off offset:1024 sc1
	global_load_dwordx4 v[26:29], v[152:153], off offset:1024
	v_min_u32_e32 v56, v160, v227
	v_sub_u32_e64 v57, v167, 4 clamp
	v_sub_u32_e32 v56, v56, v57
	v_cvt_f32_i32_e32 v142, v56
	v_pk_add_f32 v[56:57], v[64:65], v[138:139] neg_lo:[0,1] neg_hi:[0,1]
	v_div_scale_f32 v143, s[16:17], v142, v142, 1.0
	v_rcp_f32_e32 v144, v143
	v_pk_add_f32 v[56:57], v[170:171], v[56:57]
	v_fma_f32 v41, -v143, v144, 1.0
	v_fmac_f32_e32 v144, v41, v144
	v_div_scale_f32 v41, vcc, 1.0, v142, 1.0
	v_mul_f32_e32 v138, v41, v144
	v_fma_f32 v139, -v143, v138, v41
	v_fmac_f32_e32 v138, v139, v144
	v_fma_f32 v41, -v143, v138, v41
	v_div_fmas_f32 v41, v41, v144, v138
	v_div_fixup_f32 v138, v41, v142, 1.0
	v_lshl_add_u64 v[142:143], v[118:119], 0, v[130:131]
	v_lshlrev_b64 v[144:145], 11, v[80:81]
	v_lshlrev_b32_e32 v80, 16, v38
	v_and_b32_e32 v81, 0xffff0000, v38
	v_lshlrev_b32_e32 v130, 16, v39
	v_and_b32_e32 v131, 0xffff0000, v39
	v_pk_add_f32 v[136:137], v[80:81], v[136:137] neg_lo:[0,1] neg_hi:[0,1]
	v_pk_add_f32 v[38:39], v[130:131], v[134:135] neg_lo:[0,1] neg_hi:[0,1]
	v_lshlrev_b32_e32 v134, 16, v40
	v_and_b32_e32 v135, 0xffff0000, v40
	v_pk_add_f32 v[40:41], v[134:135], v[132:133] neg_lo:[0,1] neg_hi:[0,1]
	v_pk_add_f32 v[140:141], v[140:141], v[136:137]
	v_pk_add_f32 v[168:169], v[168:169], v[40:41]
	v_pk_add_f32 v[154:155], v[154:155], v[38:39]
	v_pk_fma_f32 v[136:137], v[138:139], v[140:141], v[60:61] op_sel_hi:[0,1,1] neg_lo:[0,0,1] neg_hi:[0,0,1]
	v_pk_fma_f32 v[132:133], v[138:139], v[56:57], v[48:49] op_sel_hi:[0,1,1] neg_lo:[0,0,1] neg_hi:[0,0,1]
	v_pk_fma_f32 v[40:41], v[138:139], v[168:169], v[50:51] op_sel_hi:[0,1,1] neg_lo:[0,0,1] neg_hi:[0,0,1]
	v_pk_fma_f32 v[38:39], v[138:139], v[154:155], v[74:75] op_sel_hi:[0,1,1] neg_lo:[0,0,1] neg_hi:[0,0,1]
	v_pk_mul_f32 v[136:137], v[136:137], v[14:15]
	v_pk_mul_f32 v[38:39], v[38:39], v[16:17]
	v_pk_mul_f32 v[40:41], v[40:41], v[10:11]
	v_pk_mul_f32 v[132:133], v[132:133], v[12:13]
	v_lshl_add_u64 v[152:153], v[116:117], 0, v[144:145]
	s_waitcnt vmcnt(0)
	v_lshlrev_b32_e32 v138, 16, v26
	v_and_b32_e32 v139, 0xffff0000, v26
	v_pk_mul_f32 v[136:137], v[136:137], v[138:139]
	s_nop 0
	v_cvt_pk_bf16_f32 v26, v136, v137
	v_lshlrev_b32_e32 v136, 16, v27
	v_and_b32_e32 v137, 0xffff0000, v27
	v_pk_mul_f32 v[38:39], v[38:39], v[136:137]
	s_nop 0
	v_cvt_pk_bf16_f32 v27, v38, v39
	v_lshlrev_b32_e32 v38, 16, v28
	v_and_b32_e32 v39, 0xffff0000, v28
	v_pk_mul_f32 v[38:39], v[40:41], v[38:39]
	v_lshlrev_b32_e32 v40, 16, v30
	v_cvt_pk_bf16_f32 v28, v38, v39
	v_lshlrev_b32_e32 v38, 16, v29
	v_and_b32_e32 v39, 0xffff0000, v29
	v_pk_mul_f32 v[38:39], v[132:133], v[38:39]
	v_and_b32_e32 v41, 0xffff0000, v30
	v_cvt_pk_bf16_f32 v29, v38, v39
	global_store_dwordx4 v[142:143], v[26:29], off offset:1024 sc1
	global_load_dwordx4 v[136:139], v[152:153], off offset:1024
	v_pk_add_f32 v[132:133], v[40:41], v[156:157] neg_lo:[0,1] neg_hi:[0,1]
	v_min_u32_e32 v28, v159, v227
	v_sub_u32_e64 v29, v166, 4 clamp
	v_sub_u32_e32 v30, v28, v29
	v_lshlrev_b32_e32 v26, 16, v32
	v_and_b32_e32 v27, 0xffff0000, v32
	v_cvt_f32_i32_e32 v32, v30
	v_pk_add_f32 v[28:29], v[26:27], v[174:175] neg_lo:[0,1] neg_hi:[0,1]
	v_pk_add_f32 v[140:141], v[140:141], v[132:133]
	v_pk_add_f32 v[152:153], v[168:169], v[28:29]
	v_div_scale_f32 v156, s[16:17], v32, v32, 1.0
	v_rcp_f32_e32 v166, v156
	v_div_scale_f32 v157, vcc, 1.0, v32, 1.0
	v_lshlrev_b32_e32 v38, 16, v31
	v_fma_f32 v28, -v156, v166, 1.0
	v_fmac_f32_e32 v166, v28, v166
	v_mul_f32_e32 v28, v157, v166
	v_fma_f32 v29, -v156, v28, v157
	v_fmac_f32_e32 v28, v29, v166
	v_fma_f32 v29, -v156, v28, v157
	v_div_fmas_f32 v28, v29, v166, v28
	v_div_fixup_f32 v32, v28, v32, 1.0
	v_pk_fma_f32 v[28:29], v[32:33], v[152:153], v[46:47] op_sel_hi:[0,1,1] neg_lo:[0,0,1] neg_hi:[0,0,1]
	v_pk_fma_f32 v[132:133], v[32:33], v[140:141], v[58:59] op_sel_hi:[0,1,1] neg_lo:[0,0,1] neg_hi:[0,0,1]
	v_and_b32_e32 v39, 0xffff0000, v31
	v_pk_mul_f32 v[156:157], v[28:29], v[10:11]
	v_pk_mul_f32 v[28:29], v[132:133], v[14:15]
	v_pk_add_f32 v[30:31], v[38:39], v[172:173] neg_lo:[0,1] neg_hi:[0,1]
	v_lshlrev_b64 v[142:143], 11, v[76:77]
	v_pk_add_f32 v[154:155], v[154:155], v[30:31]
	v_lshl_add_u64 v[76:77], v[118:119], 0, v[144:145]
	v_pk_fma_f32 v[30:31], v[32:33], v[154:155], v[42:43] op_sel_hi:[0,1,1] neg_lo:[0,0,1] neg_hi:[0,0,1]
	v_pk_mul_f32 v[30:31], v[30:31], v[16:17]
	v_lshl_add_u64 v[144:145], v[116:117], 0, v[142:143]
	s_waitcnt vmcnt(0)
	v_lshlrev_b32_e32 v132, 16, v136
	v_and_b32_e32 v133, 0xffff0000, v136
	v_pk_mul_f32 v[28:29], v[28:29], v[132:133]
	v_lshlrev_b32_e32 v132, 16, v33
	v_and_b32_e32 v133, 0xffff0000, v33
	v_pk_add_f32 v[124:125], v[132:133], v[124:125] neg_lo:[0,1] neg_hi:[0,1]
	v_lshlrev_b32_e32 v136, 16, v137
	v_pk_add_f32 v[124:125], v[56:57], v[124:125]
	v_and_b32_e32 v137, 0xffff0000, v137
	v_pk_fma_f32 v[32:33], v[32:33], v[124:125], v[44:45] op_sel_hi:[0,1,1] neg_lo:[0,0,1] neg_hi:[0,0,1]
	v_lshlrev_b32_e32 v166, 16, v138
	v_and_b32_e32 v167, 0xffff0000, v138
	v_pk_mul_f32 v[30:31], v[30:31], v[136:137]
	v_lshlrev_b32_e32 v136, 16, v139
	v_and_b32_e32 v137, 0xffff0000, v139
	v_pk_mul_f32 v[32:33], v[32:33], v[12:13]
	v_cvt_pk_bf16_f32 v28, v28, v29
	v_cvt_pk_bf16_f32 v29, v30, v31
	v_pk_mul_f32 v[30:31], v[156:157], v[166:167]
	v_pk_mul_f32 v[32:33], v[32:33], v[136:137]
	v_cvt_pk_bf16_f32 v30, v30, v31
	v_cvt_pk_bf16_f32 v31, v32, v33
	global_store_dwordx4 v[76:77], v[28:31], off offset:1024 sc1
	global_load_dwordx4 v[28:31], v[144:145], off offset:1024
	v_min_u32_e32 v32, v158, v227
	v_sub_u32_e64 v33, v163, 4 clamp
	v_sub_u32_e32 v138, v32, v33
	v_lshl_add_u64 v[32:33], v[118:119], 0, v[142:143]
	v_cvt_f32_i32_e32 v142, v138
	v_lshlrev_b64 v[136:137], 11, v[72:73]
	v_lshlrev_b32_e32 v72, 16, v34
	v_and_b32_e32 v73, 0xffff0000, v34
	v_div_scale_f32 v143, s[16:17], v142, v142, 1.0
	v_rcp_f32_e32 v144, v143
	v_lshlrev_b32_e32 v76, 16, v36
	v_and_b32_e32 v77, 0xffff0000, v36
	v_pk_add_f32 v[94:95], v[72:73], v[94:95] neg_lo:[0,1] neg_hi:[0,1]
	v_fma_f32 v156, -v143, v144, 1.0
	v_pk_add_f32 v[92:93], v[76:77], v[92:93] neg_lo:[0,1] neg_hi:[0,1]
	v_div_scale_f32 v145, vcc, 1.0, v142, 1.0
	v_fmac_f32_e32 v144, v156, v144
	v_pk_add_f32 v[138:139], v[140:141], v[94:95]
	v_pk_add_f32 v[140:141], v[152:153], v[92:93]
	v_mul_f32_e32 v92, v145, v144
	v_fma_f32 v93, -v143, v92, v145
	v_fmac_f32_e32 v92, v93, v144
	v_lshlrev_b32_e32 v56, 16, v37
	v_and_b32_e32 v57, 0xffff0000, v37
	v_lshlrev_b32_e32 v34, 16, v35
	v_and_b32_e32 v35, 0xffff0000, v35
	v_fma_f32 v93, -v143, v92, v145
	v_pk_add_f32 v[120:121], v[56:57], v[120:121] neg_lo:[0,1] neg_hi:[0,1]
	v_pk_add_f32 v[96:97], v[34:35], v[96:97] neg_lo:[0,1] neg_hi:[0,1]
	v_div_fmas_f32 v92, v93, v144, v92
	v_pk_add_f32 v[96:97], v[154:155], v[96:97]
	v_pk_add_f32 v[120:121], v[124:125], v[120:121]
	v_div_fixup_f32 v92, v92, v142, 1.0
	v_pk_fma_f32 v[94:95], v[92:93], v[138:139], v[122:123] op_sel_hi:[0,1,1] neg_lo:[0,0,1] neg_hi:[0,0,1]
	v_pk_fma_f32 v[122:123], v[92:93], v[96:97], v[126:127] op_sel_hi:[0,1,1] neg_lo:[0,0,1] neg_hi:[0,0,1]
	v_pk_fma_f32 v[124:125], v[92:93], v[140:141], v[128:129] op_sel_hi:[0,1,1] neg_lo:[0,0,1] neg_hi:[0,0,1]
	v_pk_fma_f32 v[52:53], v[92:93], v[120:121], v[52:53] op_sel_hi:[0,1,1] neg_lo:[0,0,1] neg_hi:[0,0,1]
	v_pk_mul_f32 v[92:93], v[94:95], v[14:15]
	v_pk_mul_f32 v[94:95], v[122:123], v[16:17]
	v_pk_mul_f32 v[122:123], v[124:125], v[10:11]
	v_pk_mul_f32 v[52:53], v[52:53], v[12:13]
	v_lshl_add_u64 v[36:37], v[116:117], 0, v[136:137]
	s_waitcnt vmcnt(0)
	v_lshlrev_b32_e32 v124, 16, v28
	v_and_b32_e32 v125, 0xffff0000, v28
	v_lshlrev_b32_e32 v28, 16, v29
	v_and_b32_e32 v29, 0xffff0000, v29
	v_lshlrev_b32_e32 v126, 16, v30
	v_and_b32_e32 v127, 0xffff0000, v30
	v_lshlrev_b32_e32 v30, 16, v31
	v_and_b32_e32 v31, 0xffff0000, v31
	v_pk_mul_f32 v[92:93], v[92:93], v[124:125]
	v_pk_mul_f32 v[94:95], v[94:95], v[28:29]
	v_pk_mul_f32 v[122:123], v[122:123], v[126:127]
	v_pk_mul_f32 v[52:53], v[52:53], v[30:31]
	v_cvt_pk_bf16_f32 v28, v92, v93
	v_cvt_pk_bf16_f32 v29, v94, v95
	v_cvt_pk_bf16_f32 v30, v122, v123
	v_cvt_pk_bf16_f32 v31, v52, v53
	global_store_dwordx4 v[32:33], v[28:31], off offset:1024 sc1
	global_load_dwordx4 v[92:95], v[36:37], off offset:1024
	v_lshlrev_b64 v[36:37], 11, v[70:71]
	v_lshlrev_b32_e32 v28, 16, v25
	v_and_b32_e32 v29, 0xffff0000, v25
	v_min_u32_e32 v25, v165, v227
	v_sub_u32_e32 v122, v25, v161
	v_pk_add_f32 v[70:71], v[28:29], v[90:91] neg_lo:[0,1] neg_hi:[0,1]
	v_add_u32_e32 v90, 4, v122
	v_cvt_f32_i32_e32 v122, v90
	v_lshlrev_b32_e32 v30, 16, v22
	v_and_b32_e32 v31, 0xffff0000, v22
	v_pk_add_f32 v[84:85], v[30:31], v[84:85] neg_lo:[0,1] neg_hi:[0,1]
	v_div_scale_f32 v123, s[16:17], v122, v122, 1.0
	v_rcp_f32_e32 v124, v123
	v_div_scale_f32 v125, vcc, 1.0, v122, 1.0
	v_pk_add_f32 v[90:91], v[138:139], v[84:85]
	v_fma_f32 v126, -v123, v124, 1.0
	v_fmac_f32_e32 v124, v126, v124
	v_mul_f32_e32 v84, v125, v124
	v_fma_f32 v85, -v123, v84, v125
	v_fmac_f32_e32 v84, v85, v124
	v_lshlrev_b32_e32 v22, 16, v23
	v_and_b32_e32 v23, 0xffff0000, v23
	v_lshlrev_b32_e32 v32, 16, v24
	v_and_b32_e32 v33, 0xffff0000, v24
	v_fma_f32 v85, -v123, v84, v125
	v_pk_add_f32 v[88:89], v[22:23], v[88:89] neg_lo:[0,1] neg_hi:[0,1]
	v_pk_add_f32 v[86:87], v[32:33], v[86:87] neg_lo:[0,1] neg_hi:[0,1]
	v_div_fmas_f32 v84, v85, v124, v84
	v_pk_add_f32 v[88:89], v[96:97], v[88:89]
	v_pk_add_f32 v[96:97], v[140:141], v[86:87]
	v_pk_add_f32 v[70:71], v[120:121], v[70:71]
	v_div_fixup_f32 v84, v84, v122, 1.0
	v_pk_fma_f32 v[80:81], v[84:85], v[90:91], v[80:81] op_sel_hi:[0,1,1] neg_lo:[0,0,1] neg_hi:[0,0,1]
	v_pk_fma_f32 v[86:87], v[84:85], v[88:89], v[130:131] op_sel_hi:[0,1,1] neg_lo:[0,0,1] neg_hi:[0,0,1]
	v_pk_fma_f32 v[120:121], v[84:85], v[96:97], v[134:135] op_sel_hi:[0,1,1] neg_lo:[0,0,1] neg_hi:[0,0,1]
	v_pk_fma_f32 v[64:65], v[84:85], v[70:71], v[64:65] op_sel_hi:[0,1,1] neg_lo:[0,0,1] neg_hi:[0,0,1]
	v_pk_mul_f32 v[80:81], v[80:81], v[14:15]
	v_pk_mul_f32 v[84:85], v[86:87], v[16:17]
	v_pk_mul_f32 v[86:87], v[120:121], v[10:11]
	v_pk_mul_f32 v[64:65], v[64:65], v[12:13]
	v_lshl_add_u64 v[24:25], v[118:119], 0, v[136:137]
	v_lshl_add_u64 v[52:53], v[116:117], 0, v[36:37]
	v_lshl_add_u64 v[36:37], v[118:119], 0, v[36:37]
	s_waitcnt vmcnt(0)
	v_lshlrev_b32_e32 v120, 16, v92
	v_and_b32_e32 v121, 0xffff0000, v92
	v_lshlrev_b32_e32 v92, 16, v93
	v_and_b32_e32 v93, 0xffff0000, v93
	v_lshlrev_b32_e32 v122, 16, v94
	v_and_b32_e32 v123, 0xffff0000, v94
	v_lshlrev_b32_e32 v94, 16, v95
	v_and_b32_e32 v95, 0xffff0000, v95
	v_pk_mul_f32 v[80:81], v[80:81], v[120:121]
	v_pk_mul_f32 v[92:93], v[84:85], v[92:93]
	v_pk_mul_f32 v[86:87], v[86:87], v[122:123]
	v_pk_mul_f32 v[64:65], v[64:65], v[94:95]
	v_cvt_pk_bf16_f32 v84, v80, v81
	v_cvt_pk_bf16_f32 v85, v92, v93
	v_cvt_pk_bf16_f32 v86, v86, v87
	v_cvt_pk_bf16_f32 v87, v64, v65
	global_store_dwordx4 v[24:25], v[84:87], off offset:1024 sc1
	global_load_dwordx4 v[84:87], v[52:53], off offset:1024
	v_min_u32_e32 v80, v164, v227
	v_lshlrev_b32_e32 v52, 16, v21
	v_and_b32_e32 v53, 0xffff0000, v21
	v_sub_u32_e32 v92, v80, v160
	v_lshlrev_b64 v[24:25], 11, v[68:69]
	v_lshlrev_b32_e32 v68, 16, v20
	v_and_b32_e32 v69, 0xffff0000, v20
	v_pk_add_f32 v[20:21], v[52:53], v[62:63] neg_lo:[0,1] neg_hi:[0,1]
	v_add_u32_e32 v52, 4, v92
	v_cvt_f32_i32_e32 v92, v52
	v_lshlrev_b32_e32 v64, 16, v18
	v_and_b32_e32 v65, 0xffff0000, v18
	v_pk_add_f32 v[52:53], v[64:65], v[78:79] neg_lo:[0,1] neg_hi:[0,1]
	v_div_scale_f32 v78, s[16:17], v92, v92, 1.0
	v_rcp_f32_e32 v79, v78
	v_lshlrev_b32_e32 v18, 16, v19
	v_and_b32_e32 v19, 0xffff0000, v19
	v_pk_add_f32 v[18:19], v[18:19], v[82:83] neg_lo:[0,1] neg_hi:[0,1]
	v_fma_f32 v62, -v78, v79, 1.0
	v_pk_add_f32 v[54:55], v[68:69], v[54:55] neg_lo:[0,1] neg_hi:[0,1]
	v_div_scale_f32 v68, vcc, 1.0, v92, 1.0
	v_fmac_f32_e32 v79, v62, v79
	v_pk_add_f32 v[64:65], v[88:89], v[18:19]
	v_mul_f32_e32 v18, v68, v79
	v_fma_f32 v19, -v78, v18, v68
	v_fmac_f32_e32 v18, v19, v79
	v_fma_f32 v19, -v78, v18, v68
	v_div_fmas_f32 v18, v19, v79, v18
	v_pk_add_f32 v[62:63], v[70:71], v[20:21]
	v_pk_add_f32 v[52:53], v[90:91], v[52:53]
	v_pk_add_f32 v[54:55], v[96:97], v[54:55]
	v_div_fixup_f32 v18, v18, v92, 1.0
	v_pk_fma_f32 v[20:21], v[18:19], v[52:53], v[40:41] op_sel_hi:[0,1,1] neg_lo:[0,0,1] neg_hi:[0,0,1]
	v_pk_fma_f32 v[38:39], v[18:19], v[64:65], v[38:39] op_sel_hi:[0,1,1] neg_lo:[0,0,1] neg_hi:[0,0,1]
	v_pk_fma_f32 v[26:27], v[18:19], v[54:55], v[26:27] op_sel_hi:[0,1,1] neg_lo:[0,0,1] neg_hi:[0,0,1]
	v_pk_fma_f32 v[18:19], v[18:19], v[62:63], v[132:133] op_sel_hi:[0,1,1] neg_lo:[0,0,1] neg_hi:[0,0,1]
	v_pk_mul_f32 v[20:21], v[20:21], v[14:15]
	v_pk_mul_f32 v[38:39], v[38:39], v[16:17]
	v_pk_mul_f32 v[26:27], v[26:27], v[10:11]
	v_pk_mul_f32 v[18:19], v[18:19], v[12:13]
	v_lshl_add_u64 v[80:81], v[116:117], 0, v[24:25]
	v_lshl_add_u64 v[24:25], v[118:119], 0, v[24:25]
	s_waitcnt vmcnt(0)
	v_lshlrev_b32_e32 v40, 16, v87
	v_and_b32_e32 v41, 0xffff0000, v87
	v_lshlrev_b32_e32 v68, 16, v84
	v_and_b32_e32 v69, 0xffff0000, v84
	v_lshlrev_b32_e32 v70, 16, v85
	v_and_b32_e32 v71, 0xffff0000, v85
	v_lshlrev_b32_e32 v78, 16, v86
	v_and_b32_e32 v79, 0xffff0000, v86
	v_pk_mul_f32 v[20:21], v[20:21], v[68:69]
	v_pk_mul_f32 v[38:39], v[38:39], v[70:71]
	v_pk_mul_f32 v[26:27], v[26:27], v[78:79]
	v_pk_mul_f32 v[40:41], v[18:19], v[40:41]
	v_cvt_pk_bf16_f32 v18, v20, v21
	v_cvt_pk_bf16_f32 v19, v38, v39
	v_cvt_pk_bf16_f32 v20, v26, v27
	v_cvt_pk_bf16_f32 v21, v40, v41
	global_store_dwordx4 v[36:37], v[18:21], off offset:1024 sc1
	global_load_dwordx4 v[18:21], v[80:81], off offset:1024
	v_min_u32_e32 v68, v162, v227
	v_lshlrev_b32_e32 v36, 16, v9
	v_and_b32_e32 v37, 0xffff0000, v9
	v_sub_u32_e32 v68, v68, v159
	v_lshlrev_b32_e32 v40, 16, v8
	v_and_b32_e32 v41, 0xffff0000, v8
	v_pk_add_f32 v[8:9], v[36:37], v[48:49] neg_lo:[0,1] neg_hi:[0,1]
	v_add_u32_e32 v36, 4, v68
	v_cvt_f32_i32_e32 v68, v36
	v_lshlrev_b32_e32 v38, 16, v6
	v_and_b32_e32 v39, 0xffff0000, v6
	v_pk_add_f32 v[36:37], v[38:39], v[60:61] neg_lo:[0,1] neg_hi:[0,1]
	v_div_scale_f32 v60, s[16:17], v68, v68, 1.0
	v_rcp_f32_e32 v61, v60
	v_pk_add_f32 v[38:39], v[40:41], v[50:51] neg_lo:[0,1] neg_hi:[0,1]
	v_lshlrev_b32_e32 v6, 16, v7
	v_and_b32_e32 v7, 0xffff0000, v7
	v_fma_f32 v40, -v60, v61, 1.0
	v_div_scale_f32 v50, vcc, 1.0, v68, 1.0
	v_fmac_f32_e32 v61, v40, v61
	v_pk_add_f32 v[6:7], v[6:7], v[74:75] neg_lo:[0,1] neg_hi:[0,1]
	v_mul_f32_e32 v51, v50, v61
	v_pk_add_f32 v[48:49], v[64:65], v[6:7]
	v_fma_f32 v6, -v60, v51, v50
	v_fmac_f32_e32 v51, v6, v61
	v_fma_f32 v6, -v60, v51, v50
	v_div_fmas_f32 v6, v6, v61, v51
	v_pk_add_f32 v[40:41], v[62:63], v[8:9]
	v_pk_add_f32 v[36:37], v[52:53], v[36:37]
	v_pk_add_f32 v[38:39], v[54:55], v[38:39]
	v_div_fixup_f32 v6, v6, v68, 1.0
	v_pk_fma_f32 v[8:9], v[6:7], v[36:37], v[72:73] op_sel_hi:[0,1,1] neg_lo:[0,0,1] neg_hi:[0,0,1]
	v_pk_fma_f32 v[34:35], v[6:7], v[48:49], v[34:35] op_sel_hi:[0,1,1] neg_lo:[0,0,1] neg_hi:[0,0,1]
	v_pk_fma_f32 v[50:51], v[6:7], v[38:39], v[76:77] op_sel_hi:[0,1,1] neg_lo:[0,0,1] neg_hi:[0,0,1]
	v_pk_fma_f32 v[6:7], v[6:7], v[40:41], v[56:57] op_sel_hi:[0,1,1] neg_lo:[0,0,1] neg_hi:[0,0,1]
	v_pk_mul_f32 v[8:9], v[8:9], v[14:15]
	v_pk_mul_f32 v[34:35], v[34:35], v[16:17]
	v_pk_mul_f32 v[50:51], v[50:51], v[10:11]
	v_pk_mul_f32 v[6:7], v[6:7], v[12:13]
	v_lshlrev_b64 v[26:27], 11, v[66:67]
	v_lshl_add_u64 v[26:27], v[116:117], 0, v[26:27]
	s_waitcnt vmcnt(0)
	v_lshlrev_b32_e32 v52, 16, v18
	v_and_b32_e32 v53, 0xffff0000, v18
	v_lshlrev_b32_e32 v18, 16, v19
	v_and_b32_e32 v19, 0xffff0000, v19
	v_lshlrev_b32_e32 v54, 16, v20
	v_and_b32_e32 v55, 0xffff0000, v20
	v_lshlrev_b32_e32 v20, 16, v21
	v_and_b32_e32 v21, 0xffff0000, v21
	v_pk_mul_f32 v[8:9], v[8:9], v[52:53]
	v_pk_mul_f32 v[18:19], v[34:35], v[18:19]
	v_pk_mul_f32 v[34:35], v[50:51], v[54:55]
	v_pk_mul_f32 v[20:21], v[6:7], v[20:21]
	v_cvt_pk_bf16_f32 v6, v8, v9
	v_cvt_pk_bf16_f32 v7, v18, v19
	v_cvt_pk_bf16_f32 v8, v34, v35
	v_cvt_pk_bf16_f32 v9, v20, v21
	global_store_dwordx4 v[24:25], v[6:9], off offset:1024 sc1
	global_load_dwordx4 v[6:9], v[26:27], off offset:1024
	v_add_u32_e32 v34, 11, v228
	v_lshlrev_b32_e32 v18, 16, v5
	v_and_b32_e32 v19, 0xffff0000, v5
	v_min_u32_e32 v34, v34, v227
	v_lshlrev_b32_e32 v24, 16, v4
	v_and_b32_e32 v25, 0xffff0000, v4
	v_pk_add_f32 v[4:5], v[18:19], v[44:45] neg_lo:[0,1] neg_hi:[0,1]
	v_sub_u32_e32 v18, v34, v158
	v_add_u32_e32 v18, 4, v18
	v_cvt_f32_i32_e32 v34, v18
	v_lshlrev_b32_e32 v20, 16, v2
	v_and_b32_e32 v21, 0xffff0000, v2
	v_lshlrev_b32_e32 v2, 16, v3
	v_and_b32_e32 v3, 0xffff0000, v3
	v_div_scale_f32 v35, s[16:17], v34, v34, 1.0
	v_pk_add_f32 v[2:3], v[2:3], v[42:43] neg_lo:[0,1] neg_hi:[0,1]
	v_rcp_f32_e32 v42, v35
	v_pk_add_f32 v[18:19], v[20:21], v[58:59] neg_lo:[0,1] neg_hi:[0,1]
	v_pk_add_f32 v[20:21], v[24:25], v[46:47] neg_lo:[0,1] neg_hi:[0,1]
	v_div_scale_f32 v24, vcc, 1.0, v34, 1.0
	v_fma_f32 v25, -v35, v42, 1.0
	v_fmac_f32_e32 v42, v25, v42
	v_mul_f32_e32 v25, v24, v42
	v_pk_add_f32 v[18:19], v[36:37], v[18:19]
	v_fma_f32 v36, -v35, v25, v24
	v_fmac_f32_e32 v25, v36, v42
	v_fma_f32 v24, -v35, v25, v24
	v_div_fmas_f32 v24, v24, v42, v25
	v_pk_add_f32 v[2:3], v[48:49], v[2:3]
	v_pk_add_f32 v[20:21], v[38:39], v[20:21]
	v_div_fixup_f32 v24, v24, v34, 1.0
	v_pk_add_f32 v[4:5], v[40:41], v[4:5]
	v_pk_fma_f32 v[18:19], v[24:25], v[18:19], v[30:31] op_sel_hi:[0,1,1] neg_lo:[0,0,1] neg_hi:[0,0,1]
	v_pk_fma_f32 v[2:3], v[24:25], v[2:3], v[22:23] op_sel_hi:[0,1,1] neg_lo:[0,0,1] neg_hi:[0,0,1]
	v_pk_fma_f32 v[20:21], v[24:25], v[20:21], v[32:33] op_sel_hi:[0,1,1] neg_lo:[0,0,1] neg_hi:[0,0,1]
	v_pk_fma_f32 v[4:5], v[24:25], v[4:5], v[28:29] op_sel_hi:[0,1,1] neg_lo:[0,0,1] neg_hi:[0,0,1]
	v_pk_mul_f32 v[14:15], v[14:15], v[18:19]
	v_pk_mul_f32 v[2:3], v[16:17], v[2:3]
	v_pk_mul_f32 v[10:11], v[10:11], v[20:21]
	v_pk_mul_f32 v[4:5], v[12:13], v[4:5]
	v_lshlrev_b64 v[26:27], 10, v[66:67]
	s_waitcnt vmcnt(0)
	v_lshlrev_b32_e32 v16, 16, v6
	v_and_b32_e32 v17, 0xffff0000, v6
	v_lshlrev_b32_e32 v6, 16, v7
	v_and_b32_e32 v7, 0xffff0000, v7
	v_lshlrev_b32_e32 v18, 16, v8
	v_and_b32_e32 v19, 0xffff0000, v8
	v_lshlrev_b32_e32 v12, 16, v9
	v_and_b32_e32 v13, 0xffff0000, v9
	v_pk_mul_f32 v[8:9], v[14:15], v[16:17]
	v_pk_mul_f32 v[14:15], v[2:3], v[6:7]
	v_pk_mul_f32 v[10:11], v[10:11], v[18:19]
	v_pk_mul_f32 v[6:7], v[4:5], v[12:13]
	v_cvt_pk_bf16_f32 v2, v8, v9
	v_cvt_pk_bf16_f32 v3, v14, v15
	v_cvt_pk_bf16_f32 v4, v10, v11
	v_mov_b64_e32 v[8:9], v[104:105]

.LBB0_2251:
	s_or_b64 exec, exec, s[16:17]
	v_add_u32_e32 v46, v228, v94
	v_ashrrev_i32_e32 v47, 31, v46
	v_lshlrev_b64 v[82:83], 11, v[46:47]
	v_lshl_add_u64 v[46:47], v[116:117], 0, v[82:83]
	global_load_dwordx4 v[6:9], v[112:113], off offset:16
	global_load_dwordx4 v[10:13], v[112:113], off
	v_min_u32_e32 v81, v80, v227
	global_load_dwordx4 v[46:49], v[46:47], off
	v_sub_u32_e64 v86, v228, 1 clamp
	v_sub_u32_e32 v81, v81, v86
	v_cvt_f32_i32_e32 v81, v81
	s_waitcnt vmcnt(3)
	v_lshlrev_b32_e32 v68, 16, v42
	v_and_b32_e32 v69, 0xffff0000, v42
	v_lshlrev_b32_e32 v64, 16, v38
	v_and_b32_e32 v65, 0xffff0000, v38
	v_lshlrev_b32_e32 v72, 16, v44
	v_and_b32_e32 v73, 0xffff0000, v44
	v_lshlrev_b32_e32 v84, 16, v45
	v_and_b32_e32 v85, 0xffff0000, v45
	v_pk_add_f32 v[44:45], v[68:69], 0 op_sel_hi:[1,0]
	v_div_scale_f32 v96, vcc, 1.0, v81, 1.0
	v_pk_add_f32 v[94:95], v[44:45], v[64:65]
	v_div_scale_f32 v44, s[16:17], v81, v81, 1.0
	v_rcp_f32_e32 v45, v44
	v_lshlrev_b32_e32 v70, 16, v43
	v_and_b32_e32 v71, 0xffff0000, v43
	v_lshlrev_b32_e32 v38, 16, v39
	v_fma_f32 v97, -v44, v45, 1.0
	v_fmac_f32_e32 v45, v97, v45
	v_mul_f32_e32 v97, v96, v45
	v_fma_f32 v120, -v44, v97, v96
	v_fmac_f32_e32 v97, v120, v45
	v_fma_f32 v44, -v44, v97, v96
	v_and_b32_e32 v39, 0xffff0000, v39
	v_lshlrev_b32_e32 v42, 16, v40
	v_and_b32_e32 v43, 0xffff0000, v40
	v_lshlrev_b32_e32 v40, 16, v41
	v_and_b32_e32 v41, 0xffff0000, v41
	v_pk_add_f32 v[86:87], v[70:71], 0 op_sel_hi:[1,0]
	v_pk_add_f32 v[88:89], v[72:73], 0 op_sel_hi:[1,0]
	v_pk_add_f32 v[92:93], v[84:85], 0 op_sel_hi:[1,0]
	v_div_fmas_f32 v44, v44, v45, v97
	v_pk_add_f32 v[86:87], v[86:87], v[38:39]
	v_pk_add_f32 v[88:89], v[88:89], v[42:43]
	v_pk_add_f32 v[92:93], v[92:93], v[40:41]
	v_div_fixup_f32 v44, v44, v81, 1.0
	v_pk_fma_f32 v[96:97], v[44:45], v[94:95], v[64:65] op_sel_hi:[0,1,1] neg_lo:[0,0,1] neg_hi:[0,0,1]
	v_pk_fma_f32 v[120:121], v[44:45], v[86:87], v[38:39] op_sel_hi:[0,1,1] neg_lo:[0,0,1] neg_hi:[0,0,1]
	v_pk_fma_f32 v[122:123], v[44:45], v[88:89], v[42:43] op_sel_hi:[0,1,1] neg_lo:[0,0,1] neg_hi:[0,0,1]
	v_pk_fma_f32 v[44:45], v[44:45], v[92:93], v[40:41] op_sel_hi:[0,1,1] neg_lo:[0,0,1] neg_hi:[0,0,1]
	v_lshlrev_b64 v[66:67], 11, v[66:67]
	v_lshl_add_u64 v[82:83], v[118:119], 0, v[82:83]
	v_lshl_add_u64 v[90:91], v[116:117], 0, v[66:67]
	v_lshlrev_b64 v[62:63], 11, v[62:63]
	v_lshl_add_u64 v[66:67], v[118:119], 0, v[66:67]
	s_waitcnt vmcnt(2)
	v_pk_mul_f32 v[122:123], v[122:123], v[6:7]
	s_waitcnt vmcnt(1)
	v_pk_mul_f32 v[96:97], v[96:97], v[10:11]
	v_pk_mul_f32 v[120:121], v[120:121], v[12:13]
	v_pk_mul_f32 v[44:45], v[44:45], v[8:9]
	s_waitcnt vmcnt(0)
	v_lshlrev_b32_e32 v124, 16, v46
	v_and_b32_e32 v125, 0xffff0000, v46
	v_lshlrev_b32_e32 v46, 16, v47
	v_and_b32_e32 v47, 0xffff0000, v47
	v_lshlrev_b32_e32 v126, 16, v48
	v_and_b32_e32 v127, 0xffff0000, v48
	v_lshlrev_b32_e32 v48, 16, v49
	v_and_b32_e32 v49, 0xffff0000, v49
	v_pk_mul_f32 v[96:97], v[96:97], v[124:125]
	v_pk_mul_f32 v[46:47], v[120:121], v[46:47]
	v_pk_mul_f32 v[120:121], v[122:123], v[126:127]
	v_pk_mul_f32 v[48:49], v[44:45], v[48:49]
	v_cvt_pk_bf16_f32 v44, v96, v97
	v_cvt_pk_bf16_f32 v45, v46, v47
	v_cvt_pk_bf16_f32 v46, v120, v121
	v_cvt_pk_bf16_f32 v47, v48, v49
	global_store_dwordx4 v[82:83], v[44:47], off sc1
	global_load_dwordx4 v[44:47], v[90:91], off
	v_lshlrev_b32_e32 v48, 16, v37
	v_and_b32_e32 v49, 0xffff0000, v37
	v_min_u32_e32 v37, v79, v227
	v_lshlrev_b32_e32 v82, 16, v34
	v_and_b32_e32 v83, 0xffff0000, v34
	v_lshlrev_b32_e32 v90, 16, v35
	v_and_b32_e32 v91, 0xffff0000, v35
	v_lshlrev_b32_e32 v96, 16, v36
	v_and_b32_e32 v97, 0xffff0000, v36
	v_sub_u32_e32 v120, v37, v80
	v_pk_add_f32 v[36:37], v[82:83], v[68:69] neg_lo:[0,1] neg_hi:[0,1]
	v_pk_add_f32 v[68:69], v[90:91], v[70:71] neg_lo:[0,1] neg_hi:[0,1]
	v_pk_add_f32 v[70:71], v[96:97], v[72:73] neg_lo:[0,1] neg_hi:[0,1]
	v_add_u32_e32 v72, 1, v120
	v_cvt_f32_i32_e32 v120, v72
	v_pk_add_f32 v[34:35], v[48:49], v[84:85] neg_lo:[0,1] neg_hi:[0,1]
	v_pk_add_f32 v[84:85], v[94:95], v[36:37]
	v_pk_add_f32 v[72:73], v[92:93], v[34:35]
	v_div_scale_f32 v34, s[16:17], v120, v120, 1.0
	v_rcp_f32_e32 v35, v34
	v_div_scale_f32 v36, vcc, 1.0, v120, 1.0
	v_pk_add_f32 v[68:69], v[86:87], v[68:69]
	v_fma_f32 v37, -v34, v35, 1.0
	v_fmac_f32_e32 v35, v37, v35
	v_mul_f32_e32 v37, v36, v35
	v_fma_f32 v86, -v34, v37, v36
	v_fmac_f32_e32 v37, v86, v35
	v_fma_f32 v34, -v34, v37, v36
	v_div_fmas_f32 v34, v34, v35, v37
	v_pk_add_f32 v[70:71], v[88:89], v[70:71]
	v_div_fixup_f32 v34, v34, v120, 1.0
	v_pk_fma_f32 v[36:37], v[34:35], v[84:85], v[82:83] op_sel_hi:[0,1,1] neg_lo:[0,0,1] neg_hi:[0,0,1]
	v_pk_fma_f32 v[86:87], v[34:35], v[68:69], v[90:91] op_sel_hi:[0,1,1] neg_lo:[0,0,1] neg_hi:[0,0,1]
	v_pk_fma_f32 v[88:89], v[34:35], v[70:71], v[96:97] op_sel_hi:[0,1,1] neg_lo:[0,0,1] neg_hi:[0,0,1]
	v_pk_fma_f32 v[34:35], v[34:35], v[72:73], v[48:49] op_sel_hi:[0,1,1] neg_lo:[0,0,1] neg_hi:[0,0,1]
	v_pk_mul_f32 v[36:37], v[36:37], v[10:11]
	v_pk_mul_f32 v[86:87], v[86:87], v[12:13]
	v_pk_mul_f32 v[88:89], v[88:89], v[6:7]
	v_pk_mul_f32 v[34:35], v[34:35], v[8:9]
	v_lshl_add_u64 v[80:81], v[116:117], 0, v[62:63]
	v_lshl_add_u64 v[62:63], v[118:119], 0, v[62:63]
	s_waitcnt vmcnt(0)
	v_lshlrev_b32_e32 v92, 16, v44
	v_and_b32_e32 v93, 0xffff0000, v44
	v_lshlrev_b32_e32 v44, 16, v45
	v_and_b32_e32 v45, 0xffff0000, v45
	v_lshlrev_b32_e32 v94, 16, v46
	v_and_b32_e32 v95, 0xffff0000, v46
	v_lshlrev_b32_e32 v46, 16, v47
	v_and_b32_e32 v47, 0xffff0000, v47
	v_pk_mul_f32 v[36:37], v[36:37], v[92:93]
	v_pk_mul_f32 v[44:45], v[86:87], v[44:45]
	v_pk_mul_f32 v[86:87], v[88:89], v[94:95]
	v_pk_mul_f32 v[46:47], v[34:35], v[46:47]
	v_cvt_pk_bf16_f32 v34, v36, v37
	v_cvt_pk_bf16_f32 v35, v44, v45
	v_cvt_pk_bf16_f32 v36, v86, v87
	v_cvt_pk_bf16_f32 v37, v46, v47
	global_store_dwordx4 v[66:67], v[34:37], off sc1
	global_load_dwordx4 v[34:37], v[80:81], off
	v_lshlrev_b32_e32 v44, 16, v33
	v_and_b32_e32 v45, 0xffff0000, v33
	v_min_u32_e32 v33, v78, v227
	v_lshlrev_b32_e32 v80, 16, v32
	v_and_b32_e32 v81, 0xffff0000, v32
	v_sub_u32_e32 v79, v33, v79
	v_lshlrev_b64 v[46:47], 11, v[60:61]
	v_lshlrev_b32_e32 v60, 16, v30
	v_and_b32_e32 v61, 0xffff0000, v30
	v_lshlrev_b32_e32 v66, 16, v31
	v_and_b32_e32 v67, 0xffff0000, v31
	v_pk_add_f32 v[30:31], v[44:45], v[40:41] neg_lo:[0,1] neg_hi:[0,1]
	v_pk_add_f32 v[40:41], v[80:81], v[42:43] neg_lo:[0,1] neg_hi:[0,1]
	v_add_u32_e32 v42, 1, v79
	v_cvt_f32_i32_e32 v79, v42
	v_pk_add_f32 v[42:43], v[72:73], v[30:31]
	v_pk_add_f32 v[32:33], v[60:61], v[64:65] neg_lo:[0,1] neg_hi:[0,1]
	v_pk_add_f32 v[38:39], v[66:67], v[38:39] neg_lo:[0,1] neg_hi:[0,1]
	v_div_scale_f32 v30, s[16:17], v79, v79, 1.0
	v_rcp_f32_e32 v31, v30
	v_pk_add_f32 v[64:65], v[84:85], v[32:33]
	v_div_scale_f32 v32, vcc, 1.0, v79, 1.0
	v_fma_f32 v33, -v30, v31, 1.0
	v_fmac_f32_e32 v31, v33, v31
	v_mul_f32_e32 v33, v32, v31
	v_pk_add_f32 v[38:39], v[68:69], v[38:39]
	v_fma_f32 v68, -v30, v33, v32
	v_fmac_f32_e32 v33, v68, v31
	v_fma_f32 v30, -v30, v33, v32
	v_div_fmas_f32 v30, v30, v31, v33
	v_pk_add_f32 v[40:41], v[70:71], v[40:41]
	v_div_fixup_f32 v30, v30, v79, 1.0
	v_pk_fma_f32 v[32:33], v[30:31], v[64:65], v[60:61] op_sel_hi:[0,1,1] neg_lo:[0,0,1] neg_hi:[0,0,1]
	v_pk_fma_f32 v[68:69], v[30:31], v[38:39], v[66:67] op_sel_hi:[0,1,1] neg_lo:[0,0,1] neg_hi:[0,0,1]
	v_pk_fma_f32 v[70:71], v[30:31], v[40:41], v[80:81] op_sel_hi:[0,1,1] neg_lo:[0,0,1] neg_hi:[0,0,1]
	v_pk_fma_f32 v[30:31], v[30:31], v[42:43], v[44:45] op_sel_hi:[0,1,1] neg_lo:[0,0,1] neg_hi:[0,0,1]
	v_pk_mul_f32 v[32:33], v[32:33], v[10:11]
	v_pk_mul_f32 v[68:69], v[68:69], v[12:13]
	v_pk_mul_f32 v[70:71], v[70:71], v[6:7]
	v_pk_mul_f32 v[30:31], v[30:31], v[8:9]
	v_lshl_add_u64 v[86:87], v[116:117], 0, v[46:47]
	v_lshl_add_u64 v[46:47], v[118:119], 0, v[46:47]
	s_waitcnt vmcnt(0)
	v_lshlrev_b32_e32 v72, 16, v34
	v_and_b32_e32 v73, 0xffff0000, v34
	v_lshlrev_b32_e32 v34, 16, v35
	v_and_b32_e32 v35, 0xffff0000, v35
	v_lshlrev_b32_e32 v84, 16, v36
	v_and_b32_e32 v85, 0xffff0000, v36
	v_lshlrev_b32_e32 v36, 16, v37
	v_and_b32_e32 v37, 0xffff0000, v37
	v_pk_mul_f32 v[32:33], v[32:33], v[72:73]
	v_pk_mul_f32 v[34:35], v[68:69], v[34:35]
	v_pk_mul_f32 v[68:69], v[70:71], v[84:85]
	v_pk_mul_f32 v[36:37], v[30:31], v[36:37]
	v_cvt_pk_bf16_f32 v30, v32, v33
	v_cvt_pk_bf16_f32 v31, v34, v35
	v_cvt_pk_bf16_f32 v32, v68, v69
	v_cvt_pk_bf16_f32 v33, v36, v37
	global_store_dwordx4 v[62:63], v[30:33], off sc1
	global_load_dwordx4 v[30:33], v[86:87], off
	v_lshlrev_b32_e32 v34, 16, v29
	v_and_b32_e32 v35, 0xffff0000, v29
	v_min_u32_e32 v29, v77, v227
	v_sub_u32_e32 v78, v29, v78
	v_add_u32_e32 v78, 1, v78
	v_cvt_f32_i32_e32 v78, v78
	v_lshlrev_b64 v[36:37], 11, v[58:59]
	v_lshlrev_b32_e32 v58, 16, v26
	v_and_b32_e32 v59, 0xffff0000, v26
	v_lshlrev_b32_e32 v62, 16, v27
	v_and_b32_e32 v63, 0xffff0000, v27
	v_pk_add_f32 v[26:27], v[34:35], v[48:49] neg_lo:[0,1] neg_hi:[0,1]
	v_lshlrev_b32_e32 v68, 16, v28
	v_pk_add_f32 v[42:43], v[42:43], v[26:27]
	v_div_scale_f32 v26, s[16:17], v78, v78, 1.0
	v_rcp_f32_e32 v27, v26
	v_and_b32_e32 v69, 0xffff0000, v28
	v_pk_add_f32 v[28:29], v[58:59], v[82:83] neg_lo:[0,1] neg_hi:[0,1]
	v_pk_add_f32 v[48:49], v[62:63], v[90:91] neg_lo:[0,1] neg_hi:[0,1]
	v_pk_add_f32 v[64:65], v[64:65], v[28:29]
	v_fma_f32 v29, -v26, v27, 1.0
	v_div_scale_f32 v28, vcc, 1.0, v78, 1.0
	v_fmac_f32_e32 v27, v29, v27
	v_mul_f32_e32 v29, v28, v27
	v_pk_add_f32 v[38:39], v[38:39], v[48:49]
	v_fma_f32 v48, -v26, v29, v28
	v_fmac_f32_e32 v29, v48, v27
	v_fma_f32 v26, -v26, v29, v28
	v_pk_add_f32 v[72:73], v[68:69], v[96:97] neg_lo:[0,1] neg_hi:[0,1]
	v_div_fmas_f32 v26, v26, v27, v29
	v_pk_add_f32 v[40:41], v[40:41], v[72:73]
	v_div_fixup_f32 v26, v26, v78, 1.0
	v_pk_fma_f32 v[28:29], v[26:27], v[64:65], v[58:59] op_sel_hi:[0,1,1] neg_lo:[0,0,1] neg_hi:[0,0,1]
	v_pk_fma_f32 v[48:49], v[26:27], v[38:39], v[62:63] op_sel_hi:[0,1,1] neg_lo:[0,0,1] neg_hi:[0,0,1]
	v_pk_fma_f32 v[72:73], v[26:27], v[40:41], v[68:69] op_sel_hi:[0,1,1] neg_lo:[0,0,1] neg_hi:[0,0,1]
	v_pk_fma_f32 v[26:27], v[26:27], v[42:43], v[34:35] op_sel_hi:[0,1,1] neg_lo:[0,0,1] neg_hi:[0,0,1]
	v_pk_mul_f32 v[28:29], v[28:29], v[10:11]
	v_pk_mul_f32 v[48:49], v[48:49], v[12:13]
	v_pk_mul_f32 v[72:73], v[72:73], v[6:7]
	v_pk_mul_f32 v[26:27], v[26:27], v[8:9]
	v_lshl_add_u64 v[70:71], v[116:117], 0, v[36:37]
	v_lshl_add_u64 v[36:37], v[118:119], 0, v[36:37]
	s_waitcnt vmcnt(0)
	v_lshlrev_b32_e32 v78, 16, v30
	v_and_b32_e32 v79, 0xffff0000, v30
	v_lshlrev_b32_e32 v30, 16, v31
	v_and_b32_e32 v31, 0xffff0000, v31
	v_lshlrev_b32_e32 v82, 16, v32
	v_and_b32_e32 v83, 0xffff0000, v32
	v_lshlrev_b32_e32 v32, 16, v33
	v_and_b32_e32 v33, 0xffff0000, v33
	v_pk_mul_f32 v[28:29], v[28:29], v[78:79]
	v_pk_mul_f32 v[30:31], v[48:49], v[30:31]
	v_pk_mul_f32 v[48:49], v[72:73], v[82:83]
	v_pk_mul_f32 v[32:33], v[26:27], v[32:33]
	v_cvt_pk_bf16_f32 v26, v28, v29
	v_cvt_pk_bf16_f32 v27, v30, v31
	v_cvt_pk_bf16_f32 v28, v48, v49
	v_cvt_pk_bf16_f32 v29, v32, v33
	global_store_dwordx4 v[46:47], v[26:29], off sc1
	global_load_dwordx4 v[26:29], v[70:71], off
	v_lshlrev_b32_e32 v30, 16, v25
	v_and_b32_e32 v31, 0xffff0000, v25
	v_min_u32_e32 v25, v76, v227
	v_lshlrev_b32_e32 v48, 16, v23
	v_and_b32_e32 v49, 0xffff0000, v23
	v_sub_u32_e32 v72, v25, v77
	v_lshlrev_b32_e32 v46, 16, v22
	v_and_b32_e32 v47, 0xffff0000, v22
	v_pk_add_f32 v[22:23], v[30:31], v[44:45] neg_lo:[0,1] neg_hi:[0,1]
	v_pk_add_f32 v[44:45], v[48:49], v[66:67] neg_lo:[0,1] neg_hi:[0,1]
	v_add_u32_e32 v66, 1, v72
	v_cvt_f32_i32_e32 v66, v66
	v_pk_add_f32 v[42:43], v[42:43], v[22:23]
	v_lshlrev_b64 v[32:33], 11, v[56:57]
	v_lshlrev_b32_e32 v56, 16, v24
	v_div_scale_f32 v22, s[16:17], v66, v66, 1.0
	v_rcp_f32_e32 v23, v22
	v_and_b32_e32 v57, 0xffff0000, v24
	v_pk_add_f32 v[24:25], v[46:47], v[60:61] neg_lo:[0,1] neg_hi:[0,1]
	v_pk_add_f32 v[38:39], v[38:39], v[44:45]
	v_pk_add_f32 v[64:65], v[64:65], v[24:25]
	v_fma_f32 v25, -v22, v23, 1.0
	v_div_scale_f32 v24, vcc, 1.0, v66, 1.0
	v_fmac_f32_e32 v23, v25, v23
	v_mul_f32_e32 v25, v24, v23
	v_fma_f32 v44, -v22, v25, v24
	v_fmac_f32_e32 v25, v44, v23
	v_fma_f32 v22, -v22, v25, v24
	v_pk_add_f32 v[60:61], v[56:57], v[80:81] neg_lo:[0,1] neg_hi:[0,1]
	v_div_fmas_f32 v22, v22, v23, v25
	v_pk_add_f32 v[40:41], v[40:41], v[60:61]
	v_div_fixup_f32 v22, v22, v66, 1.0
	v_pk_fma_f32 v[24:25], v[22:23], v[64:65], v[46:47] op_sel_hi:[0,1,1] neg_lo:[0,0,1] neg_hi:[0,0,1]
	v_pk_fma_f32 v[44:45], v[22:23], v[38:39], v[48:49] op_sel_hi:[0,1,1] neg_lo:[0,0,1] neg_hi:[0,0,1]
	v_pk_fma_f32 v[60:61], v[22:23], v[40:41], v[56:57] op_sel_hi:[0,1,1] neg_lo:[0,0,1] neg_hi:[0,0,1]
	v_pk_fma_f32 v[22:23], v[22:23], v[42:43], v[30:31] op_sel_hi:[0,1,1] neg_lo:[0,0,1] neg_hi:[0,0,1]
	v_pk_mul_f32 v[24:25], v[24:25], v[10:11]
	v_pk_mul_f32 v[44:45], v[44:45], v[12:13]
	v_pk_mul_f32 v[60:61], v[60:61], v[6:7]
	v_pk_mul_f32 v[22:23], v[22:23], v[8:9]
	v_lshl_add_u64 v[70:71], v[116:117], 0, v[32:33]
	v_lshl_add_u64 v[32:33], v[118:119], 0, v[32:33]
	s_waitcnt vmcnt(0)
	v_lshlrev_b32_e32 v66, 16, v26
	v_and_b32_e32 v67, 0xffff0000, v26
	v_lshlrev_b32_e32 v26, 16, v27
	v_and_b32_e32 v27, 0xffff0000, v27
	v_lshlrev_b32_e32 v72, 16, v28
	v_and_b32_e32 v73, 0xffff0000, v28
	v_lshlrev_b32_e32 v28, 16, v29
	v_and_b32_e32 v29, 0xffff0000, v29
	v_pk_mul_f32 v[24:25], v[24:25], v[66:67]
	v_pk_mul_f32 v[26:27], v[44:45], v[26:27]
	v_pk_mul_f32 v[44:45], v[60:61], v[72:73]
	v_pk_mul_f32 v[28:29], v[22:23], v[28:29]
	v_cvt_pk_bf16_f32 v22, v24, v25
	v_cvt_pk_bf16_f32 v23, v26, v27
	v_cvt_pk_bf16_f32 v24, v44, v45
	v_cvt_pk_bf16_f32 v25, v28, v29
	global_store_dwordx4 v[36:37], v[22:25], off sc1
	global_load_dwordx4 v[22:25], v[70:71], off
	v_min_u32_e32 v60, v75, v227
	v_lshlrev_b32_e32 v28, 16, v21
	v_and_b32_e32 v29, 0xffff0000, v21
	v_sub_u32_e32 v66, v60, v76
	v_lshlrev_b32_e32 v36, 16, v18
	v_and_b32_e32 v37, 0xffff0000, v18
	v_lshlrev_b32_e32 v44, 16, v19
	v_and_b32_e32 v45, 0xffff0000, v19
	v_pk_add_f32 v[18:19], v[28:29], v[34:35] neg_lo:[0,1] neg_hi:[0,1]
	v_add_u32_e32 v34, 1, v66
	v_cvt_f32_i32_e32 v66, v34
	v_pk_add_f32 v[42:43], v[42:43], v[18:19]
	v_lshlrev_b64 v[26:27], 11, v[54:55]
	v_lshlrev_b32_e32 v54, 16, v20
	v_div_scale_f32 v67, s[16:17], v66, v66, 1.0
	v_rcp_f32_e32 v18, v67
	v_and_b32_e32 v55, 0xffff0000, v20
	v_pk_add_f32 v[20:21], v[36:37], v[58:59] neg_lo:[0,1] neg_hi:[0,1]
	v_pk_add_f32 v[58:59], v[54:55], v[68:69] neg_lo:[0,1] neg_hi:[0,1]
	v_fma_f32 v19, -v67, v18, 1.0
	v_div_scale_f32 v68, vcc, 1.0, v66, 1.0
	v_fmac_f32_e32 v18, v19, v18
	v_mul_f32_e32 v19, v68, v18
	v_pk_add_f32 v[34:35], v[44:45], v[62:63] neg_lo:[0,1] neg_hi:[0,1]
	v_pk_add_f32 v[62:63], v[64:65], v[20:21]
	v_fma_f32 v20, -v67, v19, v68
	v_fmac_f32_e32 v19, v20, v18
	v_fma_f32 v20, -v67, v19, v68
	v_div_fmas_f32 v18, v20, v18, v19
	v_pk_add_f32 v[34:35], v[38:39], v[34:35]
	v_pk_add_f32 v[38:39], v[40:41], v[58:59]
	v_div_fixup_f32 v18, v18, v66, 1.0
	v_pk_fma_f32 v[20:21], v[18:19], v[62:63], v[36:37] op_sel_hi:[0,1,1] neg_lo:[0,0,1] neg_hi:[0,0,1]
	v_pk_fma_f32 v[40:41], v[18:19], v[34:35], v[44:45] op_sel_hi:[0,1,1] neg_lo:[0,0,1] neg_hi:[0,0,1]
	v_pk_fma_f32 v[58:59], v[18:19], v[38:39], v[54:55] op_sel_hi:[0,1,1] neg_lo:[0,0,1] neg_hi:[0,0,1]
	v_pk_fma_f32 v[18:19], v[18:19], v[42:43], v[28:29] op_sel_hi:[0,1,1] neg_lo:[0,0,1] neg_hi:[0,0,1]
	v_pk_mul_f32 v[20:21], v[20:21], v[10:11]
	v_pk_mul_f32 v[40:41], v[40:41], v[12:13]
	v_pk_mul_f32 v[58:59], v[58:59], v[6:7]
	v_pk_mul_f32 v[18:19], v[18:19], v[8:9]
	v_lshl_add_u64 v[60:61], v[116:117], 0, v[26:27]
	v_lshl_add_u64 v[26:27], v[118:119], 0, v[26:27]
	s_waitcnt vmcnt(0)
	v_lshlrev_b32_e32 v64, 16, v22
	v_and_b32_e32 v65, 0xffff0000, v22
	v_lshlrev_b32_e32 v22, 16, v23
	v_and_b32_e32 v23, 0xffff0000, v23
	v_lshlrev_b32_e32 v66, 16, v24
	v_and_b32_e32 v67, 0xffff0000, v24
	v_lshlrev_b32_e32 v24, 16, v25
	v_and_b32_e32 v25, 0xffff0000, v25
	v_pk_mul_f32 v[20:21], v[20:21], v[64:65]
	v_pk_mul_f32 v[22:23], v[40:41], v[22:23]
	v_pk_mul_f32 v[40:41], v[58:59], v[66:67]
	v_pk_mul_f32 v[24:25], v[18:19], v[24:25]
	v_cvt_pk_bf16_f32 v18, v20, v21
	v_cvt_pk_bf16_f32 v19, v22, v23
	v_cvt_pk_bf16_f32 v20, v40, v41
	v_cvt_pk_bf16_f32 v21, v24, v25
	global_store_dwordx4 v[32:33], v[18:21], off sc1
	global_load_dwordx4 v[18:21], v[60:61], off
	v_min_u32_e32 v58, v74, v227
	v_lshl_add_u64 v[22:23], v[116:117], 0, v[52:53]
	v_lshlrev_b32_e32 v24, 16, v17
	v_and_b32_e32 v25, 0xffff0000, v17
	v_lshlrev_b32_e32 v32, 16, v14
	v_and_b32_e32 v33, 0xffff0000, v14
	v_sub_u32_e32 v52, v58, v75
	v_lshlrev_b32_e32 v40, 16, v16
	v_and_b32_e32 v41, 0xffff0000, v16
	v_pk_add_f32 v[16:17], v[24:25], v[30:31] neg_lo:[0,1] neg_hi:[0,1]
	v_pk_add_f32 v[30:31], v[32:33], v[46:47] neg_lo:[0,1] neg_hi:[0,1]
	v_add_u32_e32 v46, 1, v52
	v_cvt_f32_i32_e32 v52, v46
	v_lshlrev_b32_e32 v14, 16, v15
	v_and_b32_e32 v15, 0xffff0000, v15
	v_pk_add_f32 v[46:47], v[14:15], v[48:49] neg_lo:[0,1] neg_hi:[0,1]
	v_div_scale_f32 v53, s[16:17], v52, v52, 1.0
	v_pk_add_f32 v[48:49], v[40:41], v[56:57] neg_lo:[0,1] neg_hi:[0,1]
	v_rcp_f32_e32 v57, v53
	v_pk_add_f32 v[42:43], v[42:43], v[16:17]
	v_div_scale_f32 v56, vcc, 1.0, v52, 1.0
	v_fma_f32 v16, -v53, v57, 1.0
	v_fmac_f32_e32 v57, v16, v57
	v_mul_f32_e32 v16, v56, v57
	v_fma_f32 v17, -v53, v16, v56
	v_fmac_f32_e32 v16, v17, v57
	v_fma_f32 v17, -v53, v16, v56
	v_div_fmas_f32 v16, v17, v57, v16
	v_pk_add_f32 v[30:31], v[62:63], v[30:31]
	v_pk_add_f32 v[34:35], v[34:35], v[46:47]
	v_pk_add_f32 v[38:39], v[38:39], v[48:49]
	v_div_fixup_f32 v16, v16, v52, 1.0
	v_pk_fma_f32 v[32:33], v[16:17], v[30:31], v[32:33] op_sel_hi:[0,1,1] neg_lo:[0,0,1] neg_hi:[0,0,1]
	v_pk_fma_f32 v[14:15], v[16:17], v[34:35], v[14:15] op_sel_hi:[0,1,1] neg_lo:[0,0,1] neg_hi:[0,0,1]
	v_pk_fma_f32 v[40:41], v[16:17], v[38:39], v[40:41] op_sel_hi:[0,1,1] neg_lo:[0,0,1] neg_hi:[0,0,1]
	v_pk_fma_f32 v[16:17], v[16:17], v[42:43], v[24:25] op_sel_hi:[0,1,1] neg_lo:[0,0,1] neg_hi:[0,0,1]
	v_pk_mul_f32 v[24:25], v[32:33], v[10:11]
	v_pk_mul_f32 v[14:15], v[14:15], v[12:13]
	v_pk_mul_f32 v[32:33], v[40:41], v[6:7]
	v_pk_mul_f32 v[16:17], v[16:17], v[8:9]
	s_waitcnt vmcnt(0)
	v_lshlrev_b32_e32 v40, 16, v18
	v_and_b32_e32 v41, 0xffff0000, v18
	v_lshlrev_b32_e32 v18, 16, v19
	v_and_b32_e32 v19, 0xffff0000, v19
	v_lshlrev_b32_e32 v46, 16, v20
	v_and_b32_e32 v47, 0xffff0000, v20
	v_lshlrev_b32_e32 v20, 16, v21
	v_and_b32_e32 v21, 0xffff0000, v21
	v_pk_mul_f32 v[24:25], v[24:25], v[40:41]
	v_pk_mul_f32 v[18:19], v[14:15], v[18:19]
	v_pk_mul_f32 v[32:33], v[32:33], v[46:47]
	v_pk_mul_f32 v[20:21], v[16:17], v[20:21]
	v_cvt_pk_bf16_f32 v14, v24, v25
	v_cvt_pk_bf16_f32 v15, v18, v19
	v_cvt_pk_bf16_f32 v16, v32, v33
	v_cvt_pk_bf16_f32 v17, v20, v21
	global_store_dwordx4 v[26:27], v[14:17], off sc1
	global_load_dwordx4 v[14:17], v[22:23], off
	v_add_u32_e32 v24, 8, v228
	v_lshlrev_b32_e32 v18, 16, v5
	v_and_b32_e32 v19, 0xffff0000, v5
	v_min_u32_e32 v32, v24, v227
	v_lshlrev_b32_e32 v22, 16, v4
	v_and_b32_e32 v23, 0xffff0000, v4
	v_pk_add_f32 v[4:5], v[18:19], v[28:29] neg_lo:[0,1] neg_hi:[0,1]
	v_sub_u32_e32 v28, v32, v74
	v_lshlrev_b32_e32 v20, 16, v2
	v_and_b32_e32 v21, 0xffff0000, v2
	v_add_u32_e32 v28, 1, v28
	v_pk_add_f32 v[24:25], v[20:21], v[36:37] neg_lo:[0,1] neg_hi:[0,1]
	v_cvt_f32_i32_e32 v36, v28
	v_pk_add_f32 v[32:33], v[22:23], v[54:55] neg_lo:[0,1] neg_hi:[0,1]
	v_pk_add_f32 v[24:25], v[30:31], v[24:25]
	v_pk_add_f32 v[30:31], v[38:39], v[32:33]
	v_div_scale_f32 v37, s[16:17], v36, v36, 1.0
	v_rcp_f32_e32 v41, v37
	v_div_scale_f32 v40, vcc, 1.0, v36, 1.0
	v_lshlrev_b32_e32 v2, 16, v3
	v_fma_f32 v32, -v37, v41, 1.0
	v_fmac_f32_e32 v41, v32, v41
	v_mul_f32_e32 v32, v40, v41
	v_fma_f32 v33, -v37, v32, v40
	v_fmac_f32_e32 v32, v33, v41
	v_and_b32_e32 v3, 0xffff0000, v3
	v_fma_f32 v33, -v37, v32, v40
	v_pk_add_f32 v[28:29], v[2:3], v[44:45] neg_lo:[0,1] neg_hi:[0,1]
	v_div_fmas_f32 v32, v33, v41, v32
	v_pk_add_f32 v[4:5], v[42:43], v[4:5]
	v_pk_add_f32 v[28:29], v[34:35], v[28:29]
	v_div_fixup_f32 v32, v32, v36, 1.0
	v_pk_fma_f32 v[20:21], v[32:33], v[24:25], v[20:21] op_sel_hi:[0,1,1] neg_lo:[0,0,1] neg_hi:[0,0,1]
	v_pk_fma_f32 v[2:3], v[32:33], v[28:29], v[2:3] op_sel_hi:[0,1,1] neg_lo:[0,0,1] neg_hi:[0,0,1]
	v_pk_fma_f32 v[22:23], v[32:33], v[30:31], v[22:23] op_sel_hi:[0,1,1] neg_lo:[0,0,1] neg_hi:[0,0,1]
	v_pk_fma_f32 v[4:5], v[32:33], v[4:5], v[18:19] op_sel_hi:[0,1,1] neg_lo:[0,0,1] neg_hi:[0,0,1]
	v_pk_mul_f32 v[10:11], v[10:11], v[20:21]
	v_pk_mul_f32 v[2:3], v[12:13], v[2:3]
	v_pk_mul_f32 v[6:7], v[6:7], v[22:23]
	v_pk_mul_f32 v[8:9], v[8:9], v[4:5]
	v_lshlrev_b64 v[26:27], 10, v[50:51]
	s_waitcnt vmcnt(0)
	v_lshlrev_b32_e32 v4, 16, v14
	v_and_b32_e32 v5, 0xffff0000, v14
	v_lshlrev_b32_e32 v14, 16, v15
	v_and_b32_e32 v15, 0xffff0000, v15
	v_lshlrev_b32_e32 v18, 16, v16
	v_and_b32_e32 v19, 0xffff0000, v16
	v_lshlrev_b32_e32 v12, 16, v17
	v_and_b32_e32 v13, 0xffff0000, v17
	v_pk_mul_f32 v[4:5], v[10:11], v[4:5]
	v_pk_mul_f32 v[10:11], v[2:3], v[14:15]
	v_pk_mul_f32 v[6:7], v[6:7], v[18:19]
	v_cvt_pk_bf16_f32 v2, v4, v5
	v_cvt_pk_bf16_f32 v3, v10, v11
	v_cvt_pk_bf16_f32 v4, v6, v7
	v_pk_mul_f32 v[6:7], v[8:9], v[12:13]

.LBB0_2275:
	s_or_b64 exec, exec, s[4:5]
	s_load_dword s66, s[0:1], 0x468
	s_waitcnt lgkmcnt(0)
	s_cmpk_lg_u32 s66, 0x200
	s_cbranch_scc1 FUSE18_ORIG
	s_cmp_lt_i32 s23, 20
	s_cbranch_scc1 FUSE18_ORIG
	s_waitcnt vmcnt(0)
	s_barrier
	v_bfe_u32 v5, v0, 6, 2
	s_and_b32 s73, s2, 0x1ff
	s_nop 1
	v_readfirstlane_b32 s67, v5
	s_cmp_lg_u32 s67, 0
	s_cbranch_scc1 FUSE18_WAIT
	s_and_b32 s67, s73, 63
	s_lshl_b32 s68, s67, 6
	s_and_b32 s69, s67, 32
	s_lshl_b32 s69, s69, 6
	s_add_u32 s68, s68, s69
	s_add_u32 s68, s68, 0x1c00
	v_mov_b32_e32 v2, s68
	v_mov_b32_e32 v3, 1
	s_mov_b64 s[70:71], exec
	s_mov_b64 exec, 1
	s_mov_b32 s74, 0
	global_atomic_add v2, v3, s[20:21]
FUSE18_SPIN:
	global_load_dword v4, v2, s[20:21] sc1
	s_waitcnt vmcnt(0)
	v_readfirstlane_b32 s69, v4
	s_cmp_ge_u32 s69, 40
	s_cbranch_scc1 FUSE18_GOT
	s_add_i32 s74, s74, 1
	s_cmp_gt_u32 s74, 0x20000
	s_cbranch_scc1 FUSE18_GOT
	s_sleep 1
	s_branch FUSE18_SPIN
FUSE18_GOT:
	s_mov_b64 exec, s[70:71]
FUSE18_WAIT:
	s_barrier
	s_branch .LBB0_2328
FUSE18_ORIG:
	s_cmp_lt_i32 s23, 20
	s_cbranch_scc1 .LBB0_2328
	s_waitcnt vmcnt(0)
	v_cmp_eq_u32_e32 vcc, 0, v147
	s_waitcnt vmcnt(0)
	v_mov_b32_e32 v2, v146
	v_mov_b32_e32 v4, v148
	s_barrier
	s_and_saveexec_b64 s[4:5], vcc
	s_cbranch_execz .LBB0_2325
	v_cmp_eq_u32_e32 vcc, 0, v148
	v_mov_b32_e32 v2, v146
	v_mov_b32_e32 v4, v148
	s_waitcnt vmcnt(0) expcnt(0) lgkmcnt(0)
	s_and_saveexec_b64 s[6:7], vcc
	s_cbranch_execz .LBB0_2292
	s_load_dwordx2 s[12:13], s[0:1], 0x468
	s_load_dword s3, s[0:1], 0x470
	s_add_u32 s8, s20, 0x1000
	s_addc_u32 s9, s21, 0
	s_add_u32 s10, s20, 0x1100
	s_waitcnt lgkmcnt(0)
	s_mul_i32 s11, s13, s12
	s_mul_i32 s3, s11, s3
	s_addc_u32 s11, s21, 0
	s_add_u32 s12, s20, 0x1200
	s_addc_u32 s13, s21, 0
	s_add_u32 s14, s20, 0x1300
	s_addc_u32 s15, s21, 0
	s_mov_b32 s26, 1
	v_mov_b32_e32 v18, 0
	s_branch .LBB0_2280

FUSE20_SPIN:
	global_load_dword v4, v2, s[20:21] sc1
	s_waitcnt vmcnt(0)
	v_readfirstlane_b32 s69, v4
	s_cmp_ge_u32 s69, 48
	s_cbranch_scc1 FUSE20_GOT
	s_add_i32 s74, s74, 1
	s_cmp_gt_u32 s74, 0x20000
	s_cbranch_scc1 FUSE20_GOT
	s_sleep 1
	s_branch FUSE20_SPIN
